# back-edge rotation (guide 7.11) on the fp8 attention loop and five GEMM K-loops: loop-back barrier becomes the loop head, counter/exit test parked in front of it; on top of v75
# baseline (speedup 1.0000x reference)
.LBB0_182:
	s_ashr_i32 s97, s96, 31
	s_lshl_b64 s[8:9], s[96:97], 18
	s_add_u32 s90, s76, s8
	s_addc_u32 s91, s77, s9
	s_ashr_i32 s93, s92, 31
	s_lshl_b64 s[8:9], s[92:93], 18
	s_add_u32 s42, s81, s8
	s_addc_u32 s43, s80, s9
	s_add_u32 s8, s10, 0x100
	s_addc_u32 s9, s11, 0
	s_add_u32 s12, s10, 0x180
	ds_read_b128 v[2:5], v178
	ds_read_b128 v[6:9], v178 offset:1024
	s_waitcnt vmcnt(0)
	ds_read_b128 v[10:13], v178 offset:2048
	ds_read_b128 v[14:17], v178 offset:3072
	ds_read_b128 v[18:21], v179
	ds_read_b128 v[22:25], v179 offset:1024
	ds_read_b128 v[26:29], v179 offset:2048
	ds_read_b128 v[30:33], v179 offset:3072
	s_addc_u32 s13, s11, 0
	s_and_b64 s[14:15], s[40:41], exec
	s_cselect_b32 s5, s91, s11
	s_cselect_b32 s16, s90, s10
	s_add_u32 s14, s6, 0x100
	s_addc_u32 s15, s7, 0
	s_and_b64 s[18:19], s[40:41], exec
	s_cselect_b32 s17, s43, s7
	s_cselect_b32 s18, s42, s6
	ds_read_b128 v[34:37], v180
	ds_read_b128 v[38:41], v180 offset:1024
	ds_read_b128 v[42:45], v180 offset:2048
	ds_read_b128 v[46:49], v180 offset:3072
	ds_read_b128 v[50:53], v180 offset:4096
	ds_read_b128 v[54:57], v180 offset:5120
	ds_read_b128 v[58:61], v180 offset:6144
	ds_read_b128 v[62:65], v180 offset:7168
	s_add_u32 s20, s10, 0x20080
	s_addc_u32 s21, s11, 0
	s_mov_b32 s19, m0
	s_mov_b32 m0, s37
	s_nop 0
	global_load_lds_dwordx4 v1, s[20:21]
	s_mov_b32 m0, s19
	s_nop 0
	s_mov_b32 s19, m0
	s_mov_b32 m0, s50
	s_nop 0
	global_load_lds_dwordx4 v174, s[20:21]
	s_mov_b32 m0, s19
	s_waitcnt vmcnt(8)
	s_waitcnt lgkmcnt(0)
	s_barrier
	s_setprio 1
	s_waitcnt lgkmcnt(6)
	v_mfma_f32_16x16x128_f8f6f4 v[154:157], v[2:9], v[34:41], 0
	v_mfma_f32_16x16x128_f8f6f4 v[146:149], v[10:17], v[34:41], 0
	s_waitcnt lgkmcnt(4)
	v_mfma_f32_16x16x128_f8f6f4 v[138:141], v[2:9], v[42:49], 0
	v_mfma_f32_16x16x128_f8f6f4 v[130:133], v[10:17], v[42:49], 0
	s_waitcnt lgkmcnt(2)
	v_mfma_f32_16x16x128_f8f6f4 v[122:125], v[2:9], v[50:57], 0
	v_mfma_f32_16x16x128_f8f6f4 v[114:117], v[10:17], v[50:57], 0
	s_waitcnt lgkmcnt(0)
	v_mfma_f32_16x16x128_f8f6f4 v[106:109], v[2:9], v[58:65], 0
	v_mfma_f32_16x16x128_f8f6f4 v[98:101], v[10:17], v[58:65], 0
	s_setprio 0
	s_setprio 1
	v_mfma_f32_16x16x128_f8f6f4 v[158:161], v[18:25], v[34:41], 0
	v_mfma_f32_16x16x128_f8f6f4 v[150:153], v[26:33], v[34:41], 0
	v_mfma_f32_16x16x128_f8f6f4 v[142:145], v[18:25], v[42:49], 0
	v_mfma_f32_16x16x128_f8f6f4 v[134:137], v[26:33], v[42:49], 0
	v_mfma_f32_16x16x128_f8f6f4 v[126:129], v[18:25], v[50:57], 0
	v_mfma_f32_16x16x128_f8f6f4 v[118:121], v[26:33], v[50:57], 0
	v_mfma_f32_16x16x128_f8f6f4 v[110:113], v[18:25], v[58:65], 0
	v_mfma_f32_16x16x128_f8f6f4 v[102:105], v[26:33], v[58:65], 0
	s_setprio 0
	s_barrier
	ds_read_b128 v[164:167], v180 offset:16384
	ds_read_b128 v[168:171], v180 offset:17408
	ds_read_b128 v[186:189], v180 offset:18432
	ds_read_b128 v[190:193], v180 offset:19456
	ds_read_b128 v[194:197], v180 offset:20480
	ds_read_b128 v[198:201], v180 offset:21504
	ds_read_b128 v[202:205], v180 offset:22528
	ds_read_b128 v[206:209], v180 offset:23552
	s_mov_b32 s19, m0
	s_mov_b32 m0, s69
	s_nop 0
	global_load_lds_dwordx4 v173, s[14:15]
	s_mov_b32 m0, s19
	s_nop 0
	s_mov_b32 s19, m0
	s_mov_b32 m0, s85
	s_nop 0
	global_load_lds_dwordx4 v175, s[14:15]
	s_mov_b32 m0, s19
	s_add_u32 s14, s6, 0x20100
	s_addc_u32 s15, s7, 0
	s_mov_b32 s19, m0
	s_mov_b32 m0, s0
	s_nop 0
	global_load_lds_dwordx4 v173, s[14:15]
	s_mov_b32 m0, s19
	s_nop 0
	s_mov_b32 s19, m0
	s_mov_b32 m0, s1
	s_nop 0
	global_load_lds_dwordx4 v175, s[14:15]
	s_mov_b32 m0, s19
	s_mov_b32 s14, m0
	s_mov_b32 m0, s57
	s_nop 0
	global_load_lds_dwordx4 v1, s[8:9]
	s_mov_b32 m0, s14
	s_nop 0
	s_mov_b32 s14, m0
	s_mov_b32 m0, s46
	s_nop 0
	global_load_lds_dwordx4 v174, s[8:9]
	s_mov_b32 m0, s14
	s_waitcnt vmcnt(8)
	s_waitcnt lgkmcnt(0)
	s_barrier
	s_setprio 1
	s_waitcnt lgkmcnt(6)
	v_mfma_f32_16x16x128_f8f6f4 v[90:93], v[2:9], v[164:171], 0
	v_mfma_f32_16x16x128_f8f6f4 v[82:85], v[10:17], v[164:171], 0
	s_waitcnt lgkmcnt(4)
	v_mfma_f32_16x16x128_f8f6f4 v[74:77], v[2:9], v[186:193], 0
	v_mfma_f32_16x16x128_f8f6f4 v[66:69], v[10:17], v[186:193], 0
	s_waitcnt lgkmcnt(2)
	v_mfma_f32_16x16x128_f8f6f4 v[58:61], v[2:9], v[194:201], 0
	v_mfma_f32_16x16x128_f8f6f4 v[50:53], v[10:17], v[194:201], 0
	s_waitcnt lgkmcnt(0)
	v_mfma_f32_16x16x128_f8f6f4 v[42:45], v[2:9], v[202:209], 0
	v_mfma_f32_16x16x128_f8f6f4 v[34:37], v[10:17], v[202:209], 0
	s_setprio 0
	s_setprio 1
	v_mfma_f32_16x16x128_f8f6f4 v[94:97], v[18:25], v[164:171], 0
	v_mfma_f32_16x16x128_f8f6f4 v[86:89], v[26:33], v[164:171], 0
	v_mfma_f32_16x16x128_f8f6f4 v[78:81], v[18:25], v[186:193], 0
	v_mfma_f32_16x16x128_f8f6f4 v[70:73], v[26:33], v[186:193], 0
	v_mfma_f32_16x16x128_f8f6f4 v[62:65], v[18:25], v[194:201], 0
	v_mfma_f32_16x16x128_f8f6f4 v[54:57], v[26:33], v[194:201], 0
	v_mfma_f32_16x16x128_f8f6f4 v[46:49], v[18:25], v[202:209], 0
	v_mfma_f32_16x16x128_f8f6f4 v[38:41], v[26:33], v[202:209], 0
	s_setprio 0
	s_barrier
	ds_read_b128 v[26:29], v181
	ds_read_b128 v[30:33], v181 offset:1024
	ds_read_b128 v[18:21], v181 offset:2048
	ds_read_b128 v[22:25], v181 offset:3072
	ds_read_b128 v[10:13], v182
	ds_read_b128 v[14:17], v182 offset:1024
	ds_read_b128 v[2:5], v182 offset:2048
	ds_read_b128 v[6:9], v182 offset:3072
	ds_read_b128 v[164:167], v180 offset:32768
	ds_read_b128 v[168:171], v180 offset:33792
	ds_read_b128 v[186:189], v180 offset:34816
	ds_read_b128 v[190:193], v180 offset:35840
	ds_read_b128 v[194:197], v180 offset:36864
	ds_read_b128 v[198:201], v180 offset:37888
	ds_read_b128 v[202:205], v180 offset:38912
	ds_read_b128 v[206:209], v180 offset:39936
	s_add_u32 s10, s10, 0x20100
	s_addc_u32 s11, s11, 0
	s_mov_b32 s14, m0
	s_mov_b32 m0, s47
	s_nop 0
	global_load_lds_dwordx4 v1, s[10:11]
	s_mov_b32 m0, s14
	s_nop 0
	s_mov_b32 s14, m0
	s_mov_b32 m0, s3
	s_nop 0
	global_load_lds_dwordx4 v174, s[10:11]
	s_mov_b32 m0, s14
	s_waitcnt vmcnt(8)
	s_waitcnt lgkmcnt(0)
	s_barrier
	s_setprio 1
	s_waitcnt lgkmcnt(6)
	v_mfma_f32_16x16x128_f8f6f4 v[154:157], v[26:33], v[164:171], v[154:157]
	v_mfma_f32_16x16x128_f8f6f4 v[146:149], v[18:25], v[164:171], v[146:149]
	s_waitcnt lgkmcnt(4)
	v_mfma_f32_16x16x128_f8f6f4 v[138:141], v[26:33], v[186:193], v[138:141]
	v_mfma_f32_16x16x128_f8f6f4 v[130:133], v[18:25], v[186:193], v[130:133]
	s_waitcnt lgkmcnt(2)
	v_mfma_f32_16x16x128_f8f6f4 v[122:125], v[26:33], v[194:201], v[122:125]
	v_mfma_f32_16x16x128_f8f6f4 v[114:117], v[18:25], v[194:201], v[114:117]
	s_waitcnt lgkmcnt(0)
	v_mfma_f32_16x16x128_f8f6f4 v[106:109], v[26:33], v[202:209], v[106:109]
	v_mfma_f32_16x16x128_f8f6f4 v[98:101], v[18:25], v[202:209], v[98:101]
	s_setprio 0
	s_setprio 1
	v_mfma_f32_16x16x128_f8f6f4 v[158:161], v[10:17], v[164:171], v[158:161]
	v_mfma_f32_16x16x128_f8f6f4 v[150:153], v[2:9], v[164:171], v[150:153]
	v_mfma_f32_16x16x128_f8f6f4 v[142:145], v[10:17], v[186:193], v[142:145]
	v_mfma_f32_16x16x128_f8f6f4 v[134:137], v[2:9], v[186:193], v[134:137]
	v_mfma_f32_16x16x128_f8f6f4 v[126:129], v[10:17], v[194:201], v[126:129]
	v_mfma_f32_16x16x128_f8f6f4 v[118:121], v[2:9], v[194:201], v[118:121]
	v_mfma_f32_16x16x128_f8f6f4 v[110:113], v[10:17], v[202:209], v[110:113]
	v_mfma_f32_16x16x128_f8f6f4 v[102:105], v[2:9], v[202:209], v[102:105]
	s_setprio 0
	s_barrier
	ds_read_b128 v[164:167], v180 offset:49152
	ds_read_b128 v[168:171], v180 offset:50176
	ds_read_b128 v[186:189], v180 offset:51200
	ds_read_b128 v[190:193], v180 offset:52224
	ds_read_b128 v[194:197], v180 offset:53248
	ds_read_b128 v[198:201], v180 offset:54272
	ds_read_b128 v[202:205], v180 offset:55296
	ds_read_b128 v[206:209], v180 offset:56320
	s_add_u32 s10, s6, 0x180
	s_addc_u32 s11, s7, 0
	s_mov_b32 s14, m0
	s_mov_b32 m0, s2
	s_nop 0
	global_load_lds_dwordx4 v173, s[10:11]
	s_mov_b32 m0, s14
	s_nop 0
	s_mov_b32 s14, m0
	s_mov_b32 m0, s44
	s_nop 0
	global_load_lds_dwordx4 v175, s[10:11]
	s_mov_b32 m0, s14
	s_add_u32 s10, s6, 0x20180
	s_addc_u32 s11, s7, 0
	s_mov_b32 s14, m0
	s_mov_b32 m0, s59
	s_nop 0
	global_load_lds_dwordx4 v173, s[10:11]
	s_mov_b32 m0, s14
	s_nop 0
	s_mov_b32 s14, m0
	s_mov_b32 m0, s36
	s_nop 0
	global_load_lds_dwordx4 v175, s[10:11]
	s_mov_b32 m0, s14
	s_mov_b32 s10, m0
	s_mov_b32 m0, s45
	s_nop 0
	global_load_lds_dwordx4 v1, s[12:13]
	s_mov_b32 m0, s10
	s_nop 0
	s_mov_b32 s10, m0
	s_mov_b32 m0, s58
	s_nop 0
	global_load_lds_dwordx4 v174, s[12:13]
	s_mov_b32 m0, s10
	s_waitcnt vmcnt(8)
	s_waitcnt lgkmcnt(0)
	s_barrier
	s_setprio 1
	s_waitcnt lgkmcnt(6)
	v_mfma_f32_16x16x128_f8f6f4 v[90:93], v[26:33], v[164:171], v[90:93]
	v_mfma_f32_16x16x128_f8f6f4 v[82:85], v[18:25], v[164:171], v[82:85]
	s_waitcnt lgkmcnt(4)
	v_mfma_f32_16x16x128_f8f6f4 v[74:77], v[26:33], v[186:193], v[74:77]
	v_mfma_f32_16x16x128_f8f6f4 v[66:69], v[18:25], v[186:193], v[66:69]
	s_waitcnt lgkmcnt(2)
	v_mfma_f32_16x16x128_f8f6f4 v[58:61], v[26:33], v[194:201], v[58:61]
	v_mfma_f32_16x16x128_f8f6f4 v[50:53], v[18:25], v[194:201], v[50:53]
	s_waitcnt lgkmcnt(0)
	v_mfma_f32_16x16x128_f8f6f4 v[42:45], v[26:33], v[202:209], v[42:45]
	v_mfma_f32_16x16x128_f8f6f4 v[34:37], v[18:25], v[202:209], v[34:37]
	s_setprio 0
	s_setprio 1
	v_mfma_f32_16x16x128_f8f6f4 v[94:97], v[10:17], v[164:171], v[94:97]
	v_mfma_f32_16x16x128_f8f6f4 v[86:89], v[2:9], v[164:171], v[86:89]
	v_mfma_f32_16x16x128_f8f6f4 v[78:81], v[10:17], v[186:193], v[78:81]
	v_mfma_f32_16x16x128_f8f6f4 v[70:73], v[2:9], v[186:193], v[70:73]
	v_mfma_f32_16x16x128_f8f6f4 v[62:65], v[10:17], v[194:201], v[62:65]
	v_mfma_f32_16x16x128_f8f6f4 v[54:57], v[2:9], v[194:201], v[54:57]
	v_mfma_f32_16x16x128_f8f6f4 v[46:49], v[10:17], v[202:209], v[46:49]
	v_mfma_f32_16x16x128_f8f6f4 v[38:41], v[2:9], v[202:209], v[38:41]
	s_setprio 0
	s_add_u32 s19, s6, 0x200
	s_addc_u32 s20, s7, 0
	s_mov_b32 s21, 0
.LBB0_183:
	s_barrier
	ds_read_b128 v[2:5], v178
	ds_read_b128 v[6:9], v178 offset:1024
	ds_read_b128 v[10:13], v178 offset:2048
	ds_read_b128 v[14:17], v178 offset:3072
	ds_read_b128 v[18:21], v179
	ds_read_b128 v[22:25], v179 offset:1024
	ds_read_b128 v[26:29], v179 offset:2048
	ds_read_b128 v[30:33], v179 offset:3072
	s_add_u32 s6, s8, 0x100
	s_addc_u32 s7, s9, 0
	s_cmp_eq_u32 s21, 4
	s_cselect_b32 s14, s16, s6
	s_cselect_b32 s15, s5, s7
	s_cselect_b32 s12, s18, s19
	s_cselect_b32 s13, s17, s20
	s_add_u32 s10, s14, 0x80
	s_addc_u32 s11, s15, 0
	ds_read_b128 v[164:167], v180
	ds_read_b128 v[168:171], v180 offset:1024
	ds_read_b128 v[186:189], v180 offset:2048
	ds_read_b128 v[190:193], v180 offset:3072
	ds_read_b128 v[194:197], v180 offset:4096
	ds_read_b128 v[198:201], v180 offset:5120
	ds_read_b128 v[202:205], v180 offset:6144
	ds_read_b128 v[206:209], v180 offset:7168
	s_add_u32 s8, s8, 0x20080
	s_addc_u32 s9, s9, 0
	s_mov_b32 s22, m0
	s_mov_b32 m0, s37
	s_nop 0
	global_load_lds_dwordx4 v1, s[8:9]
	s_mov_b32 m0, s22
	s_nop 0
	s_mov_b32 s22, m0
	s_mov_b32 m0, s50
	s_nop 0
	global_load_lds_dwordx4 v174, s[8:9]
	s_mov_b32 m0, s22
	s_waitcnt vmcnt(8)
	s_waitcnt lgkmcnt(0)
	s_barrier
	s_setprio 1
	s_waitcnt lgkmcnt(6)
	v_mfma_f32_16x16x128_f8f6f4 v[154:157], v[2:9], v[164:171], v[154:157]
	v_mfma_f32_16x16x128_f8f6f4 v[146:149], v[10:17], v[164:171], v[146:149]
	s_waitcnt lgkmcnt(4)
	v_mfma_f32_16x16x128_f8f6f4 v[138:141], v[2:9], v[186:193], v[138:141]
	v_mfma_f32_16x16x128_f8f6f4 v[130:133], v[10:17], v[186:193], v[130:133]
	s_waitcnt lgkmcnt(2)
	v_mfma_f32_16x16x128_f8f6f4 v[122:125], v[2:9], v[194:201], v[122:125]
	v_mfma_f32_16x16x128_f8f6f4 v[114:117], v[10:17], v[194:201], v[114:117]
	s_waitcnt lgkmcnt(0)
	v_mfma_f32_16x16x128_f8f6f4 v[106:109], v[2:9], v[202:209], v[106:109]
	v_mfma_f32_16x16x128_f8f6f4 v[98:101], v[10:17], v[202:209], v[98:101]
	s_setprio 0
	s_setprio 1
	v_mfma_f32_16x16x128_f8f6f4 v[158:161], v[18:25], v[164:171], v[158:161]
	v_mfma_f32_16x16x128_f8f6f4 v[150:153], v[26:33], v[164:171], v[150:153]
	v_mfma_f32_16x16x128_f8f6f4 v[142:145], v[18:25], v[186:193], v[142:145]
	v_mfma_f32_16x16x128_f8f6f4 v[134:137], v[26:33], v[186:193], v[134:137]
	v_mfma_f32_16x16x128_f8f6f4 v[126:129], v[18:25], v[194:201], v[126:129]
	v_mfma_f32_16x16x128_f8f6f4 v[118:121], v[26:33], v[194:201], v[118:121]
	v_mfma_f32_16x16x128_f8f6f4 v[110:113], v[18:25], v[202:209], v[110:113]
	v_mfma_f32_16x16x128_f8f6f4 v[102:105], v[26:33], v[202:209], v[102:105]
	s_setprio 0
	s_barrier
	ds_read_b128 v[164:167], v180 offset:16384
	ds_read_b128 v[168:171], v180 offset:17408
	ds_read_b128 v[186:189], v180 offset:18432
	ds_read_b128 v[190:193], v180 offset:19456
	ds_read_b128 v[194:197], v180 offset:20480
	ds_read_b128 v[198:201], v180 offset:21504
	ds_read_b128 v[202:205], v180 offset:22528
	ds_read_b128 v[206:209], v180 offset:23552
	s_mov_b32 s8, m0
	s_mov_b32 m0, s69
	s_nop 0
	global_load_lds_dwordx4 v173, s[12:13]
	s_mov_b32 m0, s8
	s_nop 0
	s_mov_b32 s8, m0
	s_mov_b32 m0, s85
	s_nop 0
	global_load_lds_dwordx4 v175, s[12:13]
	s_mov_b32 m0, s8
	s_add_u32 s8, s12, 0x20000
	s_addc_u32 s9, s13, 0
	s_mov_b32 s22, m0
	s_mov_b32 m0, s0
	s_nop 0
	global_load_lds_dwordx4 v173, s[8:9]
	s_mov_b32 m0, s22
	s_nop 0
	s_mov_b32 s22, m0
	s_mov_b32 m0, s1
	s_nop 0
	global_load_lds_dwordx4 v175, s[8:9]
	s_mov_b32 m0, s22
	s_mov_b32 s8, m0
	s_mov_b32 m0, s57
	s_nop 0
	global_load_lds_dwordx4 v1, s[14:15]
	s_mov_b32 m0, s8
	s_nop 0
	s_mov_b32 s8, m0
	s_mov_b32 m0, s46
	s_nop 0
	global_load_lds_dwordx4 v174, s[14:15]
	s_mov_b32 m0, s8
	s_waitcnt vmcnt(8)
	s_waitcnt lgkmcnt(0)
	s_barrier
	s_setprio 1
	s_waitcnt lgkmcnt(6)
	v_mfma_f32_16x16x128_f8f6f4 v[90:93], v[2:9], v[164:171], v[90:93]
	v_mfma_f32_16x16x128_f8f6f4 v[82:85], v[10:17], v[164:171], v[82:85]
	s_waitcnt lgkmcnt(4)
	v_mfma_f32_16x16x128_f8f6f4 v[74:77], v[2:9], v[186:193], v[74:77]
	v_mfma_f32_16x16x128_f8f6f4 v[66:69], v[10:17], v[186:193], v[66:69]
	s_waitcnt lgkmcnt(2)
	v_mfma_f32_16x16x128_f8f6f4 v[58:61], v[2:9], v[194:201], v[58:61]
	v_mfma_f32_16x16x128_f8f6f4 v[50:53], v[10:17], v[194:201], v[50:53]
	s_waitcnt lgkmcnt(0)
	v_mfma_f32_16x16x128_f8f6f4 v[42:45], v[2:9], v[202:209], v[42:45]
	v_mfma_f32_16x16x128_f8f6f4 v[34:37], v[10:17], v[202:209], v[34:37]
	s_setprio 0
	s_setprio 1
	v_mfma_f32_16x16x128_f8f6f4 v[94:97], v[18:25], v[164:171], v[94:97]
	v_mfma_f32_16x16x128_f8f6f4 v[86:89], v[26:33], v[164:171], v[86:89]
	v_mfma_f32_16x16x128_f8f6f4 v[78:81], v[18:25], v[186:193], v[78:81]
	v_mfma_f32_16x16x128_f8f6f4 v[70:73], v[26:33], v[186:193], v[70:73]
	v_mfma_f32_16x16x128_f8f6f4 v[62:65], v[18:25], v[194:201], v[62:65]
	v_mfma_f32_16x16x128_f8f6f4 v[54:57], v[26:33], v[194:201], v[54:57]
	v_mfma_f32_16x16x128_f8f6f4 v[46:49], v[18:25], v[202:209], v[46:49]
	v_mfma_f32_16x16x128_f8f6f4 v[38:41], v[26:33], v[202:209], v[38:41]
	s_setprio 0
	s_barrier
	ds_read_b128 v[26:29], v181
	ds_read_b128 v[30:33], v181 offset:1024
	ds_read_b128 v[18:21], v181 offset:2048
	ds_read_b128 v[22:25], v181 offset:3072
	ds_read_b128 v[10:13], v182
	ds_read_b128 v[14:17], v182 offset:1024
	ds_read_b128 v[2:5], v182 offset:2048
	ds_read_b128 v[6:9], v182 offset:3072
	ds_read_b128 v[164:167], v180 offset:32768
	ds_read_b128 v[168:171], v180 offset:33792
	ds_read_b128 v[186:189], v180 offset:34816
	ds_read_b128 v[190:193], v180 offset:35840
	ds_read_b128 v[194:197], v180 offset:36864
	ds_read_b128 v[198:201], v180 offset:37888
	ds_read_b128 v[202:205], v180 offset:38912
	ds_read_b128 v[206:209], v180 offset:39936
	s_add_u32 s8, s14, 0x20000
	s_addc_u32 s9, s15, 0
	s_mov_b32 s14, m0
	s_mov_b32 m0, s47
	s_nop 0
	global_load_lds_dwordx4 v1, s[8:9]
	s_mov_b32 m0, s14
	s_nop 0
	s_mov_b32 s14, m0
	s_mov_b32 m0, s3
	s_nop 0
	global_load_lds_dwordx4 v174, s[8:9]
	s_mov_b32 m0, s14
	s_waitcnt vmcnt(8)
	s_waitcnt lgkmcnt(0)
	s_barrier
	s_setprio 1
	s_waitcnt lgkmcnt(6)
	v_mfma_f32_16x16x128_f8f6f4 v[154:157], v[26:33], v[164:171], v[154:157]
	v_mfma_f32_16x16x128_f8f6f4 v[146:149], v[18:25], v[164:171], v[146:149]
	s_waitcnt lgkmcnt(4)
	v_mfma_f32_16x16x128_f8f6f4 v[138:141], v[26:33], v[186:193], v[138:141]
	v_mfma_f32_16x16x128_f8f6f4 v[130:133], v[18:25], v[186:193], v[130:133]
	s_waitcnt lgkmcnt(2)
	v_mfma_f32_16x16x128_f8f6f4 v[122:125], v[26:33], v[194:201], v[122:125]
	v_mfma_f32_16x16x128_f8f6f4 v[114:117], v[18:25], v[194:201], v[114:117]
	s_waitcnt lgkmcnt(0)
	v_mfma_f32_16x16x128_f8f6f4 v[106:109], v[26:33], v[202:209], v[106:109]
	v_mfma_f32_16x16x128_f8f6f4 v[98:101], v[18:25], v[202:209], v[98:101]
	s_setprio 0
	s_setprio 1
	v_mfma_f32_16x16x128_f8f6f4 v[158:161], v[10:17], v[164:171], v[158:161]
	v_mfma_f32_16x16x128_f8f6f4 v[150:153], v[2:9], v[164:171], v[150:153]
	v_mfma_f32_16x16x128_f8f6f4 v[142:145], v[10:17], v[186:193], v[142:145]
	v_mfma_f32_16x16x128_f8f6f4 v[134:137], v[2:9], v[186:193], v[134:137]
	v_mfma_f32_16x16x128_f8f6f4 v[126:129], v[10:17], v[194:201], v[126:129]
	v_mfma_f32_16x16x128_f8f6f4 v[118:121], v[2:9], v[194:201], v[118:121]
	v_mfma_f32_16x16x128_f8f6f4 v[110:113], v[10:17], v[202:209], v[110:113]
	v_mfma_f32_16x16x128_f8f6f4 v[102:105], v[2:9], v[202:209], v[102:105]
	s_setprio 0
	s_barrier
	ds_read_b128 v[164:167], v180 offset:49152
	ds_read_b128 v[168:171], v180 offset:50176
	ds_read_b128 v[186:189], v180 offset:51200
	ds_read_b128 v[190:193], v180 offset:52224
	ds_read_b128 v[194:197], v180 offset:53248
	ds_read_b128 v[198:201], v180 offset:54272
	ds_read_b128 v[202:205], v180 offset:55296
	ds_read_b128 v[206:209], v180 offset:56320
	s_add_u32 s8, s12, 0x80
	s_addc_u32 s9, s13, 0
	s_mov_b32 s14, m0
	s_mov_b32 m0, s2
	s_nop 0
	global_load_lds_dwordx4 v173, s[8:9]
	s_mov_b32 m0, s14
	s_nop 0
	s_mov_b32 s14, m0
	s_mov_b32 m0, s44
	s_nop 0
	global_load_lds_dwordx4 v175, s[8:9]
	s_mov_b32 m0, s14
	s_add_u32 s8, s12, 0x20080
	s_addc_u32 s9, s13, 0
	s_mov_b32 s12, m0
	s_mov_b32 m0, s59
	s_nop 0
	global_load_lds_dwordx4 v173, s[8:9]
	s_mov_b32 m0, s12
	s_nop 0
	s_mov_b32 s12, m0
	s_mov_b32 m0, s36
	s_nop 0
	global_load_lds_dwordx4 v175, s[8:9]
	s_mov_b32 m0, s12
	s_mov_b32 s8, m0
	s_mov_b32 m0, s45
	s_nop 0
	global_load_lds_dwordx4 v1, s[10:11]
	s_mov_b32 m0, s8
	s_nop 0
	s_mov_b32 s8, m0
	s_mov_b32 m0, s58
	s_nop 0
	global_load_lds_dwordx4 v174, s[10:11]
	s_mov_b32 m0, s8
	s_waitcnt vmcnt(8)
	s_waitcnt lgkmcnt(0)
	s_barrier
	s_setprio 1
	s_waitcnt lgkmcnt(6)
	v_mfma_f32_16x16x128_f8f6f4 v[90:93], v[26:33], v[164:171], v[90:93]
	v_mfma_f32_16x16x128_f8f6f4 v[82:85], v[18:25], v[164:171], v[82:85]
	s_waitcnt lgkmcnt(4)
	v_mfma_f32_16x16x128_f8f6f4 v[74:77], v[26:33], v[186:193], v[74:77]
	v_mfma_f32_16x16x128_f8f6f4 v[66:69], v[18:25], v[186:193], v[66:69]
	s_waitcnt lgkmcnt(2)
	v_mfma_f32_16x16x128_f8f6f4 v[58:61], v[26:33], v[194:201], v[58:61]
	v_mfma_f32_16x16x128_f8f6f4 v[50:53], v[18:25], v[194:201], v[50:53]
	s_waitcnt lgkmcnt(0)
	v_mfma_f32_16x16x128_f8f6f4 v[42:45], v[26:33], v[202:209], v[42:45]
	v_mfma_f32_16x16x128_f8f6f4 v[34:37], v[18:25], v[202:209], v[34:37]
	s_setprio 0
	s_setprio 1
	v_mfma_f32_16x16x128_f8f6f4 v[94:97], v[10:17], v[164:171], v[94:97]
	v_mfma_f32_16x16x128_f8f6f4 v[86:89], v[2:9], v[164:171], v[86:89]
	v_mfma_f32_16x16x128_f8f6f4 v[78:81], v[10:17], v[186:193], v[78:81]
	v_mfma_f32_16x16x128_f8f6f4 v[70:73], v[2:9], v[186:193], v[70:73]
	v_mfma_f32_16x16x128_f8f6f4 v[62:65], v[10:17], v[194:201], v[62:65]
	v_mfma_f32_16x16x128_f8f6f4 v[54:57], v[2:9], v[194:201], v[54:57]
	v_mfma_f32_16x16x128_f8f6f4 v[46:49], v[10:17], v[202:209], v[46:49]
	v_mfma_f32_16x16x128_f8f6f4 v[38:41], v[2:9], v[202:209], v[38:41]
	s_setprio 0
	s_add_i32 s21, s21, 2
	s_add_u32 s19, s19, 0x100
	s_addc_u32 s20, s20, 0
	s_cmp_lt_u32 s21, 6
	s_mov_b64 s[8:9], s[6:7]
	s_cbranch_scc1 .LBB0_183
	s_barrier
	v_readlane_b32 s6, v252, 13
	v_readlane_b32 s7, v252, 14
	s_andn2_b64 vcc, exec, s[6:7]
	s_cbranch_vccnz .LBB0_186
	s_barrier

.LBB0_451:
	s_ashr_i32 s61, s60, 31
	s_lshl_b64 s[8:9], s[60:61], 19
	s_add_u32 s90, s24, s8
	s_addc_u32 s91, s25, s9
	s_ashr_i32 s69, s68, 31
	s_lshl_b64 s[8:9], s[68:69], 19
	v_readlane_b32 s12, v253, 23
	v_readlane_b32 s13, v253, 24
	s_add_u32 s92, s12, s8
	s_addc_u32 s93, s13, s9
	s_add_u32 s8, s10, 0x100
	s_addc_u32 s9, s11, 0
	s_add_u32 s12, s10, 0x180
	ds_read_b128 v[2:5], v171
	ds_read_b128 v[6:9], v171 offset:1024
	s_waitcnt vmcnt(0)
	ds_read_b128 v[10:13], v171 offset:2048
	ds_read_b128 v[14:17], v171 offset:3072
	ds_read_b128 v[18:21], v173
	ds_read_b128 v[22:25], v173 offset:1024
	ds_read_b128 v[26:29], v173 offset:2048
	ds_read_b128 v[30:33], v173 offset:3072
	s_addc_u32 s13, s11, 0
	s_and_b64 s[14:15], s[56:57], exec
	s_cselect_b32 s5, s91, s11
	s_cselect_b32 s16, s90, s10
	s_add_u32 s14, s6, 0x100
	s_addc_u32 s15, s7, 0
	s_and_b64 s[22:23], s[56:57], exec
	s_cselect_b32 s17, s93, s7
	s_cselect_b32 s18, s92, s6
	ds_read_b128 v[34:37], v174
	ds_read_b128 v[38:41], v174 offset:1024
	ds_read_b128 v[42:45], v174 offset:2048
	ds_read_b128 v[46:49], v174 offset:3072
	ds_read_b128 v[50:53], v174 offset:4096
	ds_read_b128 v[54:57], v174 offset:5120
	ds_read_b128 v[58:61], v174 offset:6144
	ds_read_b128 v[62:65], v174 offset:7168
	s_add_u32 s22, s10, 0x40080
	s_addc_u32 s23, s11, 0
	s_mov_b32 s21, m0
	s_mov_b32 m0, s40
	s_nop 0
	global_load_lds_dwordx4 v1, s[22:23]
	s_mov_b32 m0, s21
	s_nop 0
	s_mov_b32 s21, m0
	s_mov_b32 m0, s42
	s_nop 0
	global_load_lds_dwordx4 v167, s[22:23]
	s_mov_b32 m0, s21
	s_waitcnt vmcnt(8)
	s_waitcnt lgkmcnt(0)
	s_barrier
	s_setprio 1
	s_waitcnt lgkmcnt(7)
	v_mfma_f32_16x16x32_bf16 v[66:69], v[2:5], v[34:37], 0
	v_mfma_f32_16x16x32_bf16 v[70:73], v[10:13], v[34:37], 0
	s_waitcnt lgkmcnt(5)
	v_mfma_f32_16x16x32_bf16 v[74:77], v[2:5], v[42:45], 0
	v_mfma_f32_16x16x32_bf16 v[78:81], v[10:13], v[42:45], 0
	s_waitcnt lgkmcnt(3)
	v_mfma_f32_16x16x32_bf16 v[82:85], v[2:5], v[50:53], 0
	v_mfma_f32_16x16x32_bf16 v[86:89], v[10:13], v[50:53], 0
	s_waitcnt lgkmcnt(1)
	v_mfma_f32_16x16x32_bf16 v[90:93], v[2:5], v[58:61], 0
	v_mfma_f32_16x16x32_bf16 v[94:97], v[10:13], v[58:61], 0
	v_mfma_f32_16x16x32_bf16 v[66:69], v[6:9], v[38:41], v[66:69]
	v_mfma_f32_16x16x32_bf16 v[70:73], v[14:17], v[38:41], v[70:73]
	v_mfma_f32_16x16x32_bf16 v[74:77], v[6:9], v[46:49], v[74:77]
	v_mfma_f32_16x16x32_bf16 v[78:81], v[14:17], v[46:49], v[78:81]
	v_mfma_f32_16x16x32_bf16 v[82:85], v[6:9], v[54:57], v[82:85]
	v_mfma_f32_16x16x32_bf16 v[86:89], v[14:17], v[54:57], v[86:89]
	s_waitcnt lgkmcnt(0)
	v_mfma_f32_16x16x32_bf16 v[90:93], v[6:9], v[62:65], v[90:93]
	v_mfma_f32_16x16x32_bf16 v[94:97], v[14:17], v[62:65], v[94:97]
	s_setprio 0
	s_setprio 1
	v_mfma_f32_16x16x32_bf16 v[98:101], v[18:21], v[34:37], 0
	v_mfma_f32_16x16x32_bf16 v[34:37], v[26:29], v[34:37], 0
	v_mfma_f32_16x16x32_bf16 v[102:105], v[22:25], v[38:41], v[98:101]
	v_mfma_f32_16x16x32_bf16 v[34:37], v[30:33], v[38:41], v[34:37]
	v_mfma_f32_16x16x32_bf16 v[38:41], v[18:21], v[42:45], 0
	v_mfma_f32_16x16x32_bf16 v[42:45], v[26:29], v[42:45], 0
	v_mfma_f32_16x16x32_bf16 v[38:41], v[22:25], v[46:49], v[38:41]
	v_mfma_f32_16x16x32_bf16 v[42:45], v[30:33], v[46:49], v[42:45]
	v_mfma_f32_16x16x32_bf16 v[46:49], v[18:21], v[50:53], 0
	v_mfma_f32_16x16x32_bf16 v[50:53], v[26:29], v[50:53], 0
	v_mfma_f32_16x16x32_bf16 v[46:49], v[22:25], v[54:57], v[46:49]
	v_mfma_f32_16x16x32_bf16 v[50:53], v[30:33], v[54:57], v[50:53]
	v_mfma_f32_16x16x32_bf16 v[54:57], v[18:21], v[58:61], 0
	v_mfma_f32_16x16x32_bf16 v[58:61], v[26:29], v[58:61], 0
	v_mfma_f32_16x16x32_bf16 v[54:57], v[22:25], v[62:65], v[54:57]
	v_mfma_f32_16x16x32_bf16 v[58:61], v[30:33], v[62:65], v[58:61]
	s_setprio 0
	s_barrier
	ds_read_b128 v[62:65], v174 offset:16384
	ds_read_b128 v[98:101], v174 offset:17408
	ds_read_b128 v[106:109], v174 offset:18432
	ds_read_b128 v[110:113], v174 offset:19456
	ds_read_b128 v[114:117], v174 offset:20480
	ds_read_b128 v[118:121], v174 offset:21504
	ds_read_b128 v[122:125], v174 offset:22528
	ds_read_b128 v[126:129], v174 offset:23552
	s_mov_b32 s21, m0
	s_mov_b32 m0, s2
	s_nop 0
	global_load_lds_dwordx4 v166, s[14:15]
	s_mov_b32 m0, s21
	s_nop 0
	s_mov_b32 s21, m0
	s_mov_b32 m0, s3
	s_nop 0
	global_load_lds_dwordx4 v168, s[14:15]
	s_mov_b32 m0, s21
	s_add_u32 s14, s6, 0x40100
	s_addc_u32 s15, s7, 0
	s_mov_b32 s21, m0
	s_mov_b32 m0, s34
	s_nop 0
	global_load_lds_dwordx4 v166, s[14:15]
	s_mov_b32 m0, s21
	s_nop 0
	s_mov_b32 s21, m0
	s_mov_b32 m0, s35
	s_nop 0
	global_load_lds_dwordx4 v168, s[14:15]
	s_mov_b32 m0, s21
	s_mov_b32 s14, m0
	s_mov_b32 m0, s1
	s_nop 0
	global_load_lds_dwordx4 v1, s[8:9]
	s_mov_b32 m0, s14
	s_nop 0
	s_mov_b32 s14, m0
	s_mov_b32 m0, s36
	s_nop 0
	global_load_lds_dwordx4 v167, s[8:9]
	s_mov_b32 m0, s14
	s_waitcnt vmcnt(8)
	s_waitcnt lgkmcnt(0)
	s_barrier
	s_setprio 1
	s_waitcnt lgkmcnt(7)
	v_mfma_f32_16x16x32_bf16 v[130:133], v[2:5], v[62:65], 0
	s_waitcnt lgkmcnt(6)
	v_mfma_f32_16x16x32_bf16 v[146:149], v[6:9], v[98:101], v[130:133]
	v_mfma_f32_16x16x32_bf16 v[130:133], v[10:13], v[62:65], 0
	v_mfma_f32_16x16x32_bf16 v[150:153], v[14:17], v[98:101], v[130:133]
	s_waitcnt lgkmcnt(5)
	v_mfma_f32_16x16x32_bf16 v[130:133], v[2:5], v[106:109], 0
	s_waitcnt lgkmcnt(4)
	v_mfma_f32_16x16x32_bf16 v[156:159], v[6:9], v[110:113], v[130:133]
	v_mfma_f32_16x16x32_bf16 v[130:133], v[10:13], v[106:109], 0
	v_mfma_f32_16x16x32_bf16 v[160:163], v[14:17], v[110:113], v[130:133]
	s_waitcnt lgkmcnt(3)
	v_mfma_f32_16x16x32_bf16 v[130:133], v[2:5], v[114:117], 0
	s_waitcnt lgkmcnt(1)
	v_mfma_f32_16x16x32_bf16 v[2:5], v[2:5], v[122:125], 0
	v_mfma_f32_16x16x32_bf16 v[180:183], v[6:9], v[118:121], v[130:133]
	s_waitcnt lgkmcnt(0)
	v_mfma_f32_16x16x32_bf16 v[2:5], v[6:9], v[126:129], v[2:5]
	v_mfma_f32_16x16x32_bf16 v[6:9], v[10:13], v[122:125], 0
	v_mfma_f32_16x16x32_bf16 v[130:133], v[10:13], v[114:117], 0
	v_mfma_f32_16x16x32_bf16 v[6:9], v[14:17], v[126:129], v[6:9]
	v_mfma_f32_16x16x32_bf16 v[184:187], v[14:17], v[118:121], v[130:133]
	s_setprio 0
	s_setprio 1
	v_mfma_f32_16x16x32_bf16 v[10:13], v[18:21], v[62:65], 0
	v_mfma_f32_16x16x32_bf16 v[14:17], v[22:25], v[98:101], v[10:13]
	v_mfma_f32_16x16x32_bf16 v[10:13], v[26:29], v[62:65], 0
	v_mfma_f32_16x16x32_bf16 v[62:65], v[30:33], v[98:101], v[10:13]
	v_mfma_f32_16x16x32_bf16 v[10:13], v[18:21], v[106:109], 0
	v_mfma_f32_16x16x32_bf16 v[188:191], v[22:25], v[110:113], v[10:13]
	v_mfma_f32_16x16x32_bf16 v[10:13], v[26:29], v[106:109], 0
	v_mfma_f32_16x16x32_bf16 v[192:195], v[30:33], v[110:113], v[10:13]
	v_mfma_f32_16x16x32_bf16 v[10:13], v[18:21], v[114:117], 0
	v_mfma_f32_16x16x32_bf16 v[196:199], v[22:25], v[118:121], v[10:13]
	v_mfma_f32_16x16x32_bf16 v[10:13], v[26:29], v[114:117], 0
	v_mfma_f32_16x16x32_bf16 v[200:203], v[30:33], v[118:121], v[10:13]
	v_mfma_f32_16x16x32_bf16 v[10:13], v[18:21], v[122:125], 0
	v_mfma_f32_16x16x32_bf16 v[18:21], v[22:25], v[126:129], v[10:13]
	v_mfma_f32_16x16x32_bf16 v[10:13], v[26:29], v[122:125], 0
	v_mfma_f32_16x16x32_bf16 v[22:25], v[30:33], v[126:129], v[10:13]
	s_setprio 0
	s_barrier
	s_nop 4
	ds_read_b128 v[10:13], v175
	ds_read_b128 v[26:29], v175 offset:1024
	ds_read_b128 v[30:33], v175 offset:2048
	ds_read_b128 v[204:207], v175 offset:3072
	ds_read_b128 v[208:211], v176
	ds_read_b128 v[212:215], v176 offset:1024
	ds_read_b128 v[220:223], v176 offset:2048
	ds_read_b128 v[224:227], v176 offset:3072
	ds_read_b128 v[110:113], v174 offset:32768
	ds_read_b128 v[118:121], v174 offset:33792
	ds_read_b128 v[228:231], v174 offset:34816
	ds_read_b128 v[232:235], v174 offset:35840
	ds_read_b128 v[236:239], v174 offset:36864
	ds_read_b128 v[240:243], v174 offset:37888
	ds_read_b128 v[244:247], v174 offset:38912
	ds_read_b128 v[248:251], v174 offset:39936
	s_add_u32 s10, s10, 0x40100
	s_addc_u32 s11, s11, 0
	s_mov_b32 s14, m0
	s_mov_b32 m0, s44
	s_nop 0
	global_load_lds_dwordx4 v1, s[10:11]
	s_mov_b32 m0, s14
	s_nop 0
	s_mov_b32 s14, m0
	s_mov_b32 m0, s45
	s_nop 0
	global_load_lds_dwordx4 v167, s[10:11]
	s_mov_b32 m0, s14
	s_waitcnt vmcnt(8)
	s_waitcnt lgkmcnt(0)
	s_barrier
	s_setprio 1
	s_waitcnt lgkmcnt(7)
	v_mfma_f32_16x16x32_bf16 v[66:69], v[10:13], v[110:113], v[66:69]
	s_waitcnt lgkmcnt(6)
	v_mfma_f32_16x16x32_bf16 v[138:141], v[26:29], v[118:121], v[66:69]
	v_mfma_f32_16x16x32_bf16 v[66:69], v[30:33], v[110:113], v[70:73]
	v_mfma_f32_16x16x32_bf16 v[130:133], v[204:207], v[118:121], v[66:69]
	s_waitcnt lgkmcnt(5)
	v_mfma_f32_16x16x32_bf16 v[66:69], v[10:13], v[228:231], v[74:77]
	s_waitcnt lgkmcnt(4)
	v_mfma_f32_16x16x32_bf16 v[122:125], v[26:29], v[232:235], v[66:69]
	v_mfma_f32_16x16x32_bf16 v[66:69], v[30:33], v[228:231], v[78:81]
	v_mfma_f32_16x16x32_bf16 v[114:117], v[204:207], v[232:235], v[66:69]
	s_waitcnt lgkmcnt(3)
	v_mfma_f32_16x16x32_bf16 v[66:69], v[10:13], v[236:239], v[82:85]
	s_waitcnt lgkmcnt(2)
	v_mfma_f32_16x16x32_bf16 v[106:109], v[26:29], v[240:243], v[66:69]
	v_mfma_f32_16x16x32_bf16 v[66:69], v[30:33], v[236:239], v[86:89]
	v_mfma_f32_16x16x32_bf16 v[98:101], v[204:207], v[240:243], v[66:69]
	s_waitcnt lgkmcnt(1)
	v_mfma_f32_16x16x32_bf16 v[66:69], v[10:13], v[244:247], v[90:93]
	s_waitcnt lgkmcnt(0)
	v_mfma_f32_16x16x32_bf16 v[90:93], v[26:29], v[248:251], v[66:69]
	v_mfma_f32_16x16x32_bf16 v[66:69], v[30:33], v[244:247], v[94:97]
	v_mfma_f32_16x16x32_bf16 v[82:85], v[204:207], v[248:251], v[66:69]
	s_setprio 0
	s_setprio 1
	v_mfma_f32_16x16x32_bf16 v[34:37], v[220:223], v[110:113], v[34:37]
	v_mfma_f32_16x16x32_bf16 v[134:137], v[224:227], v[118:121], v[34:37]
	v_mfma_f32_16x16x32_bf16 v[34:37], v[208:211], v[228:231], v[38:41]
	v_mfma_f32_16x16x32_bf16 v[66:69], v[208:211], v[110:113], v[102:105]
	v_mfma_f32_16x16x32_bf16 v[126:129], v[212:215], v[232:235], v[34:37]
	v_mfma_f32_16x16x32_bf16 v[34:37], v[220:223], v[228:231], v[42:45]
	v_mfma_f32_16x16x32_bf16 v[142:145], v[212:215], v[118:121], v[66:69]
	v_mfma_f32_16x16x32_bf16 v[118:121], v[224:227], v[232:235], v[34:37]
	v_mfma_f32_16x16x32_bf16 v[34:37], v[208:211], v[236:239], v[46:49]
	v_mfma_f32_16x16x32_bf16 v[110:113], v[212:215], v[240:243], v[34:37]
	v_mfma_f32_16x16x32_bf16 v[34:37], v[220:223], v[236:239], v[50:53]
	v_mfma_f32_16x16x32_bf16 v[102:105], v[224:227], v[240:243], v[34:37]
	v_mfma_f32_16x16x32_bf16 v[34:37], v[208:211], v[244:247], v[54:57]
	v_mfma_f32_16x16x32_bf16 v[94:97], v[212:215], v[248:251], v[34:37]
	v_mfma_f32_16x16x32_bf16 v[34:37], v[220:223], v[244:247], v[58:61]
	v_mfma_f32_16x16x32_bf16 v[86:89], v[224:227], v[248:251], v[34:37]
	s_setprio 0
	s_barrier
	ds_read_b128 v[38:41], v174 offset:49152
	ds_read_b128 v[46:49], v174 offset:50176
	ds_read_b128 v[54:57], v174 offset:51200
	ds_read_b128 v[228:231], v174 offset:52224
	ds_read_b128 v[232:235], v174 offset:53248
	ds_read_b128 v[236:239], v174 offset:54272
	ds_read_b128 v[240:243], v174 offset:55296
	ds_read_b128 v[244:247], v174 offset:56320
	s_add_u32 s10, s6, 0x180
	s_addc_u32 s11, s7, 0
	s_mov_b32 s14, m0
	s_mov_b32 m0, s50
	s_nop 0
	global_load_lds_dwordx4 v166, s[10:11]
	s_mov_b32 m0, s14
	s_nop 0
	s_mov_b32 s14, m0
	s_mov_b32 m0, s51
	s_nop 0
	global_load_lds_dwordx4 v168, s[10:11]
	s_mov_b32 m0, s14
	s_add_u32 s10, s6, 0x40180
	s_addc_u32 s11, s7, 0
	s_mov_b32 s14, m0
	s_mov_b32 m0, s59
	s_nop 0
	global_load_lds_dwordx4 v166, s[10:11]
	s_mov_b32 m0, s14
	s_nop 0
	s_mov_b32 s14, m0
	s_mov_b32 m0, s85
	s_nop 0
	global_load_lds_dwordx4 v168, s[10:11]
	s_mov_b32 m0, s14
	s_mov_b32 s10, m0
	s_mov_b32 m0, s53
	s_nop 0
	global_load_lds_dwordx4 v1, s[12:13]
	s_mov_b32 m0, s10
	s_nop 0
	s_mov_b32 s10, m0
	s_mov_b32 m0, s58
	s_nop 0
	global_load_lds_dwordx4 v167, s[12:13]
	s_mov_b32 m0, s10
	s_waitcnt vmcnt(8)
	s_waitcnt lgkmcnt(0)
	s_barrier
	s_setprio 1
	s_waitcnt lgkmcnt(7)
	v_mfma_f32_16x16x32_bf16 v[34:37], v[10:13], v[38:41], v[146:149]
	s_waitcnt lgkmcnt(6)
	v_mfma_f32_16x16x32_bf16 v[74:77], v[26:29], v[46:49], v[34:37]
	v_mfma_f32_16x16x32_bf16 v[34:37], v[30:33], v[38:41], v[150:153]
	v_mfma_f32_16x16x32_bf16 v[66:69], v[204:207], v[46:49], v[34:37]
	s_waitcnt lgkmcnt(5)
	v_mfma_f32_16x16x32_bf16 v[34:37], v[10:13], v[54:57], v[156:159]
	s_waitcnt lgkmcnt(4)
	v_mfma_f32_16x16x32_bf16 v[58:61], v[26:29], v[228:231], v[34:37]
	v_mfma_f32_16x16x32_bf16 v[34:37], v[30:33], v[54:57], v[160:163]
	v_mfma_f32_16x16x32_bf16 v[50:53], v[204:207], v[228:231], v[34:37]
	s_waitcnt lgkmcnt(3)
	v_mfma_f32_16x16x32_bf16 v[34:37], v[10:13], v[232:235], v[180:183]
	s_waitcnt lgkmcnt(1)
	v_mfma_f32_16x16x32_bf16 v[2:5], v[10:13], v[240:243], v[2:5]
	v_mfma_f32_16x16x32_bf16 v[42:45], v[26:29], v[236:239], v[34:37]
	v_mfma_f32_16x16x32_bf16 v[34:37], v[30:33], v[232:235], v[184:187]
	s_waitcnt lgkmcnt(0)
	v_mfma_f32_16x16x32_bf16 v[10:13], v[26:29], v[244:247], v[2:5]
	v_mfma_f32_16x16x32_bf16 v[2:5], v[30:33], v[240:243], v[6:9]
	v_mfma_f32_16x16x32_bf16 v[34:37], v[204:207], v[236:239], v[34:37]
	v_mfma_f32_16x16x32_bf16 v[2:5], v[204:207], v[244:247], v[2:5]
	s_setprio 0
	s_setprio 1
	v_mfma_f32_16x16x32_bf16 v[6:9], v[208:211], v[38:41], v[14:17]
	v_mfma_f32_16x16x32_bf16 v[78:81], v[212:215], v[46:49], v[6:9]
	v_mfma_f32_16x16x32_bf16 v[6:9], v[220:223], v[38:41], v[62:65]
	v_mfma_f32_16x16x32_bf16 v[70:73], v[224:227], v[46:49], v[6:9]
	v_mfma_f32_16x16x32_bf16 v[6:9], v[208:211], v[54:57], v[188:191]
	v_mfma_f32_16x16x32_bf16 v[62:65], v[212:215], v[228:231], v[6:9]
	v_mfma_f32_16x16x32_bf16 v[6:9], v[220:223], v[54:57], v[192:195]
	v_mfma_f32_16x16x32_bf16 v[54:57], v[224:227], v[228:231], v[6:9]
	v_mfma_f32_16x16x32_bf16 v[6:9], v[208:211], v[232:235], v[196:199]
	v_mfma_f32_16x16x32_bf16 v[46:49], v[212:215], v[236:239], v[6:9]
	v_mfma_f32_16x16x32_bf16 v[6:9], v[220:223], v[232:235], v[200:203]
	v_mfma_f32_16x16x32_bf16 v[38:41], v[224:227], v[236:239], v[6:9]
	v_mfma_f32_16x16x32_bf16 v[6:9], v[208:211], v[240:243], v[18:21]
	v_mfma_f32_16x16x32_bf16 v[14:17], v[212:215], v[244:247], v[6:9]
	v_mfma_f32_16x16x32_bf16 v[6:9], v[220:223], v[240:243], v[22:25]
	v_mfma_f32_16x16x32_bf16 v[6:9], v[224:227], v[244:247], v[6:9]
	s_setprio 0
	s_add_u32 s21, s6, 0x200
	s_addc_u32 s22, s7, 0
	s_mov_b32 s23, 0
.LBB0_452:
	s_barrier
	ds_read_b128 v[18:21], v171
	ds_read_b128 v[22:25], v171 offset:1024
	ds_read_b128 v[26:29], v171 offset:2048
	ds_read_b128 v[30:33], v171 offset:3072
	ds_read_b128 v[146:149], v173
	ds_read_b128 v[150:153], v173 offset:1024
	ds_read_b128 v[156:159], v173 offset:2048
	ds_read_b128 v[160:163], v173 offset:3072
	s_add_u32 s6, s8, 0x100
	s_addc_u32 s7, s9, 0
	s_cmp_eq_u32 s23, 12
	s_cselect_b32 s14, s16, s6
	s_cselect_b32 s15, s5, s7
	s_cselect_b32 s12, s18, s21
	s_cselect_b32 s13, s17, s22
	s_add_u32 s10, s14, 0x80
	s_addc_u32 s11, s15, 0
	ds_read_b128 v[180:183], v174
	ds_read_b128 v[184:187], v174 offset:1024
	ds_read_b128 v[188:191], v174 offset:2048
	ds_read_b128 v[192:195], v174 offset:3072
	ds_read_b128 v[196:199], v174 offset:4096
	ds_read_b128 v[200:203], v174 offset:5120
	ds_read_b128 v[204:207], v174 offset:6144
	ds_read_b128 v[208:211], v174 offset:7168
	s_add_u32 s8, s8, 0x40080
	s_addc_u32 s9, s9, 0
	s_mov_b32 s28, m0
	s_mov_b32 m0, s40
	s_nop 0
	global_load_lds_dwordx4 v1, s[8:9]
	s_mov_b32 m0, s28
	s_nop 0
	s_mov_b32 s28, m0
	s_mov_b32 m0, s42
	s_nop 0
	global_load_lds_dwordx4 v167, s[8:9]
	s_mov_b32 m0, s28
	s_waitcnt vmcnt(8)
	s_waitcnt lgkmcnt(0)
	s_barrier
	s_setprio 1
	s_waitcnt lgkmcnt(7)
	v_mfma_f32_16x16x32_bf16 v[138:141], v[18:21], v[180:183], v[138:141]
	v_mfma_f32_16x16x32_bf16 v[130:133], v[26:29], v[180:183], v[130:133]
	s_waitcnt lgkmcnt(5)
	v_mfma_f32_16x16x32_bf16 v[122:125], v[18:21], v[188:191], v[122:125]
	v_mfma_f32_16x16x32_bf16 v[114:117], v[26:29], v[188:191], v[114:117]
	s_waitcnt lgkmcnt(3)
	v_mfma_f32_16x16x32_bf16 v[106:109], v[18:21], v[196:199], v[106:109]
	v_mfma_f32_16x16x32_bf16 v[98:101], v[26:29], v[196:199], v[98:101]
	s_waitcnt lgkmcnt(1)
	v_mfma_f32_16x16x32_bf16 v[90:93], v[18:21], v[204:207], v[90:93]
	v_mfma_f32_16x16x32_bf16 v[82:85], v[26:29], v[204:207], v[82:85]
	v_mfma_f32_16x16x32_bf16 v[138:141], v[22:25], v[184:187], v[138:141]
	v_mfma_f32_16x16x32_bf16 v[130:133], v[30:33], v[184:187], v[130:133]
	v_mfma_f32_16x16x32_bf16 v[122:125], v[22:25], v[192:195], v[122:125]
	v_mfma_f32_16x16x32_bf16 v[114:117], v[30:33], v[192:195], v[114:117]
	v_mfma_f32_16x16x32_bf16 v[106:109], v[22:25], v[200:203], v[106:109]
	v_mfma_f32_16x16x32_bf16 v[98:101], v[30:33], v[200:203], v[98:101]
	s_waitcnt lgkmcnt(0)
	v_mfma_f32_16x16x32_bf16 v[90:93], v[22:25], v[208:211], v[90:93]
	v_mfma_f32_16x16x32_bf16 v[82:85], v[30:33], v[208:211], v[82:85]
	s_setprio 0
	s_setprio 1
	v_mfma_f32_16x16x32_bf16 v[142:145], v[146:149], v[180:183], v[142:145]
	v_mfma_f32_16x16x32_bf16 v[134:137], v[156:159], v[180:183], v[134:137]
	v_mfma_f32_16x16x32_bf16 v[126:129], v[146:149], v[188:191], v[126:129]
	v_mfma_f32_16x16x32_bf16 v[118:121], v[156:159], v[188:191], v[118:121]
	v_mfma_f32_16x16x32_bf16 v[110:113], v[146:149], v[196:199], v[110:113]
	v_mfma_f32_16x16x32_bf16 v[102:105], v[156:159], v[196:199], v[102:105]
	v_mfma_f32_16x16x32_bf16 v[94:97], v[146:149], v[204:207], v[94:97]
	v_mfma_f32_16x16x32_bf16 v[86:89], v[156:159], v[204:207], v[86:89]
	v_mfma_f32_16x16x32_bf16 v[142:145], v[150:153], v[184:187], v[142:145]
	v_mfma_f32_16x16x32_bf16 v[134:137], v[160:163], v[184:187], v[134:137]
	v_mfma_f32_16x16x32_bf16 v[126:129], v[150:153], v[192:195], v[126:129]
	v_mfma_f32_16x16x32_bf16 v[118:121], v[160:163], v[192:195], v[118:121]
	v_mfma_f32_16x16x32_bf16 v[110:113], v[150:153], v[200:203], v[110:113]
	v_mfma_f32_16x16x32_bf16 v[102:105], v[160:163], v[200:203], v[102:105]
	v_mfma_f32_16x16x32_bf16 v[94:97], v[150:153], v[208:211], v[94:97]
	v_mfma_f32_16x16x32_bf16 v[86:89], v[160:163], v[208:211], v[86:89]
	s_setprio 0
	s_barrier
	ds_read_b128 v[180:183], v174 offset:16384
	ds_read_b128 v[184:187], v174 offset:17408
	ds_read_b128 v[188:191], v174 offset:18432
	ds_read_b128 v[192:195], v174 offset:19456
	ds_read_b128 v[196:199], v174 offset:20480
	ds_read_b128 v[200:203], v174 offset:21504
	ds_read_b128 v[204:207], v174 offset:22528
	ds_read_b128 v[208:211], v174 offset:23552
	s_mov_b32 s8, m0
	s_mov_b32 m0, s2
	s_nop 0
	global_load_lds_dwordx4 v166, s[12:13]
	s_mov_b32 m0, s8
	s_nop 0
	s_mov_b32 s8, m0
	s_mov_b32 m0, s3
	s_nop 0
	global_load_lds_dwordx4 v168, s[12:13]
	s_mov_b32 m0, s8
	s_add_u32 s8, s12, 0x40000
	s_addc_u32 s9, s13, 0
	s_mov_b32 s28, m0
	s_mov_b32 m0, s34
	s_nop 0
	global_load_lds_dwordx4 v166, s[8:9]
	s_mov_b32 m0, s28
	s_nop 0
	s_mov_b32 s28, m0
	s_mov_b32 m0, s35
	s_nop 0
	global_load_lds_dwordx4 v168, s[8:9]
	s_mov_b32 m0, s28
	s_mov_b32 s8, m0
	s_mov_b32 m0, s1
	s_nop 0
	global_load_lds_dwordx4 v1, s[14:15]
	s_mov_b32 m0, s8
	s_nop 0
	s_mov_b32 s8, m0
	s_mov_b32 m0, s36
	s_nop 0
	global_load_lds_dwordx4 v167, s[14:15]
	s_mov_b32 m0, s8
	s_waitcnt vmcnt(8)
	s_waitcnt lgkmcnt(0)
	s_barrier
	s_setprio 1
	s_waitcnt lgkmcnt(7)
	v_mfma_f32_16x16x32_bf16 v[74:77], v[18:21], v[180:183], v[74:77]
	v_mfma_f32_16x16x32_bf16 v[66:69], v[26:29], v[180:183], v[66:69]
	s_waitcnt lgkmcnt(5)
	v_mfma_f32_16x16x32_bf16 v[58:61], v[18:21], v[188:191], v[58:61]
	v_mfma_f32_16x16x32_bf16 v[50:53], v[26:29], v[188:191], v[50:53]
	s_waitcnt lgkmcnt(3)
	v_mfma_f32_16x16x32_bf16 v[42:45], v[18:21], v[196:199], v[42:45]
	v_mfma_f32_16x16x32_bf16 v[34:37], v[26:29], v[196:199], v[34:37]
	s_waitcnt lgkmcnt(1)
	v_mfma_f32_16x16x32_bf16 v[10:13], v[18:21], v[204:207], v[10:13]
	v_mfma_f32_16x16x32_bf16 v[2:5], v[26:29], v[204:207], v[2:5]
	v_mfma_f32_16x16x32_bf16 v[74:77], v[22:25], v[184:187], v[74:77]
	v_mfma_f32_16x16x32_bf16 v[66:69], v[30:33], v[184:187], v[66:69]
	v_mfma_f32_16x16x32_bf16 v[58:61], v[22:25], v[192:195], v[58:61]
	v_mfma_f32_16x16x32_bf16 v[50:53], v[30:33], v[192:195], v[50:53]
	v_mfma_f32_16x16x32_bf16 v[42:45], v[22:25], v[200:203], v[42:45]
	v_mfma_f32_16x16x32_bf16 v[34:37], v[30:33], v[200:203], v[34:37]
	s_waitcnt lgkmcnt(0)
	v_mfma_f32_16x16x32_bf16 v[10:13], v[22:25], v[208:211], v[10:13]
	v_mfma_f32_16x16x32_bf16 v[2:5], v[30:33], v[208:211], v[2:5]
	s_setprio 0
	s_setprio 1
	v_mfma_f32_16x16x32_bf16 v[46:49], v[146:149], v[196:199], v[46:49]
	v_mfma_f32_16x16x32_bf16 v[38:41], v[156:159], v[196:199], v[38:41]
	v_mfma_f32_16x16x32_bf16 v[14:17], v[146:149], v[204:207], v[14:17]
	v_mfma_f32_16x16x32_bf16 v[6:9], v[156:159], v[204:207], v[6:9]
	v_mfma_f32_16x16x32_bf16 v[18:21], v[146:149], v[180:183], v[78:81]
	v_mfma_f32_16x16x32_bf16 v[22:25], v[156:159], v[180:183], v[70:73]
	v_mfma_f32_16x16x32_bf16 v[26:29], v[146:149], v[188:191], v[62:65]
	v_mfma_f32_16x16x32_bf16 v[30:33], v[156:159], v[188:191], v[54:57]
	v_mfma_f32_16x16x32_bf16 v[46:49], v[150:153], v[200:203], v[46:49]
	v_mfma_f32_16x16x32_bf16 v[38:41], v[160:163], v[200:203], v[38:41]
	v_mfma_f32_16x16x32_bf16 v[14:17], v[150:153], v[208:211], v[14:17]
	v_mfma_f32_16x16x32_bf16 v[6:9], v[160:163], v[208:211], v[6:9]
	v_mfma_f32_16x16x32_bf16 v[18:21], v[150:153], v[184:187], v[18:21]
	v_mfma_f32_16x16x32_bf16 v[22:25], v[160:163], v[184:187], v[22:25]
	v_mfma_f32_16x16x32_bf16 v[26:29], v[150:153], v[192:195], v[26:29]
	v_mfma_f32_16x16x32_bf16 v[30:33], v[160:163], v[192:195], v[30:33]
	s_setprio 0
	s_barrier
	ds_read_b128 v[54:57], v175
	ds_read_b128 v[62:65], v175 offset:1024
	ds_read_b128 v[70:73], v175 offset:2048
	ds_read_b128 v[78:81], v175 offset:3072
	ds_read_b128 v[146:149], v176
	ds_read_b128 v[150:153], v176 offset:1024
	ds_read_b128 v[156:159], v176 offset:2048
	ds_read_b128 v[160:163], v176 offset:3072
	ds_read_b128 v[180:183], v174 offset:32768
	ds_read_b128 v[184:187], v174 offset:33792
	ds_read_b128 v[188:191], v174 offset:34816
	ds_read_b128 v[192:195], v174 offset:35840
	ds_read_b128 v[196:199], v174 offset:36864
	ds_read_b128 v[200:203], v174 offset:37888
	ds_read_b128 v[204:207], v174 offset:38912
	ds_read_b128 v[208:211], v174 offset:39936
	s_add_u32 s8, s14, 0x40000
	s_addc_u32 s9, s15, 0
	s_mov_b32 s14, m0
	s_mov_b32 m0, s44
	s_nop 0
	global_load_lds_dwordx4 v1, s[8:9]
	s_mov_b32 m0, s14
	s_nop 0
	s_mov_b32 s14, m0
	s_mov_b32 m0, s45
	s_nop 0
	global_load_lds_dwordx4 v167, s[8:9]
	s_mov_b32 m0, s14
	s_waitcnt vmcnt(8)
	s_waitcnt lgkmcnt(0)
	s_barrier
	s_setprio 1
	s_waitcnt lgkmcnt(7)
	v_mfma_f32_16x16x32_bf16 v[138:141], v[54:57], v[180:183], v[138:141]
	v_mfma_f32_16x16x32_bf16 v[130:133], v[70:73], v[180:183], v[130:133]
	s_waitcnt lgkmcnt(5)
	v_mfma_f32_16x16x32_bf16 v[122:125], v[54:57], v[188:191], v[122:125]
	v_mfma_f32_16x16x32_bf16 v[114:117], v[70:73], v[188:191], v[114:117]
	s_waitcnt lgkmcnt(3)
	v_mfma_f32_16x16x32_bf16 v[106:109], v[54:57], v[196:199], v[106:109]
	v_mfma_f32_16x16x32_bf16 v[98:101], v[70:73], v[196:199], v[98:101]
	s_waitcnt lgkmcnt(1)
	v_mfma_f32_16x16x32_bf16 v[90:93], v[54:57], v[204:207], v[90:93]
	v_mfma_f32_16x16x32_bf16 v[82:85], v[70:73], v[204:207], v[82:85]
	v_mfma_f32_16x16x32_bf16 v[138:141], v[62:65], v[184:187], v[138:141]
	v_mfma_f32_16x16x32_bf16 v[130:133], v[78:81], v[184:187], v[130:133]
	v_mfma_f32_16x16x32_bf16 v[122:125], v[62:65], v[192:195], v[122:125]
	v_mfma_f32_16x16x32_bf16 v[114:117], v[78:81], v[192:195], v[114:117]
	v_mfma_f32_16x16x32_bf16 v[106:109], v[62:65], v[200:203], v[106:109]
	v_mfma_f32_16x16x32_bf16 v[98:101], v[78:81], v[200:203], v[98:101]
	s_waitcnt lgkmcnt(0)
	v_mfma_f32_16x16x32_bf16 v[90:93], v[62:65], v[208:211], v[90:93]
	v_mfma_f32_16x16x32_bf16 v[82:85], v[78:81], v[208:211], v[82:85]
	s_setprio 0
	s_setprio 1
	v_mfma_f32_16x16x32_bf16 v[142:145], v[146:149], v[180:183], v[142:145]
	v_mfma_f32_16x16x32_bf16 v[134:137], v[156:159], v[180:183], v[134:137]
	v_mfma_f32_16x16x32_bf16 v[126:129], v[146:149], v[188:191], v[126:129]
	v_mfma_f32_16x16x32_bf16 v[118:121], v[156:159], v[188:191], v[118:121]
	v_mfma_f32_16x16x32_bf16 v[110:113], v[146:149], v[196:199], v[110:113]
	v_mfma_f32_16x16x32_bf16 v[102:105], v[156:159], v[196:199], v[102:105]
	v_mfma_f32_16x16x32_bf16 v[94:97], v[146:149], v[204:207], v[94:97]
	v_mfma_f32_16x16x32_bf16 v[86:89], v[156:159], v[204:207], v[86:89]
	v_mfma_f32_16x16x32_bf16 v[142:145], v[150:153], v[184:187], v[142:145]
	v_mfma_f32_16x16x32_bf16 v[134:137], v[160:163], v[184:187], v[134:137]
	v_mfma_f32_16x16x32_bf16 v[126:129], v[150:153], v[192:195], v[126:129]
	v_mfma_f32_16x16x32_bf16 v[118:121], v[160:163], v[192:195], v[118:121]
	v_mfma_f32_16x16x32_bf16 v[110:113], v[150:153], v[200:203], v[110:113]
	v_mfma_f32_16x16x32_bf16 v[102:105], v[160:163], v[200:203], v[102:105]
	v_mfma_f32_16x16x32_bf16 v[94:97], v[150:153], v[208:211], v[94:97]
	v_mfma_f32_16x16x32_bf16 v[86:89], v[160:163], v[208:211], v[86:89]
	s_setprio 0
	s_barrier
	ds_read_b128 v[180:183], v174 offset:49152
	ds_read_b128 v[184:187], v174 offset:50176
	ds_read_b128 v[188:191], v174 offset:51200
	ds_read_b128 v[192:195], v174 offset:52224
	ds_read_b128 v[196:199], v174 offset:53248
	ds_read_b128 v[200:203], v174 offset:54272
	ds_read_b128 v[204:207], v174 offset:55296
	ds_read_b128 v[208:211], v174 offset:56320
	s_add_u32 s8, s12, 0x80
	s_addc_u32 s9, s13, 0
	s_mov_b32 s14, m0
	s_mov_b32 m0, s50
	s_nop 0
	global_load_lds_dwordx4 v166, s[8:9]
	s_mov_b32 m0, s14
	s_nop 0
	s_mov_b32 s14, m0
	s_mov_b32 m0, s51
	s_nop 0
	global_load_lds_dwordx4 v168, s[8:9]
	s_mov_b32 m0, s14
	s_add_u32 s8, s12, 0x40080
	s_addc_u32 s9, s13, 0
	s_mov_b32 s12, m0
	s_mov_b32 m0, s59
	s_nop 0
	global_load_lds_dwordx4 v166, s[8:9]
	s_mov_b32 m0, s12
	s_nop 0
	s_mov_b32 s12, m0
	s_mov_b32 m0, s85
	s_nop 0
	global_load_lds_dwordx4 v168, s[8:9]
	s_mov_b32 m0, s12
	s_mov_b32 s8, m0
	s_mov_b32 m0, s53
	s_nop 0
	global_load_lds_dwordx4 v1, s[10:11]
	s_mov_b32 m0, s8
	s_nop 0
	s_mov_b32 s8, m0
	s_mov_b32 m0, s58
	s_nop 0
	global_load_lds_dwordx4 v167, s[10:11]
	s_mov_b32 m0, s8
	s_waitcnt vmcnt(8)
	s_waitcnt lgkmcnt(0)
	s_barrier
	s_setprio 1
	s_waitcnt lgkmcnt(7)
	v_mfma_f32_16x16x32_bf16 v[74:77], v[54:57], v[180:183], v[74:77]
	v_mfma_f32_16x16x32_bf16 v[66:69], v[70:73], v[180:183], v[66:69]
	s_waitcnt lgkmcnt(5)
	v_mfma_f32_16x16x32_bf16 v[58:61], v[54:57], v[188:191], v[58:61]
	v_mfma_f32_16x16x32_bf16 v[50:53], v[70:73], v[188:191], v[50:53]
	s_waitcnt lgkmcnt(3)
	v_mfma_f32_16x16x32_bf16 v[42:45], v[54:57], v[196:199], v[42:45]
	v_mfma_f32_16x16x32_bf16 v[34:37], v[70:73], v[196:199], v[34:37]
	s_waitcnt lgkmcnt(1)
	v_mfma_f32_16x16x32_bf16 v[10:13], v[54:57], v[204:207], v[10:13]
	v_mfma_f32_16x16x32_bf16 v[2:5], v[70:73], v[204:207], v[2:5]
	v_mfma_f32_16x16x32_bf16 v[74:77], v[62:65], v[184:187], v[74:77]
	v_mfma_f32_16x16x32_bf16 v[66:69], v[78:81], v[184:187], v[66:69]
	v_mfma_f32_16x16x32_bf16 v[58:61], v[62:65], v[192:195], v[58:61]
	v_mfma_f32_16x16x32_bf16 v[50:53], v[78:81], v[192:195], v[50:53]
	v_mfma_f32_16x16x32_bf16 v[42:45], v[62:65], v[200:203], v[42:45]
	v_mfma_f32_16x16x32_bf16 v[34:37], v[78:81], v[200:203], v[34:37]
	s_waitcnt lgkmcnt(0)
	v_mfma_f32_16x16x32_bf16 v[10:13], v[62:65], v[208:211], v[10:13]
	v_mfma_f32_16x16x32_bf16 v[2:5], v[78:81], v[208:211], v[2:5]
	s_setprio 0
	s_setprio 1
	v_mfma_f32_16x16x32_bf16 v[18:21], v[146:149], v[180:183], v[18:21]
	v_mfma_f32_16x16x32_bf16 v[78:81], v[150:153], v[184:187], v[18:21]
	v_mfma_f32_16x16x32_bf16 v[18:21], v[156:159], v[180:183], v[22:25]
	v_mfma_f32_16x16x32_bf16 v[70:73], v[160:163], v[184:187], v[18:21]
	v_mfma_f32_16x16x32_bf16 v[18:21], v[146:149], v[188:191], v[26:29]
	v_mfma_f32_16x16x32_bf16 v[62:65], v[150:153], v[192:195], v[18:21]
	v_mfma_f32_16x16x32_bf16 v[18:21], v[156:159], v[188:191], v[30:33]
	v_mfma_f32_16x16x32_bf16 v[54:57], v[160:163], v[192:195], v[18:21]
	v_mfma_f32_16x16x32_bf16 v[18:21], v[146:149], v[196:199], v[46:49]
	v_mfma_f32_16x16x32_bf16 v[46:49], v[150:153], v[200:203], v[18:21]
	v_mfma_f32_16x16x32_bf16 v[18:21], v[156:159], v[196:199], v[38:41]
	v_mfma_f32_16x16x32_bf16 v[14:17], v[146:149], v[204:207], v[14:17]
	v_mfma_f32_16x16x32_bf16 v[6:9], v[156:159], v[204:207], v[6:9]
	v_mfma_f32_16x16x32_bf16 v[38:41], v[160:163], v[200:203], v[18:21]
	v_mfma_f32_16x16x32_bf16 v[14:17], v[150:153], v[208:211], v[14:17]
	v_mfma_f32_16x16x32_bf16 v[6:9], v[160:163], v[208:211], v[6:9]
	s_setprio 0
	s_add_i32 s23, s23, 2
	s_add_u32 s21, s21, 0x100
	s_addc_u32 s22, s22, 0
	s_cmp_lt_u32 s23, 14
	s_mov_b64 s[8:9], s[6:7]
	s_cbranch_scc1 .LBB0_452
	s_barrier
	v_readlane_b32 s6, v252, 13
	v_readlane_b32 s7, v252, 14
	s_andn2_b64 vcc, exec, s[6:7]
	s_cbranch_vccnz .LBB0_455
	s_barrier

.LBB0_856:
	v_and_b32_e32 v2, 15, v4
	v_bfe_u32 v3, v4, 4, 1
	v_cmp_eq_u32_e32 vcc, v2, v3
	v_and_b32_e32 v44, 0x800, v5
	v_lshlrev_b32_e32 v45, 4, v6
	v_cndmask_b32_e32 v162, 0, v1, vcc
	v_mov_b32_e32 v163, v162
	v_mov_b32_e32 v164, v162
	v_mov_b32_e32 v165, v162
	v_mov_b32_e32 v166, v162
	v_mov_b32_e32 v167, v162
	v_mov_b32_e32 v168, v162
	v_mov_b32_e32 v169, v162
	v_add3_u32 v227, 0, v44, v45
	s_waitcnt vmcnt(1) lgkmcnt(0)
	s_barrier
	ds_read_b128 v[22:25], v227 offset:1024
	ds_read_b128 v[18:21], v227
	ds_read_b128 v[36:39], v227 offset:512
	ds_read_b128 v[40:43], v227 offset:1536
	s_waitcnt vmcnt(2) lgkmcnt(2)
	v_mfma_f32_32x32x64_f8f6f4 v[2:17], v[18:25], v[178:185], 0
	v_add3_u32 v220, s28, v44, v45
	v_lshl_add_u64 v[222:223], v[34:35], 0, s[20:21]
	s_waitcnt vmcnt(1) lgkmcnt(0)
	s_barrier
	s_waitcnt lgkmcnt(0)
	v_mfma_f32_32x32x64_f8f6f4 v[50:65], v[36:43], v[178:185], 0
	s_waitcnt vmcnt(0)
	v_mfma_f32_32x32x64_f8f6f4 v[18:33], v[18:25], v[170:177], 0
	v_mfma_f32_32x32x64_f8f6f4 v[34:49], v[36:43], v[170:177], 0
	s_nop 12
	v_exp_f32_e32 v2, v2
	v_exp_f32_e32 v3, v3
	v_exp_f32_e32 v4, v4
	v_exp_f32_e32 v5, v5
	v_exp_f32_e32 v6, v6
	v_cvt_pk_bf8_f32 v2, v2, v3
	v_exp_f32_e32 v7, v7
	v_exp_f32_e32 v8, v8
	v_exp_f32_e32 v9, v9
	v_cvt_pk_bf8_f32 v2, v4, v5 op_sel:[0,0,1]
	v_cvt_pk_bf8_f32 v3, v6, v7
	s_nop 0
	s_add_i32 s20, s40, s35
	s_mov_b32 s21, m0
	s_mov_b32 m0, s20
	s_nop 0
	global_load_lds_dwordx4 v[222:223], off
	s_mov_b32 m0, s21
	v_lshl_add_u64 v[146:147], v[222:223], 0, s[14:15]
	v_exp_f32_e32 v10, v10
	v_exp_f32_e32 v11, v11
	v_exp_f32_e32 v12, v12
	v_exp_f32_e32 v13, v13
	v_exp_f32_e32 v14, v14
	v_exp_f32_e32 v15, v15
	v_cvt_pk_bf8_f32 v4, v10, v11
	v_cvt_pk_bf8_f32 v3, v8, v9 op_sel:[0,0,1]
	v_exp_f32_e32 v16, v16
	v_exp_f32_e32 v17, v17
	v_cvt_pk_bf8_f32 v5, v14, v15
	v_cvt_pk_bf8_f32 v4, v12, v13 op_sel:[0,0,1]
	s_nop 0
	s_nop 0
	ds_read_b128 v[82:85], v227 offset:8192
	ds_read_b128 v[86:89], v227 offset:9216
	v_exp_f32_e32 v50, v50
	v_exp_f32_e32 v51, v51
	v_exp_f32_e32 v52, v52
	v_exp_f32_e32 v53, v53
	v_exp_f32_e32 v54, v54
	v_cvt_pk_bf8_f32 v6, v50, v51
	v_exp_f32_e32 v55, v55
	v_cvt_pk_bf8_f32 v5, v16, v17 op_sel:[0,0,1]
	v_exp_f32_e32 v56, v56
	v_cvt_pk_bf8_f32 v6, v52, v53 op_sel:[0,0,1]
	v_exp_f32_e32 v57, v57
	v_cvt_pk_bf8_f32 v7, v54, v55
	ds_read_b128 v[122:125], v227 offset:8704
	ds_read_b128 v[126:129], v227 offset:9728
	v_exp_f32_e32 v58, v58
	v_exp_f32_e32 v59, v59
	v_exp_f32_e32 v60, v60
	v_exp_f32_e32 v61, v61
	v_exp_f32_e32 v62, v62
	v_cvt_pk_bf8_f32 v8, v58, v59
	v_exp_f32_e32 v63, v63
	v_cvt_pk_bf8_f32 v7, v56, v57 op_sel:[0,0,1]
	v_exp_f32_e32 v64, v64
	v_cvt_pk_bf8_f32 v8, v60, v61 op_sel:[0,0,1]
	v_exp_f32_e32 v65, v65
	v_cvt_pk_bf8_f32 v9, v62, v63
	s_waitcnt lgkmcnt(2)
	v_mfma_f32_32x32x64_f8f6f4 v[98:113], v[82:89], v[178:185], 0
	v_exp_f32_e32 v18, v18
	v_exp_f32_e32 v19, v19
	v_exp_f32_e32 v20, v20
	v_exp_f32_e32 v21, v21
	v_exp_f32_e32 v22, v22
	v_exp_f32_e32 v23, v23
	v_cvt_pk_bf8_f32 v18, v18, v19
	v_cvt_pk_bf8_f32 v9, v64, v65 op_sel:[0,0,1]
	v_exp_f32_e32 v24, v24
	v_exp_f32_e32 v25, v25
	v_cvt_pk_bf8_f32 v19, v22, v23
	v_cvt_pk_bf8_f32 v18, v20, v21 op_sel:[0,0,1]
	s_nop 0
	s_nop 0
	s_waitcnt lgkmcnt(0)
	v_mfma_f32_32x32x64_f8f6f4 v[66:81], v[122:129], v[178:185], 0
	v_exp_f32_e32 v26, v26
	v_exp_f32_e32 v27, v27
	v_exp_f32_e32 v28, v28
	v_exp_f32_e32 v29, v29
	v_exp_f32_e32 v30, v30
	v_exp_f32_e32 v31, v31
	v_cvt_pk_bf8_f32 v20, v26, v27
	v_cvt_pk_bf8_f32 v19, v24, v25 op_sel:[0,0,1]
	v_exp_f32_e32 v32, v32
	v_exp_f32_e32 v33, v33
	v_cvt_pk_bf8_f32 v21, v30, v31
	v_cvt_pk_bf8_f32 v20, v28, v29 op_sel:[0,0,1]
	s_nop 0
	s_nop 0
	ds_read_b128 v[10:13], v220
	ds_read_b128 v[14:17], v220 offset:1024
	v_mfma_f32_32x32x64_f8f6f4 v[82:97], v[82:89], v[170:177], 0
	v_exp_f32_e32 v34, v34
	v_exp_f32_e32 v35, v35
	v_exp_f32_e32 v36, v36
	v_exp_f32_e32 v37, v37
	v_exp_f32_e32 v38, v38
	v_cvt_pk_bf8_f32 v22, v34, v35
	v_exp_f32_e32 v39, v39
	v_cvt_pk_bf8_f32 v21, v32, v33 op_sel:[0,0,1]
	v_exp_f32_e32 v40, v40
	v_cvt_pk_bf8_f32 v22, v36, v37 op_sel:[0,0,1]
	v_exp_f32_e32 v41, v41
	v_cvt_pk_bf8_f32 v23, v38, v39
	ds_read_b128 v[114:117], v220 offset:512
	ds_read_b128 v[118:121], v220 offset:1536
	v_mfma_f32_32x32x64_f8f6f4 v[130:145], v[122:129], v[170:177], 0
	v_exp_f32_e32 v42, v42
	v_exp_f32_e32 v43, v43
	v_exp_f32_e32 v44, v44
	v_exp_f32_e32 v45, v45
	v_exp_f32_e32 v46, v46
	v_cvt_pk_bf8_f32 v24, v42, v43
	v_exp_f32_e32 v47, v47
	v_cvt_pk_bf8_f32 v23, v40, v41 op_sel:[0,0,1]
	v_exp_f32_e32 v48, v48
	v_cvt_pk_bf8_f32 v24, v44, v45 op_sel:[0,0,1]
	v_exp_f32_e32 v49, v49
	v_cvt_pk_bf8_f32 v25, v46, v47
	s_nop 0
	v_cvt_pk_bf8_f32 v25, v48, v49 op_sel:[0,0,1]
	s_waitcnt vmcnt(1) lgkmcnt(0)
	s_barrier
	s_waitcnt lgkmcnt(2)
	v_mfma_f32_32x32x64_f8f6f4 v[34:49], v[2:9], v[10:17], 0 cbsz:1
	v_exp_f32_e32 v98, v98
	v_exp_f32_e32 v99, v99
	v_exp_f32_e32 v100, v100
	v_exp_f32_e32 v101, v101
	v_exp_f32_e32 v102, v102
	v_exp_f32_e32 v103, v103
	v_cvt_pk_bf8_f32 v98, v98, v99
	v_exp_f32_e32 v104, v104
	v_exp_f32_e32 v105, v105
	v_cvt_pk_bf8_f32 v99, v102, v103
	v_cvt_pk_bf8_f32 v98, v100, v101 op_sel:[0,0,1]
	s_nop 0
	s_nop 0
	v_mfma_f32_16x16x128_f8f6f4 v[214:217], v[162:169], v[2:9], 0 blgp:1
	s_add_i32 s20, s39, s35
	s_mov_b32 s21, m0
	s_mov_b32 m0, s20
	s_nop 0
	global_load_lds_dwordx4 v[146:147], off
	s_mov_b32 m0, s21
	s_waitcnt lgkmcnt(0)
	v_mfma_f32_32x32x64_f8f6f4 v[50:65], v[2:9], v[114:121], 0 cbsz:1
	v_exp_f32_e32 v106, v106
	v_exp_f32_e32 v107, v107
	v_exp_f32_e32 v108, v108
	v_exp_f32_e32 v109, v109
	v_exp_f32_e32 v110, v110
	v_exp_f32_e32 v111, v111
	v_cvt_pk_bf8_f32 v100, v106, v107
	v_cvt_pk_bf8_f32 v99, v104, v105 op_sel:[0,0,1]
	v_exp_f32_e32 v112, v112
	v_exp_f32_e32 v113, v113
	v_cvt_pk_bf8_f32 v101, v110, v111
	v_cvt_pk_bf8_f32 v100, v108, v109 op_sel:[0,0,1]
	s_nop 0
	s_nop 0
	ds_read_b128 v[194:197], v227 offset:16384
	ds_read_b128 v[198:201], v227 offset:17408
	v_mfma_f32_32x32x64_f8f6f4 v[2:17], v[18:25], v[10:17], 0 cbsz:1
	v_exp_f32_e32 v66, v66
	v_exp_f32_e32 v67, v67
	v_exp_f32_e32 v68, v68
	v_exp_f32_e32 v69, v69
	v_exp_f32_e32 v70, v70
	v_cvt_pk_bf8_f32 v102, v66, v67
	v_exp_f32_e32 v71, v71
	v_cvt_pk_bf8_f32 v101, v112, v113 op_sel:[0,0,1]
	v_exp_f32_e32 v72, v72
	v_cvt_pk_bf8_f32 v102, v68, v69 op_sel:[0,0,1]
	v_exp_f32_e32 v73, v73
	v_cvt_pk_bf8_f32 v103, v70, v71
	ds_read_b128 v[202:205], v227 offset:16896
	ds_read_b128 v[206:209], v227 offset:17920
	v_mfma_f32_16x16x128_f8f6f4 v[210:213], v[162:169], v[18:25], 0 blgp:1
	v_mfma_f32_32x32x64_f8f6f4 v[18:33], v[18:25], v[114:121], 0 cbsz:1
	v_exp_f32_e32 v74, v74
	v_exp_f32_e32 v75, v75
	v_exp_f32_e32 v76, v76
	v_exp_f32_e32 v77, v77
	v_exp_f32_e32 v78, v78
	v_cvt_pk_bf8_f32 v104, v74, v75
	v_exp_f32_e32 v79, v79
	v_cvt_pk_bf8_f32 v103, v72, v73 op_sel:[0,0,1]
	v_exp_f32_e32 v80, v80
	v_cvt_pk_bf8_f32 v104, v76, v77 op_sel:[0,0,1]
	v_exp_f32_e32 v81, v81
	v_cvt_pk_bf8_f32 v105, v78, v79
	s_waitcnt lgkmcnt(2)
	v_mfma_f32_32x32x64_f8f6f4 v[114:129], v[194:201], v[178:185], 0
	v_exp_f32_e32 v82, v82
	v_exp_f32_e32 v83, v83
	v_exp_f32_e32 v84, v84
	v_exp_f32_e32 v85, v85
	v_exp_f32_e32 v86, v86
	v_exp_f32_e32 v87, v87
	v_cvt_pk_bf8_f32 v82, v82, v83
	v_cvt_pk_bf8_f32 v105, v80, v81 op_sel:[0,0,1]
	v_exp_f32_e32 v88, v88
	v_exp_f32_e32 v89, v89
	v_cvt_pk_bf8_f32 v83, v86, v87
	v_cvt_pk_bf8_f32 v82, v84, v85 op_sel:[0,0,1]
	s_nop 0
	s_nop 0
	s_waitcnt lgkmcnt(0)
	v_mfma_f32_32x32x64_f8f6f4 v[146:161], v[202:209], v[178:185], 0
	v_exp_f32_e32 v90, v90
	v_exp_f32_e32 v91, v91
	v_exp_f32_e32 v92, v92
	v_exp_f32_e32 v93, v93
	v_exp_f32_e32 v94, v94
	v_exp_f32_e32 v95, v95
	v_cvt_pk_bf8_f32 v84, v90, v91
	v_cvt_pk_bf8_f32 v83, v88, v89 op_sel:[0,0,1]
	v_exp_f32_e32 v96, v96
	v_exp_f32_e32 v97, v97
	v_cvt_pk_bf8_f32 v85, v94, v95
	v_cvt_pk_bf8_f32 v84, v92, v93 op_sel:[0,0,1]
	s_nop 0
	s_nop 0
	ds_read_b128 v[186:189], v220 offset:8192
	ds_read_b128 v[190:193], v220 offset:9216
	v_mfma_f32_32x32x64_f8f6f4 v[66:81], v[194:201], v[170:177], 0
	v_exp_f32_e32 v130, v130
	v_exp_f32_e32 v131, v131
	v_exp_f32_e32 v132, v132
	v_exp_f32_e32 v133, v133
	v_exp_f32_e32 v134, v134
	v_cvt_pk_bf8_f32 v86, v130, v131
	v_exp_f32_e32 v135, v135
	v_cvt_pk_bf8_f32 v85, v96, v97 op_sel:[0,0,1]
	v_exp_f32_e32 v136, v136
	v_cvt_pk_bf8_f32 v86, v132, v133 op_sel:[0,0,1]
	v_exp_f32_e32 v137, v137
	v_cvt_pk_bf8_f32 v87, v134, v135
	ds_read_b128 v[106:109], v220 offset:8704
	ds_read_b128 v[110:113], v220 offset:9728
	v_exp_f32_e32 v138, v138
	v_exp_f32_e32 v139, v139
	v_exp_f32_e32 v140, v140
	v_exp_f32_e32 v141, v141
	v_exp_f32_e32 v142, v142
	v_cvt_pk_bf8_f32 v88, v138, v139
	v_exp_f32_e32 v143, v143
	v_cvt_pk_bf8_f32 v87, v136, v137 op_sel:[0,0,1]
	v_exp_f32_e32 v144, v144
	v_cvt_pk_bf8_f32 v88, v140, v141 op_sel:[0,0,1]
	v_exp_f32_e32 v145, v145
	v_cvt_pk_bf8_f32 v89, v142, v143
	s_nop 0
	v_cvt_pk_bf8_f32 v89, v144, v145 op_sel:[0,0,1]
	v_mfma_f32_32x32x64_f8f6f4 v[130:145], v[202:209], v[170:177], 0
	s_waitcnt vmcnt(1) lgkmcnt(0)
	s_movk_i32 s20, 0x2000
	s_mov_b32 s21, 0
.LBB0_857:
	s_barrier
	s_mov_b32 s39, s21
	s_mov_b32 s21, s37
	v_lshl_add_u64 v[224:225], v[222:223], 0, s[18:19]
	s_waitcnt lgkmcnt(2)
	v_mfma_f32_32x32x64_f8f6f4 v[34:49], v[98:105], v[186:193], v[34:49] cbsz:1
	v_exp_f32_e32 v114, v114
	v_exp_f32_e32 v115, v115
	v_exp_f32_e32 v116, v116
	v_exp_f32_e32 v117, v117
	v_exp_f32_e32 v118, v118
	v_exp_f32_e32 v119, v119
	v_cvt_pk_bf8_f32 v114, v114, v115
	v_exp_f32_e32 v120, v120
	v_exp_f32_e32 v121, v121
	v_cvt_pk_bf8_f32 v115, v118, v119
	v_cvt_pk_bf8_f32 v114, v116, v117 op_sel:[0,0,1]
	s_nop 0
	s_nop 0
	v_mfma_f32_16x16x128_f8f6f4 v[202:205], v[162:169], v[98:105], v[214:217] blgp:1
	s_and_b64 s[40:41], s[16:17], exec
	s_cselect_b32 s37, s37, s20
	s_add_i32 s37, s37, s35
	s_mov_b32 s40, m0
	s_mov_b32 m0, s37
	s_nop 0
	global_load_lds_dwordx4 v[224:225], off
	s_mov_b32 m0, s40
	v_lshl_add_u64 v[222:223], v[222:223], 0, s[0:1]
	s_waitcnt lgkmcnt(0)
	v_mfma_f32_32x32x64_f8f6f4 v[50:65], v[98:105], v[106:113], v[50:65] cbsz:1
	v_exp_f32_e32 v122, v122
	v_exp_f32_e32 v123, v123
	v_exp_f32_e32 v124, v124
	v_exp_f32_e32 v125, v125
	v_exp_f32_e32 v126, v126
	v_exp_f32_e32 v127, v127
	v_cvt_pk_bf8_f32 v116, v122, v123
	v_cvt_pk_bf8_f32 v115, v120, v121 op_sel:[0,0,1]
	v_exp_f32_e32 v128, v128
	v_exp_f32_e32 v129, v129
	v_cvt_pk_bf8_f32 v117, v126, v127
	v_cvt_pk_bf8_f32 v116, v124, v125 op_sel:[0,0,1]
	v_add_u32_e32 v198, s39, v227
	s_nop 0
	ds_read_b128 v[90:93], v198
	ds_read_b128 v[94:97], v198 offset:1024
	v_mfma_f32_32x32x64_f8f6f4 v[2:17], v[82:89], v[186:193], v[2:17] cbsz:1
	v_exp_f32_e32 v146, v146
	v_exp_f32_e32 v147, v147
	v_exp_f32_e32 v148, v148
	v_exp_f32_e32 v149, v149
	v_exp_f32_e32 v150, v150
	v_cvt_pk_bf8_f32 v118, v146, v147
	v_exp_f32_e32 v151, v151
	v_cvt_pk_bf8_f32 v117, v128, v129 op_sel:[0,0,1]
	v_exp_f32_e32 v152, v152
	v_cvt_pk_bf8_f32 v118, v148, v149 op_sel:[0,0,1]
	v_exp_f32_e32 v153, v153
	v_cvt_pk_bf8_f32 v119, v150, v151
	ds_read_b128 v[194:197], v198 offset:512
	ds_read_b128 v[198:201], v198 offset:1536
	v_mfma_f32_16x16x128_f8f6f4 v[206:209], v[162:169], v[82:89], v[210:213] blgp:1
	v_mfma_f32_32x32x64_f8f6f4 v[18:33], v[82:89], v[106:113], v[18:33] cbsz:1
	v_exp_f32_e32 v154, v154
	v_exp_f32_e32 v155, v155
	v_exp_f32_e32 v156, v156
	v_exp_f32_e32 v157, v157
	v_exp_f32_e32 v158, v158
	v_cvt_pk_bf8_f32 v120, v154, v155
	v_exp_f32_e32 v159, v159
	v_cvt_pk_bf8_f32 v119, v152, v153 op_sel:[0,0,1]
	v_exp_f32_e32 v160, v160
	v_cvt_pk_bf8_f32 v120, v156, v157 op_sel:[0,0,1]
	v_exp_f32_e32 v161, v161
	v_cvt_pk_bf8_f32 v121, v158, v159
	s_waitcnt lgkmcnt(2)
	v_mfma_f32_32x32x64_f8f6f4 v[98:113], v[90:97], v[178:185], 0
	v_exp_f32_e32 v66, v66
	v_exp_f32_e32 v67, v67
	v_exp_f32_e32 v68, v68
	v_exp_f32_e32 v69, v69
	v_exp_f32_e32 v70, v70
	v_exp_f32_e32 v71, v71
	v_cvt_pk_bf8_f32 v66, v66, v67
	v_cvt_pk_bf8_f32 v121, v160, v161 op_sel:[0,0,1]
	v_exp_f32_e32 v72, v72
	v_exp_f32_e32 v73, v73
	v_cvt_pk_bf8_f32 v67, v70, v71
	v_cvt_pk_bf8_f32 v66, v68, v69 op_sel:[0,0,1]
	s_nop 0
	s_nop 0
	s_waitcnt lgkmcnt(0)
	v_mfma_f32_32x32x64_f8f6f4 v[146:161], v[194:201], v[178:185], 0
	v_exp_f32_e32 v74, v74
	v_exp_f32_e32 v75, v75
	v_exp_f32_e32 v76, v76
	v_exp_f32_e32 v77, v77
	v_exp_f32_e32 v78, v78
	v_exp_f32_e32 v79, v79
	v_cvt_pk_bf8_f32 v68, v74, v75
	v_cvt_pk_bf8_f32 v67, v72, v73 op_sel:[0,0,1]
	v_exp_f32_e32 v80, v80
	v_exp_f32_e32 v81, v81
	v_cvt_pk_bf8_f32 v69, v78, v79
	v_cvt_pk_bf8_f32 v68, v76, v77 op_sel:[0,0,1]
	v_add_u32_e32 v82, s21, v220
	s_nop 0
	ds_read_b128 v[122:125], v82
	ds_read_b128 v[126:129], v82 offset:1024
	v_exp_f32_e32 v130, v130
	v_exp_f32_e32 v131, v131
	v_exp_f32_e32 v132, v132
	v_exp_f32_e32 v133, v133
	v_exp_f32_e32 v134, v134
	v_cvt_pk_bf8_f32 v70, v130, v131
	v_exp_f32_e32 v135, v135
	v_cvt_pk_bf8_f32 v69, v80, v81 op_sel:[0,0,1]
	v_exp_f32_e32 v136, v136
	v_cvt_pk_bf8_f32 v70, v132, v133 op_sel:[0,0,1]
	v_exp_f32_e32 v137, v137
	v_cvt_pk_bf8_f32 v71, v134, v135
	ds_read_b128 v[186:189], v82 offset:512
	ds_read_b128 v[190:193], v82 offset:1536
	v_mfma_f32_32x32x64_f8f6f4 v[82:97], v[90:97], v[170:177], 0
	v_exp_f32_e32 v138, v138
	v_exp_f32_e32 v139, v139
	v_exp_f32_e32 v140, v140
	v_exp_f32_e32 v141, v141
	v_exp_f32_e32 v142, v142
	v_cvt_pk_bf8_f32 v72, v138, v139
	v_exp_f32_e32 v143, v143
	v_cvt_pk_bf8_f32 v71, v136, v137 op_sel:[0,0,1]
	v_exp_f32_e32 v144, v144
	v_cvt_pk_bf8_f32 v72, v140, v141 op_sel:[0,0,1]
	v_exp_f32_e32 v145, v145
	v_cvt_pk_bf8_f32 v73, v142, v143
	s_nop 0
	v_cvt_pk_bf8_f32 v73, v144, v145 op_sel:[0,0,1]
	v_mfma_f32_32x32x64_f8f6f4 v[130:145], v[194:201], v[170:177], 0
	s_waitcnt vmcnt(1) lgkmcnt(0)
	s_barrier
	s_waitcnt lgkmcnt(2)
	v_mfma_f32_32x32x64_f8f6f4 v[34:49], v[114:121], v[122:129], v[34:49] cbsz:1
	v_exp_f32_e32 v98, v98
	v_exp_f32_e32 v99, v99
	v_exp_f32_e32 v100, v100
	v_exp_f32_e32 v101, v101
	v_exp_f32_e32 v102, v102
	v_exp_f32_e32 v103, v103
	v_cvt_pk_bf8_f32 v98, v98, v99
	v_exp_f32_e32 v104, v104
	v_exp_f32_e32 v105, v105
	v_cvt_pk_bf8_f32 v99, v102, v103
	v_cvt_pk_bf8_f32 v98, v100, v101 op_sel:[0,0,1]
	s_nop 0
	s_nop 0
	v_mfma_f32_16x16x128_f8f6f4 v[214:217], v[162:169], v[114:121], v[202:205] blgp:1
	s_and_b64 s[40:41], s[16:17], exec
	s_cselect_b32 s37, s39, s21
	s_add_i32 s37, s37, s35
	s_mov_b32 s40, m0
	s_mov_b32 m0, s37
	s_nop 0
	global_load_lds_dwordx4 v[222:223], off
	s_mov_b32 m0, s40
	s_waitcnt lgkmcnt(0)
	v_mfma_f32_32x32x64_f8f6f4 v[50:65], v[114:121], v[186:193], v[50:65] cbsz:1
	v_exp_f32_e32 v106, v106
	v_exp_f32_e32 v107, v107
	v_exp_f32_e32 v108, v108
	v_exp_f32_e32 v109, v109
	v_exp_f32_e32 v110, v110
	v_exp_f32_e32 v111, v111
	v_cvt_pk_bf8_f32 v100, v106, v107
	v_cvt_pk_bf8_f32 v99, v104, v105 op_sel:[0,0,1]
	v_exp_f32_e32 v112, v112
	v_exp_f32_e32 v113, v113
	v_cvt_pk_bf8_f32 v101, v110, v111
	v_cvt_pk_bf8_f32 v100, v108, v109 op_sel:[0,0,1]
	v_add_u32_e32 v198, s20, v227
	s_nop 0
	ds_read_b128 v[74:77], v198
	ds_read_b128 v[78:81], v198 offset:1024
	v_mfma_f32_32x32x64_f8f6f4 v[2:17], v[66:73], v[122:129], v[2:17] cbsz:1
	v_exp_f32_e32 v146, v146
	v_exp_f32_e32 v147, v147
	v_exp_f32_e32 v148, v148
	v_exp_f32_e32 v149, v149
	v_exp_f32_e32 v150, v150
	v_cvt_pk_bf8_f32 v102, v146, v147
	v_exp_f32_e32 v151, v151
	v_cvt_pk_bf8_f32 v101, v112, v113 op_sel:[0,0,1]
	v_exp_f32_e32 v152, v152
	v_cvt_pk_bf8_f32 v102, v148, v149 op_sel:[0,0,1]
	v_exp_f32_e32 v153, v153
	v_cvt_pk_bf8_f32 v103, v150, v151
	ds_read_b128 v[194:197], v198 offset:512
	ds_read_b128 v[198:201], v198 offset:1536
	v_mfma_f32_16x16x128_f8f6f4 v[210:213], v[162:169], v[66:73], v[206:209] blgp:1
	v_mfma_f32_32x32x64_f8f6f4 v[18:33], v[66:73], v[186:193], v[18:33] cbsz:1
	v_exp_f32_e32 v154, v154
	v_exp_f32_e32 v155, v155
	v_exp_f32_e32 v156, v156
	v_exp_f32_e32 v157, v157
	v_exp_f32_e32 v158, v158
	v_cvt_pk_bf8_f32 v104, v154, v155
	v_exp_f32_e32 v159, v159
	v_cvt_pk_bf8_f32 v103, v152, v153 op_sel:[0,0,1]
	v_exp_f32_e32 v160, v160
	v_cvt_pk_bf8_f32 v104, v156, v157 op_sel:[0,0,1]
	v_exp_f32_e32 v161, v161
	v_cvt_pk_bf8_f32 v105, v158, v159
	s_waitcnt lgkmcnt(2)
	v_mfma_f32_32x32x64_f8f6f4 v[114:129], v[74:81], v[178:185], 0
	v_exp_f32_e32 v82, v82
	v_exp_f32_e32 v83, v83
	v_exp_f32_e32 v84, v84
	v_exp_f32_e32 v85, v85
	v_exp_f32_e32 v86, v86
	v_exp_f32_e32 v87, v87
	v_cvt_pk_bf8_f32 v82, v82, v83
	v_cvt_pk_bf8_f32 v105, v160, v161 op_sel:[0,0,1]
	v_exp_f32_e32 v88, v88
	v_exp_f32_e32 v89, v89
	v_cvt_pk_bf8_f32 v83, v86, v87
	v_cvt_pk_bf8_f32 v82, v84, v85 op_sel:[0,0,1]
	s_nop 0
	s_nop 0
	s_waitcnt lgkmcnt(0)
	v_mfma_f32_32x32x64_f8f6f4 v[146:161], v[194:201], v[178:185], 0
	v_exp_f32_e32 v90, v90
	v_exp_f32_e32 v91, v91
	v_exp_f32_e32 v92, v92
	v_exp_f32_e32 v93, v93
	v_exp_f32_e32 v94, v94
	v_exp_f32_e32 v95, v95
	v_cvt_pk_bf8_f32 v84, v90, v91
	v_cvt_pk_bf8_f32 v83, v88, v89 op_sel:[0,0,1]
	v_exp_f32_e32 v96, v96
	v_exp_f32_e32 v97, v97
	v_cvt_pk_bf8_f32 v85, v94, v95
	v_cvt_pk_bf8_f32 v84, v92, v93 op_sel:[0,0,1]
	v_add_u32_e32 v66, s39, v220
	s_nop 0
	ds_read_b128 v[186:189], v66
	ds_read_b128 v[190:193], v66 offset:1024
	v_exp_f32_e32 v130, v130
	v_exp_f32_e32 v131, v131
	v_exp_f32_e32 v132, v132
	v_exp_f32_e32 v133, v133
	v_exp_f32_e32 v134, v134
	v_cvt_pk_bf8_f32 v86, v130, v131
	v_exp_f32_e32 v135, v135
	v_cvt_pk_bf8_f32 v85, v96, v97 op_sel:[0,0,1]
	v_exp_f32_e32 v136, v136
	v_cvt_pk_bf8_f32 v86, v132, v133 op_sel:[0,0,1]
	v_exp_f32_e32 v137, v137
	v_cvt_pk_bf8_f32 v87, v134, v135
	ds_read_b128 v[106:109], v66 offset:512
	ds_read_b128 v[110:113], v66 offset:1536
	v_mfma_f32_32x32x64_f8f6f4 v[66:81], v[74:81], v[170:177], 0
	v_exp_f32_e32 v138, v138
	v_exp_f32_e32 v139, v139
	v_exp_f32_e32 v140, v140
	v_exp_f32_e32 v141, v141
	v_exp_f32_e32 v142, v142
	v_cvt_pk_bf8_f32 v88, v138, v139
	v_exp_f32_e32 v143, v143
	v_cvt_pk_bf8_f32 v87, v136, v137 op_sel:[0,0,1]
	v_exp_f32_e32 v144, v144
	v_cvt_pk_bf8_f32 v88, v140, v141 op_sel:[0,0,1]
	v_exp_f32_e32 v145, v145
	v_cvt_pk_bf8_f32 v89, v142, v143
	s_nop 0
	v_cvt_pk_bf8_f32 v89, v144, v145 op_sel:[0,0,1]
	v_mfma_f32_32x32x64_f8f6f4 v[130:145], v[194:201], v[170:177], 0
	s_waitcnt vmcnt(1) lgkmcnt(0)
	s_add_i32 s36, s36, 2
	v_mov_b64_e32 v[222:223], v[224:225]
	s_mov_b32 s37, s20
	s_cmpk_gt_u32 s36, 0x7d
	s_mov_b32 s20, s39
	s_cbranch_scc0 .LBB0_857
	s_barrier
	v_lshl_add_u64 v[222:223], v[224:225], 0, s[18:19]
	s_waitcnt lgkmcnt(2)
	v_mfma_f32_32x32x64_f8f6f4 v[34:49], v[98:105], v[186:193], v[34:49] cbsz:1
	v_exp_f32_e32 v114, v114
	v_exp_f32_e32 v115, v115
	v_exp_f32_e32 v116, v116
	v_exp_f32_e32 v117, v117
	v_exp_f32_e32 v118, v118
	v_exp_f32_e32 v119, v119
	v_cvt_pk_bf8_f32 v114, v114, v115
	v_exp_f32_e32 v120, v120
	v_exp_f32_e32 v121, v121
	v_cvt_pk_bf8_f32 v115, v118, v119
	v_cvt_pk_bf8_f32 v114, v116, v117 op_sel:[0,0,1]
	s_nop 0
	s_nop 0
	v_mfma_f32_16x16x128_f8f6f4 v[214:217], v[162:169], v[98:105], v[214:217] blgp:1
	s_and_b64 s[16:17], s[16:17], exec
	s_cselect_b32 s0, s23, 0x2000
	s_add_i32 s0, s35, s0
	s_mov_b32 s16, m0
	s_mov_b32 m0, s0
	s_nop 0
	global_load_lds_dwordx4 v[222:223], off
	s_mov_b32 m0, s16
	s_waitcnt lgkmcnt(0)
	v_mfma_f32_32x32x64_f8f6f4 v[50:65], v[98:105], v[106:113], v[50:65] cbsz:1
	v_exp_f32_e32 v122, v122
	v_exp_f32_e32 v123, v123
	v_exp_f32_e32 v124, v124
	v_exp_f32_e32 v125, v125
	v_exp_f32_e32 v126, v126
	v_exp_f32_e32 v127, v127
	v_cvt_pk_bf8_f32 v116, v122, v123
	v_cvt_pk_bf8_f32 v115, v120, v121 op_sel:[0,0,1]
	v_exp_f32_e32 v128, v128
	v_exp_f32_e32 v129, v129
	v_cvt_pk_bf8_f32 v117, v126, v127
	v_cvt_pk_bf8_f32 v116, v124, v125 op_sel:[0,0,1]
	s_nop 0
	s_nop 0
	ds_read_b128 v[90:93], v227
	ds_read_b128 v[94:97], v227 offset:1024
	v_mfma_f32_32x32x64_f8f6f4 v[2:17], v[82:89], v[186:193], v[2:17] cbsz:1
	v_exp_f32_e32 v146, v146
	v_exp_f32_e32 v147, v147
	v_exp_f32_e32 v148, v148
	v_exp_f32_e32 v149, v149
	v_exp_f32_e32 v150, v150
	v_cvt_pk_bf8_f32 v118, v146, v147
	v_exp_f32_e32 v151, v151
	v_cvt_pk_bf8_f32 v117, v128, v129 op_sel:[0,0,1]
	v_exp_f32_e32 v152, v152
	v_cvt_pk_bf8_f32 v118, v148, v149 op_sel:[0,0,1]
	v_exp_f32_e32 v153, v153
	v_cvt_pk_bf8_f32 v119, v150, v151
	ds_read_b128 v[202:205], v227 offset:512
	ds_read_b128 v[206:209], v227 offset:1536
	v_mfma_f32_16x16x128_f8f6f4 v[210:213], v[162:169], v[82:89], v[210:213] blgp:1
	v_mfma_f32_32x32x64_f8f6f4 v[18:33], v[82:89], v[106:113], v[18:33] cbsz:1
	v_exp_f32_e32 v154, v154
	v_exp_f32_e32 v155, v155
	v_exp_f32_e32 v156, v156
	v_exp_f32_e32 v157, v157
	v_exp_f32_e32 v158, v158
	v_cvt_pk_bf8_f32 v120, v154, v155
	v_exp_f32_e32 v159, v159
	v_cvt_pk_bf8_f32 v119, v152, v153 op_sel:[0,0,1]
	v_exp_f32_e32 v160, v160
	v_cvt_pk_bf8_f32 v120, v156, v157 op_sel:[0,0,1]
	v_exp_f32_e32 v161, v161
	v_cvt_pk_bf8_f32 v121, v158, v159
	s_waitcnt lgkmcnt(2)
	v_mfma_f32_32x32x64_f8f6f4 v[98:113], v[90:97], v[178:185], 0
	v_exp_f32_e32 v66, v66
	v_exp_f32_e32 v67, v67
	v_exp_f32_e32 v68, v68
	v_exp_f32_e32 v69, v69
	v_exp_f32_e32 v70, v70
	v_exp_f32_e32 v71, v71
	v_cvt_pk_bf8_f32 v66, v66, v67
	v_cvt_pk_bf8_f32 v121, v160, v161 op_sel:[0,0,1]
	v_exp_f32_e32 v72, v72
	v_exp_f32_e32 v73, v73
	v_cvt_pk_bf8_f32 v67, v70, v71
	v_cvt_pk_bf8_f32 v66, v68, v69 op_sel:[0,0,1]
	s_nop 0
	s_nop 0
	s_waitcnt lgkmcnt(0)
	v_mfma_f32_32x32x64_f8f6f4 v[146:161], v[202:209], v[178:185], 0
	v_exp_f32_e32 v74, v74
	v_exp_f32_e32 v75, v75
	v_exp_f32_e32 v76, v76
	v_exp_f32_e32 v77, v77
	v_exp_f32_e32 v78, v78
	v_exp_f32_e32 v79, v79
	v_cvt_pk_bf8_f32 v68, v74, v75
	v_cvt_pk_bf8_f32 v67, v72, v73 op_sel:[0,0,1]
	v_exp_f32_e32 v80, v80
	v_exp_f32_e32 v81, v81
	v_cvt_pk_bf8_f32 v69, v78, v79
	v_cvt_pk_bf8_f32 v68, v76, v77 op_sel:[0,0,1]
	s_nop 0
	s_nop 0
	ds_read_b128 v[186:189], v220 offset:16384
	ds_read_b128 v[190:193], v220 offset:17408
	v_mfma_f32_32x32x64_f8f6f4 v[82:97], v[90:97], v[170:177], 0
	v_exp_f32_e32 v130, v130
	v_exp_f32_e32 v131, v131
	v_exp_f32_e32 v132, v132
	v_exp_f32_e32 v133, v133
	v_exp_f32_e32 v134, v134
	v_cvt_pk_bf8_f32 v70, v130, v131
	v_exp_f32_e32 v135, v135
	v_cvt_pk_bf8_f32 v69, v80, v81 op_sel:[0,0,1]
	v_exp_f32_e32 v136, v136
	v_cvt_pk_bf8_f32 v70, v132, v133 op_sel:[0,0,1]
	v_exp_f32_e32 v137, v137
	v_cvt_pk_bf8_f32 v71, v134, v135
	ds_read_b128 v[194:197], v220 offset:16896
	ds_read_b128 v[198:201], v220 offset:17920
	v_exp_f32_e32 v138, v138
	v_exp_f32_e32 v139, v139
	v_exp_f32_e32 v140, v140
	v_exp_f32_e32 v141, v141
	v_exp_f32_e32 v142, v142
	v_cvt_pk_bf8_f32 v72, v138, v139
	v_exp_f32_e32 v143, v143
	v_exp_f32_e32 v144, v144
	v_exp_f32_e32 v145, v145
	v_cvt_pk_bf8_f32 v71, v136, v137 op_sel:[0,0,1]
	v_cvt_pk_bf8_f32 v72, v140, v141 op_sel:[0,0,1]
	v_cvt_pk_bf8_f32 v73, v142, v143
	s_nop 0
	v_mfma_f32_32x32x64_f8f6f4 v[122:137], v[202:209], v[170:177], 0
	s_waitcnt vmcnt(1) lgkmcnt(0)
	s_barrier
	s_waitcnt lgkmcnt(2)
	v_mfma_f32_32x32x64_f8f6f4 v[34:49], v[114:121], v[186:193], v[34:49] cbsz:1
	v_exp_f32_e32 v98, v98
	v_exp_f32_e32 v99, v99
	v_exp_f32_e32 v100, v100
	v_exp_f32_e32 v101, v101
	v_exp_f32_e32 v102, v102
	v_exp_f32_e32 v103, v103
	v_cvt_pk_bf8_f32 v98, v98, v99
	v_exp_f32_e32 v104, v104
	v_exp_f32_e32 v105, v105
	v_cvt_pk_bf8_f32 v99, v102, v103
	v_cvt_pk_bf8_f32 v98, v100, v101 op_sel:[0,0,1]
	s_nop 0
	s_nop 0
	v_mfma_f32_16x16x128_f8f6f4 v[202:205], v[162:169], v[114:121], v[214:217] blgp:1
	s_and_b64 vcc, exec, s[12:13]
	s_cbranch_vccz .LBB0_860
	v_lshl_add_u64 v[74:75], v[222:223], 0, s[14:15]
	s_add_i32 s0, s35, 0x4000
	s_mov_b32 s12, m0
	s_mov_b32 m0, s0
	s_nop 0
	global_load_lds_dwordx4 v[74:75], off
	s_mov_b32 m0, s12

.LBB0_1151:
	s_ashr_i32 s17, s16, 31
	s_lshl_b64 s[22:23], s[16:17], 19
	s_add_u32 s22, s24, s22
	s_addc_u32 s23, s25, s23
	s_ashr_i32 s19, s18, 31
	s_lshl_b64 s[30:31], s[18:19], 19
	s_add_u32 s30, s84, s30
	s_addc_u32 s31, s85, s31
	s_add_u32 s36, s38, 0x100
	s_addc_u32 s37, s39, 0
	s_add_u32 s40, s38, 0x180
	s_waitcnt lgkmcnt(0)
	ds_read_b128 v[2:5], v211
	ds_read_b128 v[6:9], v211 offset:1024
	s_waitcnt vmcnt(0)
	ds_read_b128 v[10:13], v211 offset:2048
	ds_read_b128 v[14:17], v211 offset:3072
	ds_read_b128 v[18:21], v212
	ds_read_b128 v[22:25], v212 offset:1024
	ds_read_b128 v[26:29], v212 offset:2048
	ds_read_b128 v[30:33], v212 offset:3072
	s_addc_u32 s41, s39, 0
	s_and_b64 s[42:43], s[20:21], exec
	s_cselect_b32 s17, s23, s39
	s_cselect_b32 s19, s22, s38
	s_add_u32 s42, s0, 0x100
	s_addc_u32 s43, s1, 0
	s_and_b64 s[62:63], s[20:21], exec
	s_cselect_b32 s29, s31, s1
	s_cselect_b32 s61, s30, s0
	ds_read_b128 v[34:37], v213
	ds_read_b128 v[38:41], v213 offset:1024
	ds_read_b128 v[42:45], v213 offset:2048
	ds_read_b128 v[46:49], v213 offset:3072
	ds_read_b128 v[50:53], v213 offset:4096
	ds_read_b128 v[54:57], v213 offset:5120
	ds_read_b128 v[58:61], v213 offset:6144
	ds_read_b128 v[62:65], v213 offset:7168
	s_add_u32 s62, s38, 0x40080
	s_addc_u32 s63, s39, 0
	s_mov_b32 s64, m0
	s_mov_b32 m0, s58
	s_nop 0
	global_load_lds_dwordx4 v1, s[62:63]
	s_mov_b32 m0, s64
	s_nop 0
	s_mov_b32 s64, m0
	s_mov_b32 m0, s59
	s_nop 0
	global_load_lds_dwordx4 v207, s[62:63]
	s_mov_b32 m0, s64
	s_waitcnt vmcnt(8)
	s_waitcnt lgkmcnt(0)
	s_barrier
	s_setprio 1
	s_waitcnt lgkmcnt(7)
	v_mfma_f32_16x16x32_bf16 v[66:69], v[2:5], v[34:37], 0
	v_mfma_f32_16x16x32_bf16 v[70:73], v[10:13], v[34:37], 0
	s_waitcnt lgkmcnt(5)
	v_mfma_f32_16x16x32_bf16 v[74:77], v[2:5], v[42:45], 0
	v_mfma_f32_16x16x32_bf16 v[78:81], v[10:13], v[42:45], 0
	s_waitcnt lgkmcnt(3)
	v_mfma_f32_16x16x32_bf16 v[82:85], v[2:5], v[50:53], 0
	v_mfma_f32_16x16x32_bf16 v[86:89], v[10:13], v[50:53], 0
	s_waitcnt lgkmcnt(1)
	v_mfma_f32_16x16x32_bf16 v[90:93], v[2:5], v[58:61], 0
	v_mfma_f32_16x16x32_bf16 v[94:97], v[10:13], v[58:61], 0
	v_mfma_f32_16x16x32_bf16 v[66:69], v[6:9], v[38:41], v[66:69]
	v_mfma_f32_16x16x32_bf16 v[70:73], v[14:17], v[38:41], v[70:73]
	v_mfma_f32_16x16x32_bf16 v[74:77], v[6:9], v[46:49], v[74:77]
	v_mfma_f32_16x16x32_bf16 v[78:81], v[14:17], v[46:49], v[78:81]
	v_mfma_f32_16x16x32_bf16 v[82:85], v[6:9], v[54:57], v[82:85]
	v_mfma_f32_16x16x32_bf16 v[86:89], v[14:17], v[54:57], v[86:89]
	s_waitcnt lgkmcnt(0)
	v_mfma_f32_16x16x32_bf16 v[90:93], v[6:9], v[62:65], v[90:93]
	v_mfma_f32_16x16x32_bf16 v[98:101], v[14:17], v[62:65], v[94:97]
	s_setprio 0
	s_setprio 1
	v_mfma_f32_16x16x32_bf16 v[94:97], v[18:21], v[34:37], 0
	v_mfma_f32_16x16x32_bf16 v[34:37], v[26:29], v[34:37], 0
	v_mfma_f32_16x16x32_bf16 v[102:105], v[22:25], v[38:41], v[94:97]
	v_mfma_f32_16x16x32_bf16 v[34:37], v[30:33], v[38:41], v[34:37]
	v_mfma_f32_16x16x32_bf16 v[38:41], v[18:21], v[42:45], 0
	v_mfma_f32_16x16x32_bf16 v[42:45], v[26:29], v[42:45], 0
	v_mfma_f32_16x16x32_bf16 v[38:41], v[22:25], v[46:49], v[38:41]
	v_mfma_f32_16x16x32_bf16 v[42:45], v[30:33], v[46:49], v[42:45]
	v_mfma_f32_16x16x32_bf16 v[46:49], v[18:21], v[50:53], 0
	v_mfma_f32_16x16x32_bf16 v[50:53], v[26:29], v[50:53], 0
	v_mfma_f32_16x16x32_bf16 v[46:49], v[22:25], v[54:57], v[46:49]
	v_mfma_f32_16x16x32_bf16 v[50:53], v[30:33], v[54:57], v[50:53]
	v_mfma_f32_16x16x32_bf16 v[54:57], v[18:21], v[58:61], 0
	v_mfma_f32_16x16x32_bf16 v[58:61], v[26:29], v[58:61], 0
	v_mfma_f32_16x16x32_bf16 v[54:57], v[22:25], v[62:65], v[54:57]
	v_mfma_f32_16x16x32_bf16 v[58:61], v[30:33], v[62:65], v[58:61]
	s_setprio 0
	s_barrier
	ds_read_b128 v[62:65], v213 offset:16384
	ds_read_b128 v[94:97], v213 offset:17408
	ds_read_b128 v[106:109], v213 offset:18432
	ds_read_b128 v[110:113], v213 offset:19456
	ds_read_b128 v[114:117], v213 offset:20480
	ds_read_b128 v[118:121], v213 offset:21504
	ds_read_b128 v[122:125], v213 offset:22528
	ds_read_b128 v[126:129], v213 offset:23552
	s_mov_b32 s62, m0
	s_mov_b32 m0, s34
	s_nop 0
	global_load_lds_dwordx4 v206, s[42:43]
	s_mov_b32 m0, s62
	s_nop 0
	s_mov_b32 s62, m0
	s_mov_b32 m0, s35
	s_nop 0
	global_load_lds_dwordx4 v208, s[42:43]
	s_mov_b32 m0, s62
	s_add_u32 s42, s0, 0x40100
	s_addc_u32 s43, s1, 0
	s_mov_b32 s62, m0
	s_mov_b32 m0, s44
	s_nop 0
	global_load_lds_dwordx4 v206, s[42:43]
	s_mov_b32 m0, s62
	s_nop 0
	s_mov_b32 s62, m0
	s_mov_b32 m0, s45
	s_nop 0
	global_load_lds_dwordx4 v208, s[42:43]
	s_mov_b32 m0, s62
	s_mov_b32 s42, m0
	s_mov_b32 m0, s33
	s_nop 0
	global_load_lds_dwordx4 v1, s[36:37]
	s_mov_b32 m0, s42
	s_nop 0
	s_mov_b32 s42, m0
	s_mov_b32 m0, s46
	s_nop 0
	global_load_lds_dwordx4 v207, s[36:37]
	s_mov_b32 m0, s42
	s_waitcnt vmcnt(8)
	s_waitcnt lgkmcnt(0)
	s_barrier
	s_setprio 1
	s_waitcnt lgkmcnt(7)
	v_mfma_f32_16x16x32_bf16 v[130:133], v[2:5], v[62:65], 0
	s_waitcnt lgkmcnt(6)
	v_mfma_f32_16x16x32_bf16 v[146:149], v[6:9], v[94:97], v[130:133]
	v_mfma_f32_16x16x32_bf16 v[130:133], v[10:13], v[62:65], 0
	v_mfma_f32_16x16x32_bf16 v[150:153], v[14:17], v[94:97], v[130:133]
	s_waitcnt lgkmcnt(5)
	v_mfma_f32_16x16x32_bf16 v[130:133], v[2:5], v[106:109], 0
	s_waitcnt lgkmcnt(4)
	v_mfma_f32_16x16x32_bf16 v[154:157], v[6:9], v[110:113], v[130:133]
	v_mfma_f32_16x16x32_bf16 v[130:133], v[10:13], v[106:109], 0
	v_mfma_f32_16x16x32_bf16 v[158:161], v[14:17], v[110:113], v[130:133]
	s_waitcnt lgkmcnt(3)
	v_mfma_f32_16x16x32_bf16 v[130:133], v[2:5], v[114:117], 0
	s_waitcnt lgkmcnt(1)
	v_mfma_f32_16x16x32_bf16 v[2:5], v[2:5], v[122:125], 0
	v_mfma_f32_16x16x32_bf16 v[162:165], v[6:9], v[118:121], v[130:133]
	s_waitcnt lgkmcnt(0)
	v_mfma_f32_16x16x32_bf16 v[2:5], v[6:9], v[126:129], v[2:5]
	v_mfma_f32_16x16x32_bf16 v[6:9], v[10:13], v[122:125], 0
	v_mfma_f32_16x16x32_bf16 v[130:133], v[10:13], v[114:117], 0
	v_mfma_f32_16x16x32_bf16 v[6:9], v[14:17], v[126:129], v[6:9]
	v_mfma_f32_16x16x32_bf16 v[166:169], v[14:17], v[118:121], v[130:133]
	s_setprio 0
	s_setprio 1
	v_mfma_f32_16x16x32_bf16 v[10:13], v[18:21], v[62:65], 0
	v_mfma_f32_16x16x32_bf16 v[170:173], v[22:25], v[94:97], v[10:13]
	v_mfma_f32_16x16x32_bf16 v[10:13], v[26:29], v[62:65], 0
	v_mfma_f32_16x16x32_bf16 v[62:65], v[30:33], v[94:97], v[10:13]
	v_mfma_f32_16x16x32_bf16 v[10:13], v[18:21], v[106:109], 0
	v_mfma_f32_16x16x32_bf16 v[174:177], v[22:25], v[110:113], v[10:13]
	v_mfma_f32_16x16x32_bf16 v[10:13], v[26:29], v[106:109], 0
	v_mfma_f32_16x16x32_bf16 v[178:181], v[30:33], v[110:113], v[10:13]
	v_mfma_f32_16x16x32_bf16 v[10:13], v[18:21], v[114:117], 0
	v_mfma_f32_16x16x32_bf16 v[182:185], v[22:25], v[118:121], v[10:13]
	v_mfma_f32_16x16x32_bf16 v[10:13], v[26:29], v[114:117], 0
	v_mfma_f32_16x16x32_bf16 v[186:189], v[30:33], v[118:121], v[10:13]
	v_mfma_f32_16x16x32_bf16 v[10:13], v[18:21], v[122:125], 0
	v_mfma_f32_16x16x32_bf16 v[190:193], v[22:25], v[126:129], v[10:13]
	v_mfma_f32_16x16x32_bf16 v[10:13], v[26:29], v[122:125], 0
	v_mfma_f32_16x16x32_bf16 v[194:197], v[30:33], v[126:129], v[10:13]
	s_setprio 0
	s_barrier
	s_nop 4
	ds_read_b128 v[10:13], v214
	ds_read_b128 v[14:17], v214 offset:1024
	ds_read_b128 v[18:21], v214 offset:2048
	ds_read_b128 v[22:25], v214 offset:3072
	ds_read_b128 v[198:201], v215
	ds_read_b128 v[202:205], v215 offset:1024
	ds_read_b128 v[218:221], v215 offset:2048
	ds_read_b128 v[222:225], v215 offset:3072
	ds_read_b128 v[26:29], v213 offset:32768
	ds_read_b128 v[30:33], v213 offset:33792
	ds_read_b128 v[114:117], v213 offset:34816
	ds_read_b128 v[226:229], v213 offset:35840
	ds_read_b128 v[230:233], v213 offset:36864
	ds_read_b128 v[234:237], v213 offset:37888
	ds_read_b128 v[238:241], v213 offset:38912
	ds_read_b128 v[242:245], v213 offset:39936
	s_add_u32 s38, s38, 0x40100
	s_addc_u32 s39, s39, 0
	s_mov_b32 s42, m0
	s_mov_b32 m0, s47
	s_nop 0
	global_load_lds_dwordx4 v1, s[38:39]
	s_mov_b32 m0, s42
	s_nop 0
	s_mov_b32 s42, m0
	s_mov_b32 m0, s48
	s_nop 0
	global_load_lds_dwordx4 v207, s[38:39]
	s_mov_b32 m0, s42
	s_waitcnt vmcnt(8)
	s_waitcnt lgkmcnt(0)
	s_barrier
	s_setprio 1
	s_waitcnt lgkmcnt(7)
	v_mfma_f32_16x16x32_bf16 v[66:69], v[10:13], v[26:29], v[66:69]
	s_waitcnt lgkmcnt(6)
	v_mfma_f32_16x16x32_bf16 v[142:145], v[14:17], v[30:33], v[66:69]
	v_mfma_f32_16x16x32_bf16 v[66:69], v[18:21], v[26:29], v[70:73]
	v_mfma_f32_16x16x32_bf16 v[138:141], v[22:25], v[30:33], v[66:69]
	s_waitcnt lgkmcnt(5)
	v_mfma_f32_16x16x32_bf16 v[66:69], v[10:13], v[114:117], v[74:77]
	s_waitcnt lgkmcnt(4)
	v_mfma_f32_16x16x32_bf16 v[126:129], v[14:17], v[226:229], v[66:69]
	v_mfma_f32_16x16x32_bf16 v[66:69], v[18:21], v[114:117], v[78:81]
	v_mfma_f32_16x16x32_bf16 v[122:125], v[22:25], v[226:229], v[66:69]
	s_waitcnt lgkmcnt(3)
	v_mfma_f32_16x16x32_bf16 v[66:69], v[10:13], v[230:233], v[82:85]
	s_waitcnt lgkmcnt(2)
	v_mfma_f32_16x16x32_bf16 v[110:113], v[14:17], v[234:237], v[66:69]
	v_mfma_f32_16x16x32_bf16 v[66:69], v[18:21], v[230:233], v[86:89]
	v_mfma_f32_16x16x32_bf16 v[106:109], v[22:25], v[234:237], v[66:69]
	s_waitcnt lgkmcnt(1)
	v_mfma_f32_16x16x32_bf16 v[66:69], v[10:13], v[238:241], v[90:93]
	s_waitcnt lgkmcnt(0)
	v_mfma_f32_16x16x32_bf16 v[94:97], v[14:17], v[242:245], v[66:69]
	v_mfma_f32_16x16x32_bf16 v[66:69], v[18:21], v[238:241], v[98:101]
	v_mfma_f32_16x16x32_bf16 v[90:93], v[22:25], v[242:245], v[66:69]
	s_setprio 0
	s_setprio 1
	v_mfma_f32_16x16x32_bf16 v[66:69], v[198:201], v[26:29], v[102:105]
	v_mfma_f32_16x16x32_bf16 v[26:29], v[218:221], v[26:29], v[34:37]
	v_mfma_f32_16x16x32_bf16 v[130:133], v[222:225], v[30:33], v[26:29]
	v_mfma_f32_16x16x32_bf16 v[26:29], v[198:201], v[114:117], v[38:41]
	v_mfma_f32_16x16x32_bf16 v[118:121], v[202:205], v[226:229], v[26:29]
	v_mfma_f32_16x16x32_bf16 v[26:29], v[218:221], v[114:117], v[42:45]
	v_mfma_f32_16x16x32_bf16 v[114:117], v[222:225], v[226:229], v[26:29]
	v_mfma_f32_16x16x32_bf16 v[26:29], v[198:201], v[230:233], v[46:49]
	v_mfma_f32_16x16x32_bf16 v[102:105], v[202:205], v[234:237], v[26:29]
	v_mfma_f32_16x16x32_bf16 v[26:29], v[218:221], v[230:233], v[50:53]
	v_mfma_f32_16x16x32_bf16 v[98:101], v[222:225], v[234:237], v[26:29]
	v_mfma_f32_16x16x32_bf16 v[26:29], v[198:201], v[238:241], v[54:57]
	v_mfma_f32_16x16x32_bf16 v[86:89], v[202:205], v[242:245], v[26:29]
	v_mfma_f32_16x16x32_bf16 v[26:29], v[218:221], v[238:241], v[58:61]
	v_mfma_f32_16x16x32_bf16 v[134:137], v[202:205], v[30:33], v[66:69]
	v_mfma_f32_16x16x32_bf16 v[82:85], v[222:225], v[242:245], v[26:29]
	s_setprio 0
	s_barrier
	ds_read_b128 v[34:37], v213 offset:49152
	ds_read_b128 v[38:41], v213 offset:50176
	ds_read_b128 v[50:53], v213 offset:51200
	ds_read_b128 v[54:57], v213 offset:52224
	ds_read_b128 v[58:61], v213 offset:53248
	ds_read_b128 v[226:229], v213 offset:54272
	ds_read_b128 v[230:233], v213 offset:55296
	ds_read_b128 v[234:237], v213 offset:56320
	s_add_u32 s38, s0, 0x180
	s_addc_u32 s39, s1, 0
	s_mov_b32 s42, m0
	s_mov_b32 m0, s52
	s_nop 0
	global_load_lds_dwordx4 v206, s[38:39]
	s_mov_b32 m0, s42
	s_nop 0
	s_mov_b32 s42, m0
	s_mov_b32 m0, s53
	s_nop 0
	global_load_lds_dwordx4 v208, s[38:39]
	s_mov_b32 m0, s42
	s_add_u32 s38, s0, 0x40180
	s_addc_u32 s39, s1, 0
	s_mov_b32 s42, m0
	s_mov_b32 m0, s56
	s_nop 0
	global_load_lds_dwordx4 v206, s[38:39]
	s_mov_b32 m0, s42
	s_nop 0
	s_mov_b32 s42, m0
	s_mov_b32 m0, s57
	s_nop 0
	global_load_lds_dwordx4 v208, s[38:39]
	s_mov_b32 m0, s42
	s_mov_b32 s38, m0
	s_mov_b32 m0, s54
	s_nop 0
	global_load_lds_dwordx4 v1, s[40:41]
	s_mov_b32 m0, s38
	s_nop 0
	s_mov_b32 s38, m0
	s_mov_b32 m0, s55
	s_nop 0
	global_load_lds_dwordx4 v207, s[40:41]
	s_mov_b32 m0, s38
	s_waitcnt vmcnt(8)
	s_waitcnt lgkmcnt(0)
	s_barrier
	s_setprio 1
	s_waitcnt lgkmcnt(7)
	v_mfma_f32_16x16x32_bf16 v[26:29], v[10:13], v[34:37], v[146:149]
	s_waitcnt lgkmcnt(6)
	v_mfma_f32_16x16x32_bf16 v[78:81], v[14:17], v[38:41], v[26:29]
	v_mfma_f32_16x16x32_bf16 v[26:29], v[18:21], v[34:37], v[150:153]
	v_mfma_f32_16x16x32_bf16 v[74:77], v[22:25], v[38:41], v[26:29]
	s_waitcnt lgkmcnt(5)
	v_mfma_f32_16x16x32_bf16 v[26:29], v[10:13], v[50:53], v[154:157]
	s_waitcnt lgkmcnt(4)
	v_mfma_f32_16x16x32_bf16 v[46:49], v[14:17], v[54:57], v[26:29]
	v_mfma_f32_16x16x32_bf16 v[26:29], v[18:21], v[50:53], v[158:161]
	v_mfma_f32_16x16x32_bf16 v[42:45], v[22:25], v[54:57], v[26:29]
	s_waitcnt lgkmcnt(3)
	v_mfma_f32_16x16x32_bf16 v[26:29], v[10:13], v[58:61], v[162:165]
	s_waitcnt lgkmcnt(1)
	v_mfma_f32_16x16x32_bf16 v[2:5], v[10:13], v[230:233], v[2:5]
	v_mfma_f32_16x16x32_bf16 v[30:33], v[14:17], v[226:229], v[26:29]
	v_mfma_f32_16x16x32_bf16 v[26:29], v[18:21], v[58:61], v[166:169]
	s_waitcnt lgkmcnt(0)
	v_mfma_f32_16x16x32_bf16 v[14:17], v[14:17], v[234:237], v[2:5]
	v_mfma_f32_16x16x32_bf16 v[2:5], v[18:21], v[230:233], v[6:9]
	v_mfma_f32_16x16x32_bf16 v[26:29], v[22:25], v[226:229], v[26:29]
	v_mfma_f32_16x16x32_bf16 v[10:13], v[22:25], v[234:237], v[2:5]
	s_setprio 0
	s_setprio 1
	v_mfma_f32_16x16x32_bf16 v[2:5], v[198:201], v[34:37], v[170:173]
	v_mfma_f32_16x16x32_bf16 v[70:73], v[202:205], v[38:41], v[2:5]
	v_mfma_f32_16x16x32_bf16 v[2:5], v[218:221], v[34:37], v[62:65]
	v_mfma_f32_16x16x32_bf16 v[66:69], v[222:225], v[38:41], v[2:5]
	v_mfma_f32_16x16x32_bf16 v[2:5], v[198:201], v[50:53], v[174:177]
	v_mfma_f32_16x16x32_bf16 v[38:41], v[202:205], v[54:57], v[2:5]
	v_mfma_f32_16x16x32_bf16 v[2:5], v[218:221], v[50:53], v[178:181]
	v_mfma_f32_16x16x32_bf16 v[34:37], v[222:225], v[54:57], v[2:5]
	v_mfma_f32_16x16x32_bf16 v[2:5], v[198:201], v[58:61], v[182:185]
	v_mfma_f32_16x16x32_bf16 v[22:25], v[202:205], v[226:229], v[2:5]
	v_mfma_f32_16x16x32_bf16 v[2:5], v[218:221], v[58:61], v[186:189]
	v_mfma_f32_16x16x32_bf16 v[18:21], v[222:225], v[226:229], v[2:5]
	v_mfma_f32_16x16x32_bf16 v[2:5], v[198:201], v[230:233], v[190:193]
	v_mfma_f32_16x16x32_bf16 v[6:9], v[202:205], v[234:237], v[2:5]
	v_mfma_f32_16x16x32_bf16 v[2:5], v[218:221], v[230:233], v[194:197]
	v_mfma_f32_16x16x32_bf16 v[2:5], v[222:225], v[234:237], v[2:5]
	s_setprio 0
	s_add_u32 s62, s0, 0x200
	s_addc_u32 s63, s1, 0
	s_mov_b32 s64, 0
.LBB0_1152:
	s_barrier
	ds_read_b128 v[50:53], v211
	ds_read_b128 v[54:57], v211 offset:1024
	ds_read_b128 v[58:61], v211 offset:2048
	ds_read_b128 v[62:65], v211 offset:3072
	ds_read_b128 v[146:149], v212
	ds_read_b128 v[150:153], v212 offset:1024
	ds_read_b128 v[154:157], v212 offset:2048
	ds_read_b128 v[158:161], v212 offset:3072
	s_add_u32 s0, s36, 0x100
	s_addc_u32 s1, s37, 0
	s_cmp_eq_u32 s64, 12
	s_cselect_b32 s42, s19, s0
	s_cselect_b32 s43, s17, s1
	s_cselect_b32 s40, s61, s62
	s_cselect_b32 s41, s29, s63
	s_add_u32 s38, s42, 0x80
	s_addc_u32 s39, s43, 0
	ds_read_b128 v[162:165], v213
	ds_read_b128 v[166:169], v213 offset:1024
	ds_read_b128 v[170:173], v213 offset:2048
	ds_read_b128 v[174:177], v213 offset:3072
	ds_read_b128 v[178:181], v213 offset:4096
	ds_read_b128 v[182:185], v213 offset:5120
	ds_read_b128 v[186:189], v213 offset:6144
	ds_read_b128 v[190:193], v213 offset:7168
	s_add_u32 s36, s36, 0x40080
	s_addc_u32 s37, s37, 0
	s_mov_b32 s65, m0
	s_mov_b32 m0, s58
	s_nop 0
	global_load_lds_dwordx4 v1, s[36:37]
	s_mov_b32 m0, s65
	s_nop 0
	s_mov_b32 s65, m0
	s_mov_b32 m0, s59
	s_nop 0
	global_load_lds_dwordx4 v207, s[36:37]
	s_mov_b32 m0, s65
	s_waitcnt vmcnt(8)
	s_waitcnt lgkmcnt(0)
	s_barrier
	s_setprio 1
	s_waitcnt lgkmcnt(7)
	v_mfma_f32_16x16x32_bf16 v[142:145], v[50:53], v[162:165], v[142:145]
	v_mfma_f32_16x16x32_bf16 v[138:141], v[58:61], v[162:165], v[138:141]
	s_waitcnt lgkmcnt(5)
	v_mfma_f32_16x16x32_bf16 v[126:129], v[50:53], v[170:173], v[126:129]
	v_mfma_f32_16x16x32_bf16 v[122:125], v[58:61], v[170:173], v[122:125]
	s_waitcnt lgkmcnt(3)
	v_mfma_f32_16x16x32_bf16 v[110:113], v[50:53], v[178:181], v[110:113]
	v_mfma_f32_16x16x32_bf16 v[106:109], v[58:61], v[178:181], v[106:109]
	s_waitcnt lgkmcnt(1)
	v_mfma_f32_16x16x32_bf16 v[94:97], v[50:53], v[186:189], v[94:97]
	v_mfma_f32_16x16x32_bf16 v[90:93], v[58:61], v[186:189], v[90:93]
	v_mfma_f32_16x16x32_bf16 v[142:145], v[54:57], v[166:169], v[142:145]
	v_mfma_f32_16x16x32_bf16 v[138:141], v[62:65], v[166:169], v[138:141]
	v_mfma_f32_16x16x32_bf16 v[126:129], v[54:57], v[174:177], v[126:129]
	v_mfma_f32_16x16x32_bf16 v[122:125], v[62:65], v[174:177], v[122:125]
	v_mfma_f32_16x16x32_bf16 v[110:113], v[54:57], v[182:185], v[110:113]
	v_mfma_f32_16x16x32_bf16 v[106:109], v[62:65], v[182:185], v[106:109]
	s_waitcnt lgkmcnt(0)
	v_mfma_f32_16x16x32_bf16 v[94:97], v[54:57], v[190:193], v[94:97]
	v_mfma_f32_16x16x32_bf16 v[90:93], v[62:65], v[190:193], v[90:93]
	s_setprio 0
	s_setprio 1
	v_mfma_f32_16x16x32_bf16 v[134:137], v[146:149], v[162:165], v[134:137]
	v_mfma_f32_16x16x32_bf16 v[130:133], v[154:157], v[162:165], v[130:133]
	v_mfma_f32_16x16x32_bf16 v[118:121], v[146:149], v[170:173], v[118:121]
	v_mfma_f32_16x16x32_bf16 v[114:117], v[154:157], v[170:173], v[114:117]
	v_mfma_f32_16x16x32_bf16 v[102:105], v[146:149], v[178:181], v[102:105]
	v_mfma_f32_16x16x32_bf16 v[98:101], v[154:157], v[178:181], v[98:101]
	v_mfma_f32_16x16x32_bf16 v[86:89], v[146:149], v[186:189], v[86:89]
	v_mfma_f32_16x16x32_bf16 v[82:85], v[154:157], v[186:189], v[82:85]
	v_mfma_f32_16x16x32_bf16 v[134:137], v[150:153], v[166:169], v[134:137]
	v_mfma_f32_16x16x32_bf16 v[130:133], v[158:161], v[166:169], v[130:133]
	v_mfma_f32_16x16x32_bf16 v[118:121], v[150:153], v[174:177], v[118:121]
	v_mfma_f32_16x16x32_bf16 v[114:117], v[158:161], v[174:177], v[114:117]
	v_mfma_f32_16x16x32_bf16 v[102:105], v[150:153], v[182:185], v[102:105]
	v_mfma_f32_16x16x32_bf16 v[98:101], v[158:161], v[182:185], v[98:101]
	v_mfma_f32_16x16x32_bf16 v[86:89], v[150:153], v[190:193], v[86:89]
	v_mfma_f32_16x16x32_bf16 v[82:85], v[158:161], v[190:193], v[82:85]
	s_setprio 0
	s_barrier
	ds_read_b128 v[162:165], v213 offset:16384
	ds_read_b128 v[166:169], v213 offset:17408
	ds_read_b128 v[170:173], v213 offset:18432
	ds_read_b128 v[174:177], v213 offset:19456
	ds_read_b128 v[178:181], v213 offset:20480
	ds_read_b128 v[182:185], v213 offset:21504
	ds_read_b128 v[186:189], v213 offset:22528
	ds_read_b128 v[190:193], v213 offset:23552
	s_mov_b32 s36, m0
	s_mov_b32 m0, s34
	s_nop 0
	global_load_lds_dwordx4 v206, s[40:41]
	s_mov_b32 m0, s36
	s_nop 0
	s_mov_b32 s36, m0
	s_mov_b32 m0, s35
	s_nop 0
	global_load_lds_dwordx4 v208, s[40:41]
	s_mov_b32 m0, s36
	s_add_u32 s36, s40, 0x40000
	s_addc_u32 s37, s41, 0
	s_mov_b32 s65, m0
	s_mov_b32 m0, s44
	s_nop 0
	global_load_lds_dwordx4 v206, s[36:37]
	s_mov_b32 m0, s65
	s_nop 0
	s_mov_b32 s65, m0
	s_mov_b32 m0, s45
	s_nop 0
	global_load_lds_dwordx4 v208, s[36:37]
	s_mov_b32 m0, s65
	s_mov_b32 s36, m0
	s_mov_b32 m0, s33
	s_nop 0
	global_load_lds_dwordx4 v1, s[42:43]
	s_mov_b32 m0, s36
	s_nop 0
	s_mov_b32 s36, m0
	s_mov_b32 m0, s46
	s_nop 0
	global_load_lds_dwordx4 v207, s[42:43]
	s_mov_b32 m0, s36
	s_waitcnt vmcnt(8)
	s_waitcnt lgkmcnt(0)
	s_barrier
	s_setprio 1
	s_waitcnt lgkmcnt(7)
	v_mfma_f32_16x16x32_bf16 v[78:81], v[50:53], v[162:165], v[78:81]
	v_mfma_f32_16x16x32_bf16 v[74:77], v[58:61], v[162:165], v[74:77]
	s_waitcnt lgkmcnt(5)
	v_mfma_f32_16x16x32_bf16 v[46:49], v[50:53], v[170:173], v[46:49]
	v_mfma_f32_16x16x32_bf16 v[42:45], v[58:61], v[170:173], v[42:45]
	s_waitcnt lgkmcnt(3)
	v_mfma_f32_16x16x32_bf16 v[30:33], v[50:53], v[178:181], v[30:33]
	v_mfma_f32_16x16x32_bf16 v[26:29], v[58:61], v[178:181], v[26:29]
	s_waitcnt lgkmcnt(1)
	v_mfma_f32_16x16x32_bf16 v[14:17], v[50:53], v[186:189], v[14:17]
	v_mfma_f32_16x16x32_bf16 v[10:13], v[58:61], v[186:189], v[10:13]
	v_mfma_f32_16x16x32_bf16 v[78:81], v[54:57], v[166:169], v[78:81]
	v_mfma_f32_16x16x32_bf16 v[74:77], v[62:65], v[166:169], v[74:77]
	v_mfma_f32_16x16x32_bf16 v[46:49], v[54:57], v[174:177], v[46:49]
	v_mfma_f32_16x16x32_bf16 v[42:45], v[62:65], v[174:177], v[42:45]
	v_mfma_f32_16x16x32_bf16 v[30:33], v[54:57], v[182:185], v[30:33]
	v_mfma_f32_16x16x32_bf16 v[26:29], v[62:65], v[182:185], v[26:29]
	s_waitcnt lgkmcnt(0)
	v_mfma_f32_16x16x32_bf16 v[14:17], v[54:57], v[190:193], v[14:17]
	v_mfma_f32_16x16x32_bf16 v[10:13], v[62:65], v[190:193], v[10:13]
	s_setprio 0
	s_setprio 1
	v_mfma_f32_16x16x32_bf16 v[38:41], v[146:149], v[170:173], v[38:41]
	v_mfma_f32_16x16x32_bf16 v[34:37], v[154:157], v[170:173], v[34:37]
	v_mfma_f32_16x16x32_bf16 v[22:25], v[146:149], v[178:181], v[22:25]
	v_mfma_f32_16x16x32_bf16 v[18:21], v[154:157], v[178:181], v[18:21]
	v_mfma_f32_16x16x32_bf16 v[6:9], v[146:149], v[186:189], v[6:9]
	v_mfma_f32_16x16x32_bf16 v[2:5], v[154:157], v[186:189], v[2:5]
	v_mfma_f32_16x16x32_bf16 v[50:53], v[146:149], v[162:165], v[70:73]
	v_mfma_f32_16x16x32_bf16 v[54:57], v[154:157], v[162:165], v[66:69]
	v_mfma_f32_16x16x32_bf16 v[38:41], v[150:153], v[174:177], v[38:41]
	v_mfma_f32_16x16x32_bf16 v[34:37], v[158:161], v[174:177], v[34:37]
	v_mfma_f32_16x16x32_bf16 v[22:25], v[150:153], v[182:185], v[22:25]
	v_mfma_f32_16x16x32_bf16 v[18:21], v[158:161], v[182:185], v[18:21]
	v_mfma_f32_16x16x32_bf16 v[6:9], v[150:153], v[190:193], v[6:9]
	v_mfma_f32_16x16x32_bf16 v[2:5], v[158:161], v[190:193], v[2:5]
	v_mfma_f32_16x16x32_bf16 v[50:53], v[150:153], v[166:169], v[50:53]
	v_mfma_f32_16x16x32_bf16 v[54:57], v[158:161], v[166:169], v[54:57]
	s_setprio 0
	s_barrier
	ds_read_b128 v[58:61], v214
	ds_read_b128 v[62:65], v214 offset:1024
	ds_read_b128 v[66:69], v214 offset:2048
	ds_read_b128 v[70:73], v214 offset:3072
	ds_read_b128 v[146:149], v215
	ds_read_b128 v[150:153], v215 offset:1024
	ds_read_b128 v[154:157], v215 offset:2048
	ds_read_b128 v[158:161], v215 offset:3072
	ds_read_b128 v[162:165], v213 offset:32768
	ds_read_b128 v[166:169], v213 offset:33792
	ds_read_b128 v[170:173], v213 offset:34816
	ds_read_b128 v[174:177], v213 offset:35840
	ds_read_b128 v[178:181], v213 offset:36864
	ds_read_b128 v[182:185], v213 offset:37888
	ds_read_b128 v[186:189], v213 offset:38912
	ds_read_b128 v[190:193], v213 offset:39936
	s_add_u32 s36, s42, 0x40000
	s_addc_u32 s37, s43, 0
	s_mov_b32 s42, m0
	s_mov_b32 m0, s47
	s_nop 0
	global_load_lds_dwordx4 v1, s[36:37]
	s_mov_b32 m0, s42
	s_nop 0
	s_mov_b32 s42, m0
	s_mov_b32 m0, s48
	s_nop 0
	global_load_lds_dwordx4 v207, s[36:37]
	s_mov_b32 m0, s42
	s_waitcnt vmcnt(8)
	s_waitcnt lgkmcnt(0)
	s_barrier
	s_setprio 1
	s_waitcnt lgkmcnt(7)
	v_mfma_f32_16x16x32_bf16 v[142:145], v[58:61], v[162:165], v[142:145]
	v_mfma_f32_16x16x32_bf16 v[138:141], v[66:69], v[162:165], v[138:141]
	s_waitcnt lgkmcnt(5)
	v_mfma_f32_16x16x32_bf16 v[126:129], v[58:61], v[170:173], v[126:129]
	v_mfma_f32_16x16x32_bf16 v[122:125], v[66:69], v[170:173], v[122:125]
	s_waitcnt lgkmcnt(3)
	v_mfma_f32_16x16x32_bf16 v[110:113], v[58:61], v[178:181], v[110:113]
	v_mfma_f32_16x16x32_bf16 v[106:109], v[66:69], v[178:181], v[106:109]
	s_waitcnt lgkmcnt(1)
	v_mfma_f32_16x16x32_bf16 v[94:97], v[58:61], v[186:189], v[94:97]
	v_mfma_f32_16x16x32_bf16 v[90:93], v[66:69], v[186:189], v[90:93]
	v_mfma_f32_16x16x32_bf16 v[142:145], v[62:65], v[166:169], v[142:145]
	v_mfma_f32_16x16x32_bf16 v[138:141], v[70:73], v[166:169], v[138:141]
	v_mfma_f32_16x16x32_bf16 v[126:129], v[62:65], v[174:177], v[126:129]
	v_mfma_f32_16x16x32_bf16 v[122:125], v[70:73], v[174:177], v[122:125]
	v_mfma_f32_16x16x32_bf16 v[110:113], v[62:65], v[182:185], v[110:113]
	v_mfma_f32_16x16x32_bf16 v[106:109], v[70:73], v[182:185], v[106:109]
	s_waitcnt lgkmcnt(0)
	v_mfma_f32_16x16x32_bf16 v[94:97], v[62:65], v[190:193], v[94:97]
	v_mfma_f32_16x16x32_bf16 v[90:93], v[70:73], v[190:193], v[90:93]
	s_setprio 0
	s_setprio 1
	v_mfma_f32_16x16x32_bf16 v[134:137], v[146:149], v[162:165], v[134:137]
	v_mfma_f32_16x16x32_bf16 v[130:133], v[154:157], v[162:165], v[130:133]
	v_mfma_f32_16x16x32_bf16 v[118:121], v[146:149], v[170:173], v[118:121]
	v_mfma_f32_16x16x32_bf16 v[114:117], v[154:157], v[170:173], v[114:117]
	v_mfma_f32_16x16x32_bf16 v[102:105], v[146:149], v[178:181], v[102:105]
	v_mfma_f32_16x16x32_bf16 v[98:101], v[154:157], v[178:181], v[98:101]
	v_mfma_f32_16x16x32_bf16 v[86:89], v[146:149], v[186:189], v[86:89]
	v_mfma_f32_16x16x32_bf16 v[82:85], v[154:157], v[186:189], v[82:85]
	v_mfma_f32_16x16x32_bf16 v[134:137], v[150:153], v[166:169], v[134:137]
	v_mfma_f32_16x16x32_bf16 v[130:133], v[158:161], v[166:169], v[130:133]
	v_mfma_f32_16x16x32_bf16 v[118:121], v[150:153], v[174:177], v[118:121]
	v_mfma_f32_16x16x32_bf16 v[114:117], v[158:161], v[174:177], v[114:117]
	v_mfma_f32_16x16x32_bf16 v[102:105], v[150:153], v[182:185], v[102:105]
	v_mfma_f32_16x16x32_bf16 v[98:101], v[158:161], v[182:185], v[98:101]
	v_mfma_f32_16x16x32_bf16 v[86:89], v[150:153], v[190:193], v[86:89]
	v_mfma_f32_16x16x32_bf16 v[82:85], v[158:161], v[190:193], v[82:85]
	s_setprio 0
	s_barrier
	ds_read_b128 v[162:165], v213 offset:49152
	ds_read_b128 v[166:169], v213 offset:50176
	ds_read_b128 v[170:173], v213 offset:51200
	ds_read_b128 v[174:177], v213 offset:52224
	ds_read_b128 v[178:181], v213 offset:53248
	ds_read_b128 v[182:185], v213 offset:54272
	ds_read_b128 v[186:189], v213 offset:55296
	ds_read_b128 v[190:193], v213 offset:56320
	s_add_u32 s36, s40, 0x80
	s_addc_u32 s37, s41, 0
	s_mov_b32 s42, m0
	s_mov_b32 m0, s52
	s_nop 0
	global_load_lds_dwordx4 v206, s[36:37]
	s_mov_b32 m0, s42
	s_nop 0
	s_mov_b32 s42, m0
	s_mov_b32 m0, s53
	s_nop 0
	global_load_lds_dwordx4 v208, s[36:37]
	s_mov_b32 m0, s42
	s_add_u32 s36, s40, 0x40080
	s_addc_u32 s37, s41, 0
	s_mov_b32 s40, m0
	s_mov_b32 m0, s56
	s_nop 0
	global_load_lds_dwordx4 v206, s[36:37]
	s_mov_b32 m0, s40
	s_nop 0
	s_mov_b32 s40, m0
	s_mov_b32 m0, s57
	s_nop 0
	global_load_lds_dwordx4 v208, s[36:37]
	s_mov_b32 m0, s40
	s_mov_b32 s36, m0
	s_mov_b32 m0, s54
	s_nop 0
	global_load_lds_dwordx4 v1, s[38:39]
	s_mov_b32 m0, s36
	s_nop 0
	s_mov_b32 s36, m0
	s_mov_b32 m0, s55
	s_nop 0
	global_load_lds_dwordx4 v207, s[38:39]
	s_mov_b32 m0, s36
	s_waitcnt vmcnt(8)
	s_waitcnt lgkmcnt(0)
	s_barrier
	s_setprio 1
	s_waitcnt lgkmcnt(7)
	v_mfma_f32_16x16x32_bf16 v[78:81], v[58:61], v[162:165], v[78:81]
	v_mfma_f32_16x16x32_bf16 v[74:77], v[66:69], v[162:165], v[74:77]
	s_waitcnt lgkmcnt(5)
	v_mfma_f32_16x16x32_bf16 v[46:49], v[58:61], v[170:173], v[46:49]
	v_mfma_f32_16x16x32_bf16 v[42:45], v[66:69], v[170:173], v[42:45]
	s_waitcnt lgkmcnt(3)
	v_mfma_f32_16x16x32_bf16 v[30:33], v[58:61], v[178:181], v[30:33]
	v_mfma_f32_16x16x32_bf16 v[26:29], v[66:69], v[178:181], v[26:29]
	s_waitcnt lgkmcnt(1)
	v_mfma_f32_16x16x32_bf16 v[14:17], v[58:61], v[186:189], v[14:17]
	v_mfma_f32_16x16x32_bf16 v[10:13], v[66:69], v[186:189], v[10:13]
	v_mfma_f32_16x16x32_bf16 v[78:81], v[62:65], v[166:169], v[78:81]
	v_mfma_f32_16x16x32_bf16 v[74:77], v[70:73], v[166:169], v[74:77]
	v_mfma_f32_16x16x32_bf16 v[46:49], v[62:65], v[174:177], v[46:49]
	v_mfma_f32_16x16x32_bf16 v[42:45], v[70:73], v[174:177], v[42:45]
	v_mfma_f32_16x16x32_bf16 v[30:33], v[62:65], v[182:185], v[30:33]
	v_mfma_f32_16x16x32_bf16 v[26:29], v[70:73], v[182:185], v[26:29]
	s_waitcnt lgkmcnt(0)
	v_mfma_f32_16x16x32_bf16 v[14:17], v[62:65], v[190:193], v[14:17]
	v_mfma_f32_16x16x32_bf16 v[10:13], v[70:73], v[190:193], v[10:13]
	s_setprio 0
	s_setprio 1
	v_mfma_f32_16x16x32_bf16 v[50:53], v[146:149], v[162:165], v[50:53]
	v_mfma_f32_16x16x32_bf16 v[70:73], v[150:153], v[166:169], v[50:53]
	v_mfma_f32_16x16x32_bf16 v[50:53], v[154:157], v[162:165], v[54:57]
	v_mfma_f32_16x16x32_bf16 v[38:41], v[146:149], v[170:173], v[38:41]
	v_mfma_f32_16x16x32_bf16 v[34:37], v[154:157], v[170:173], v[34:37]
	v_mfma_f32_16x16x32_bf16 v[22:25], v[146:149], v[178:181], v[22:25]
	v_mfma_f32_16x16x32_bf16 v[18:21], v[154:157], v[178:181], v[18:21]
	v_mfma_f32_16x16x32_bf16 v[6:9], v[146:149], v[186:189], v[6:9]
	v_mfma_f32_16x16x32_bf16 v[2:5], v[154:157], v[186:189], v[2:5]
	v_mfma_f32_16x16x32_bf16 v[66:69], v[158:161], v[166:169], v[50:53]
	v_mfma_f32_16x16x32_bf16 v[38:41], v[150:153], v[174:177], v[38:41]
	v_mfma_f32_16x16x32_bf16 v[34:37], v[158:161], v[174:177], v[34:37]
	v_mfma_f32_16x16x32_bf16 v[22:25], v[150:153], v[182:185], v[22:25]
	v_mfma_f32_16x16x32_bf16 v[18:21], v[158:161], v[182:185], v[18:21]
	v_mfma_f32_16x16x32_bf16 v[6:9], v[150:153], v[190:193], v[6:9]
	v_mfma_f32_16x16x32_bf16 v[2:5], v[158:161], v[190:193], v[2:5]
	s_setprio 0
	s_add_i32 s64, s64, 2
	s_add_u32 s62, s62, 0x100
	s_addc_u32 s63, s63, 0
	s_cmp_lt_u32 s64, 14
	s_mov_b64 s[36:37], s[0:1]
	s_cbranch_scc1 .LBB0_1152
	s_barrier
	s_andn2_b64 vcc, exec, s[12:13]
	s_cbranch_vccnz .LBB0_1155
	s_barrier

.LBB0_1243:
	s_ashr_i32 s13, s12, 31
	s_lshl_b64 s[18:19], s[12:13], 19
	s_add_u32 s18, s26, s18
	s_addc_u32 s19, s27, s19
	s_ashr_i32 s15, s14, 31
	s_lshl_b64 s[20:21], s[14:15], 19
	s_add_u32 s13, s64, s20
	s_addc_u32 s15, s65, s21
	s_add_u32 s20, s13, s16
	s_addc_u32 s21, s15, s17
	s_add_u32 s30, s34, 0x100
	s_addc_u32 s31, s35, 0
	s_add_u32 s36, s34, 0x180
	ds_read_b128 v[2:5], v175
	ds_read_b128 v[6:9], v175 offset:1024
	s_waitcnt vmcnt(0)
	ds_read_b128 v[10:13], v175 offset:2048
	ds_read_b128 v[14:17], v175 offset:3072
	ds_read_b128 v[18:21], v176
	ds_read_b128 v[22:25], v176 offset:1024
	ds_read_b128 v[26:29], v176 offset:2048
	ds_read_b128 v[30:33], v176 offset:3072
	s_addc_u32 s37, s35, 0
	s_and_b64 s[38:39], s[10:11], exec
	s_cselect_b32 s13, s19, s35
	s_cselect_b32 s15, s18, s34
	s_add_u32 s38, s28, 0x100
	s_addc_u32 s39, s29, 0
	s_and_b64 s[58:59], s[10:11], exec
	s_cselect_b32 s57, s21, s29
	s_cselect_b32 s58, s20, s28
	ds_read_b128 v[34:37], v177
	ds_read_b128 v[38:41], v177 offset:1024
	ds_read_b128 v[42:45], v177 offset:2048
	ds_read_b128 v[46:49], v177 offset:3072
	ds_read_b128 v[50:53], v177 offset:4096
	ds_read_b128 v[54:57], v177 offset:5120
	ds_read_b128 v[58:61], v177 offset:6144
	ds_read_b128 v[62:65], v177 offset:7168
	s_add_u32 s60, s34, 0x40080
	s_addc_u32 s61, s35, 0
	s_mov_b32 s59, m0
	s_mov_b32 m0, s55
	s_nop 0
	global_load_lds_dwordx4 v1, s[60:61]
	s_mov_b32 m0, s59
	s_nop 0
	s_mov_b32 s59, m0
	s_mov_b32 m0, s56
	s_nop 0
	global_load_lds_dwordx4 v171, s[60:61]
	s_mov_b32 m0, s59
	s_waitcnt vmcnt(8)
	s_waitcnt lgkmcnt(0)
	s_barrier
	s_setprio 1
	s_waitcnt lgkmcnt(7)
	v_mfma_f32_16x16x32_bf16 v[66:69], v[2:5], v[34:37], 0
	v_mfma_f32_16x16x32_bf16 v[70:73], v[10:13], v[34:37], 0
	s_waitcnt lgkmcnt(5)
	v_mfma_f32_16x16x32_bf16 v[74:77], v[2:5], v[42:45], 0
	v_mfma_f32_16x16x32_bf16 v[78:81], v[10:13], v[42:45], 0
	v_mfma_f32_16x16x32_bf16 v[66:69], v[6:9], v[38:41], v[66:69]
	v_mfma_f32_16x16x32_bf16 v[70:73], v[14:17], v[38:41], v[70:73]
	s_waitcnt lgkmcnt(4)
	v_mfma_f32_16x16x32_bf16 v[74:77], v[6:9], v[46:49], v[74:77]
	v_mfma_f32_16x16x32_bf16 v[78:81], v[14:17], v[46:49], v[78:81]
	s_waitcnt lgkmcnt(3)
	v_mfma_f32_16x16x32_bf16 v[82:85], v[2:5], v[50:53], 0
	v_mfma_f32_16x16x32_bf16 v[86:89], v[10:13], v[50:53], 0
	s_waitcnt lgkmcnt(1)
	v_mfma_f32_16x16x32_bf16 v[90:93], v[2:5], v[58:61], 0
	v_mfma_f32_16x16x32_bf16 v[94:97], v[10:13], v[58:61], 0
	v_mfma_f32_16x16x32_bf16 v[82:85], v[6:9], v[54:57], v[82:85]
	v_mfma_f32_16x16x32_bf16 v[86:89], v[14:17], v[54:57], v[86:89]
	s_waitcnt lgkmcnt(0)
	v_mfma_f32_16x16x32_bf16 v[90:93], v[6:9], v[62:65], v[90:93]
	v_mfma_f32_16x16x32_bf16 v[94:97], v[14:17], v[62:65], v[94:97]
	s_setprio 0
	s_setprio 1
	v_mfma_f32_16x16x32_bf16 v[98:101], v[18:21], v[34:37], 0
	v_mfma_f32_16x16x32_bf16 v[34:37], v[26:29], v[34:37], 0
	v_mfma_f32_16x16x32_bf16 v[98:101], v[22:25], v[38:41], v[98:101]
	v_mfma_f32_16x16x32_bf16 v[34:37], v[30:33], v[38:41], v[34:37]
	v_mfma_f32_16x16x32_bf16 v[38:41], v[18:21], v[42:45], 0
	v_mfma_f32_16x16x32_bf16 v[42:45], v[26:29], v[42:45], 0
	v_mfma_f32_16x16x32_bf16 v[38:41], v[22:25], v[46:49], v[38:41]
	v_mfma_f32_16x16x32_bf16 v[42:45], v[30:33], v[46:49], v[42:45]
	v_mfma_f32_16x16x32_bf16 v[46:49], v[18:21], v[50:53], 0
	v_mfma_f32_16x16x32_bf16 v[50:53], v[26:29], v[50:53], 0
	v_mfma_f32_16x16x32_bf16 v[46:49], v[22:25], v[54:57], v[46:49]
	v_mfma_f32_16x16x32_bf16 v[50:53], v[30:33], v[54:57], v[50:53]
	v_mfma_f32_16x16x32_bf16 v[54:57], v[18:21], v[58:61], 0
	v_mfma_f32_16x16x32_bf16 v[58:61], v[26:29], v[58:61], 0
	v_mfma_f32_16x16x32_bf16 v[54:57], v[22:25], v[62:65], v[54:57]
	v_mfma_f32_16x16x32_bf16 v[58:61], v[30:33], v[62:65], v[58:61]
	s_setprio 0
	s_barrier
	ds_read_b128 v[62:65], v177 offset:16384
	ds_read_b128 v[102:105], v177 offset:17408
	ds_read_b128 v[106:109], v177 offset:18432
	ds_read_b128 v[110:113], v177 offset:19456
	ds_read_b128 v[114:117], v177 offset:20480
	ds_read_b128 v[118:121], v177 offset:21504
	ds_read_b128 v[122:125], v177 offset:22528
	ds_read_b128 v[126:129], v177 offset:23552
	s_mov_b32 s59, m0
	s_mov_b32 m0, s40
	s_nop 0
	global_load_lds_dwordx4 v170, s[38:39]
	s_mov_b32 m0, s59
	s_nop 0
	s_mov_b32 s59, m0
	s_mov_b32 m0, s41
	s_nop 0
	global_load_lds_dwordx4 v172, s[38:39]
	s_mov_b32 m0, s59
	s_add_u32 s38, s28, 0x40100
	s_addc_u32 s39, s29, 0
	s_mov_b32 s59, m0
	s_mov_b32 m0, s42
	s_nop 0
	global_load_lds_dwordx4 v170, s[38:39]
	s_mov_b32 m0, s59
	s_nop 0
	s_mov_b32 s59, m0
	s_mov_b32 m0, s43
	s_nop 0
	global_load_lds_dwordx4 v172, s[38:39]
	s_mov_b32 m0, s59
	s_mov_b32 s38, m0
	s_mov_b32 m0, s33
	s_nop 0
	global_load_lds_dwordx4 v1, s[30:31]
	s_mov_b32 m0, s38
	s_nop 0
	s_mov_b32 s38, m0
	s_mov_b32 m0, s44
	s_nop 0
	global_load_lds_dwordx4 v171, s[30:31]
	s_mov_b32 m0, s38
	s_waitcnt vmcnt(8)
	s_waitcnt lgkmcnt(0)
	s_barrier
	s_setprio 1
	s_waitcnt lgkmcnt(7)
	v_mfma_f32_16x16x32_bf16 v[130:133], v[2:5], v[62:65], 0
	s_waitcnt lgkmcnt(6)
	v_mfma_f32_16x16x32_bf16 v[134:137], v[6:9], v[102:105], v[130:133]
	v_mfma_f32_16x16x32_bf16 v[130:133], v[10:13], v[62:65], 0
	v_mfma_f32_16x16x32_bf16 v[154:157], v[14:17], v[102:105], v[130:133]
	s_waitcnt lgkmcnt(5)
	v_mfma_f32_16x16x32_bf16 v[130:133], v[2:5], v[106:109], 0
	s_waitcnt lgkmcnt(4)
	v_mfma_f32_16x16x32_bf16 v[158:161], v[6:9], v[110:113], v[130:133]
	v_mfma_f32_16x16x32_bf16 v[130:133], v[10:13], v[106:109], 0
	v_mfma_f32_16x16x32_bf16 v[162:165], v[14:17], v[110:113], v[130:133]
	s_waitcnt lgkmcnt(3)
	v_mfma_f32_16x16x32_bf16 v[130:133], v[2:5], v[114:117], 0
	s_waitcnt lgkmcnt(1)
	v_mfma_f32_16x16x32_bf16 v[2:5], v[2:5], v[122:125], 0
	v_mfma_f32_16x16x32_bf16 v[166:169], v[6:9], v[118:121], v[130:133]
	s_waitcnt lgkmcnt(0)
	v_mfma_f32_16x16x32_bf16 v[2:5], v[6:9], v[126:129], v[2:5]
	v_mfma_f32_16x16x32_bf16 v[6:9], v[10:13], v[122:125], 0
	v_mfma_f32_16x16x32_bf16 v[130:133], v[10:13], v[114:117], 0
	v_mfma_f32_16x16x32_bf16 v[6:9], v[14:17], v[126:129], v[6:9]
	v_mfma_f32_16x16x32_bf16 v[182:185], v[14:17], v[118:121], v[130:133]
	s_setprio 0
	s_setprio 1
	v_mfma_f32_16x16x32_bf16 v[10:13], v[18:21], v[62:65], 0
	v_mfma_f32_16x16x32_bf16 v[186:189], v[22:25], v[102:105], v[10:13]
	v_mfma_f32_16x16x32_bf16 v[10:13], v[26:29], v[62:65], 0
	v_mfma_f32_16x16x32_bf16 v[190:193], v[30:33], v[102:105], v[10:13]
	v_mfma_f32_16x16x32_bf16 v[10:13], v[18:21], v[106:109], 0
	v_mfma_f32_16x16x32_bf16 v[194:197], v[22:25], v[110:113], v[10:13]
	v_mfma_f32_16x16x32_bf16 v[10:13], v[26:29], v[106:109], 0
	v_mfma_f32_16x16x32_bf16 v[198:201], v[30:33], v[110:113], v[10:13]
	v_mfma_f32_16x16x32_bf16 v[10:13], v[18:21], v[114:117], 0
	v_mfma_f32_16x16x32_bf16 v[202:205], v[22:25], v[118:121], v[10:13]
	v_mfma_f32_16x16x32_bf16 v[10:13], v[26:29], v[114:117], 0
	v_mfma_f32_16x16x32_bf16 v[114:117], v[30:33], v[118:121], v[10:13]
	v_mfma_f32_16x16x32_bf16 v[10:13], v[18:21], v[122:125], 0
	v_mfma_f32_16x16x32_bf16 v[206:209], v[22:25], v[126:129], v[10:13]
	v_mfma_f32_16x16x32_bf16 v[10:13], v[26:29], v[122:125], 0
	v_mfma_f32_16x16x32_bf16 v[210:213], v[30:33], v[126:129], v[10:13]
	s_setprio 0
	s_barrier
	s_nop 4
	ds_read_b128 v[10:13], v178
	ds_read_b128 v[14:17], v178 offset:1024
	ds_read_b128 v[18:21], v178 offset:2048
	ds_read_b128 v[22:25], v178 offset:3072
	ds_read_b128 v[214:217], v179
	ds_read_b128 v[218:221], v179 offset:1024
	ds_read_b128 v[222:225], v179 offset:2048
	ds_read_b128 v[226:229], v179 offset:3072
	ds_read_b128 v[26:29], v177 offset:32768
	ds_read_b128 v[30:33], v177 offset:33792
	ds_read_b128 v[62:65], v177 offset:34816
	ds_read_b128 v[102:105], v177 offset:35840
	ds_read_b128 v[230:233], v177 offset:36864
	ds_read_b128 v[234:237], v177 offset:37888
	ds_read_b128 v[238:241], v177 offset:38912
	ds_read_b128 v[242:245], v177 offset:39936
	s_add_u32 s34, s34, 0x40100
	s_addc_u32 s35, s35, 0
	s_mov_b32 s38, m0
	s_mov_b32 m0, s45
	s_nop 0
	global_load_lds_dwordx4 v1, s[34:35]
	s_mov_b32 m0, s38
	s_nop 0
	s_mov_b32 s38, m0
	s_mov_b32 m0, s46
	s_nop 0
	global_load_lds_dwordx4 v171, s[34:35]
	s_mov_b32 m0, s38
	s_waitcnt vmcnt(8)
	s_waitcnt lgkmcnt(0)
	s_barrier
	s_setprio 1
	s_waitcnt lgkmcnt(7)
	v_mfma_f32_16x16x32_bf16 v[66:69], v[10:13], v[26:29], v[66:69]
	s_waitcnt lgkmcnt(6)
	v_mfma_f32_16x16x32_bf16 v[150:153], v[14:17], v[30:33], v[66:69]
	v_mfma_f32_16x16x32_bf16 v[66:69], v[18:21], v[26:29], v[70:73]
	v_mfma_f32_16x16x32_bf16 v[146:149], v[22:25], v[30:33], v[66:69]
	s_waitcnt lgkmcnt(5)
	v_mfma_f32_16x16x32_bf16 v[66:69], v[10:13], v[62:65], v[74:77]
	s_waitcnt lgkmcnt(4)
	v_mfma_f32_16x16x32_bf16 v[130:133], v[14:17], v[102:105], v[66:69]
	v_mfma_f32_16x16x32_bf16 v[66:69], v[18:21], v[62:65], v[78:81]
	v_mfma_f32_16x16x32_bf16 v[126:129], v[22:25], v[102:105], v[66:69]
	s_waitcnt lgkmcnt(3)
	v_mfma_f32_16x16x32_bf16 v[66:69], v[10:13], v[230:233], v[82:85]
	s_waitcnt lgkmcnt(2)
	v_mfma_f32_16x16x32_bf16 v[110:113], v[14:17], v[234:237], v[66:69]
	v_mfma_f32_16x16x32_bf16 v[66:69], v[18:21], v[230:233], v[86:89]
	v_mfma_f32_16x16x32_bf16 v[106:109], v[22:25], v[234:237], v[66:69]
	s_waitcnt lgkmcnt(1)
	v_mfma_f32_16x16x32_bf16 v[66:69], v[10:13], v[238:241], v[90:93]
	s_waitcnt lgkmcnt(0)
	v_mfma_f32_16x16x32_bf16 v[78:81], v[14:17], v[242:245], v[66:69]
	v_mfma_f32_16x16x32_bf16 v[66:69], v[18:21], v[238:241], v[94:97]
	v_mfma_f32_16x16x32_bf16 v[74:77], v[22:25], v[242:245], v[66:69]
	s_setprio 0
	s_setprio 1
	v_mfma_f32_16x16x32_bf16 v[66:69], v[214:217], v[26:29], v[98:101]
	v_mfma_f32_16x16x32_bf16 v[26:29], v[222:225], v[26:29], v[34:37]
	v_mfma_f32_16x16x32_bf16 v[138:141], v[226:229], v[30:33], v[26:29]
	v_mfma_f32_16x16x32_bf16 v[26:29], v[214:217], v[62:65], v[38:41]
	v_mfma_f32_16x16x32_bf16 v[122:125], v[218:221], v[102:105], v[26:29]
	v_mfma_f32_16x16x32_bf16 v[26:29], v[222:225], v[62:65], v[42:45]
	v_mfma_f32_16x16x32_bf16 v[118:121], v[226:229], v[102:105], v[26:29]
	v_mfma_f32_16x16x32_bf16 v[26:29], v[214:217], v[230:233], v[46:49]
	v_mfma_f32_16x16x32_bf16 v[102:105], v[218:221], v[234:237], v[26:29]
	v_mfma_f32_16x16x32_bf16 v[26:29], v[222:225], v[230:233], v[50:53]
	v_mfma_f32_16x16x32_bf16 v[98:101], v[226:229], v[234:237], v[26:29]
	v_mfma_f32_16x16x32_bf16 v[26:29], v[214:217], v[238:241], v[54:57]
	v_mfma_f32_16x16x32_bf16 v[70:73], v[218:221], v[242:245], v[26:29]
	v_mfma_f32_16x16x32_bf16 v[26:29], v[222:225], v[238:241], v[58:61]
	v_mfma_f32_16x16x32_bf16 v[142:145], v[218:221], v[30:33], v[66:69]
	v_mfma_f32_16x16x32_bf16 v[66:69], v[226:229], v[242:245], v[26:29]
	s_setprio 0
	s_barrier
	ds_read_b128 v[34:37], v177 offset:49152
	ds_read_b128 v[38:41], v177 offset:50176
	ds_read_b128 v[82:85], v177 offset:51200
	ds_read_b128 v[86:89], v177 offset:52224
	ds_read_b128 v[90:93], v177 offset:53248
	ds_read_b128 v[94:97], v177 offset:54272
	ds_read_b128 v[230:233], v177 offset:55296
	ds_read_b128 v[234:237], v177 offset:56320
	s_add_u32 s34, s28, 0x180
	s_addc_u32 s35, s29, 0
	s_mov_b32 s38, m0
	s_mov_b32 m0, s49
	s_nop 0
	global_load_lds_dwordx4 v170, s[34:35]
	s_mov_b32 m0, s38
	s_nop 0
	s_mov_b32 s38, m0
	s_mov_b32 m0, s50
	s_nop 0
	global_load_lds_dwordx4 v172, s[34:35]
	s_mov_b32 m0, s38
	s_add_u32 s34, s28, 0x40180
	s_addc_u32 s35, s29, 0
	s_mov_b32 s38, m0
	s_mov_b32 m0, s53
	s_nop 0
	global_load_lds_dwordx4 v170, s[34:35]
	s_mov_b32 m0, s38
	s_nop 0
	s_mov_b32 s38, m0
	s_mov_b32 m0, s54
	s_nop 0
	global_load_lds_dwordx4 v172, s[34:35]
	s_mov_b32 m0, s38
	s_mov_b32 s34, m0
	s_mov_b32 m0, s51
	s_nop 0
	global_load_lds_dwordx4 v1, s[36:37]
	s_mov_b32 m0, s34
	s_nop 0
	s_mov_b32 s34, m0
	s_mov_b32 m0, s52
	s_nop 0
	global_load_lds_dwordx4 v171, s[36:37]
	s_mov_b32 m0, s34
	s_waitcnt vmcnt(8)
	s_waitcnt lgkmcnt(0)
	s_barrier
	s_setprio 1
	s_waitcnt lgkmcnt(7)
	v_mfma_f32_16x16x32_bf16 v[26:29], v[10:13], v[34:37], v[134:137]
	s_waitcnt lgkmcnt(6)
	v_mfma_f32_16x16x32_bf16 v[62:65], v[14:17], v[38:41], v[26:29]
	v_mfma_f32_16x16x32_bf16 v[26:29], v[18:21], v[34:37], v[154:157]
	v_mfma_f32_16x16x32_bf16 v[58:61], v[22:25], v[38:41], v[26:29]
	s_waitcnt lgkmcnt(5)
	v_mfma_f32_16x16x32_bf16 v[26:29], v[10:13], v[82:85], v[158:161]
	s_waitcnt lgkmcnt(4)
	v_mfma_f32_16x16x32_bf16 v[46:49], v[14:17], v[86:89], v[26:29]
	v_mfma_f32_16x16x32_bf16 v[26:29], v[18:21], v[82:85], v[162:165]
	v_mfma_f32_16x16x32_bf16 v[42:45], v[22:25], v[86:89], v[26:29]
	s_waitcnt lgkmcnt(3)
	v_mfma_f32_16x16x32_bf16 v[26:29], v[10:13], v[90:93], v[166:169]
	s_waitcnt lgkmcnt(1)
	v_mfma_f32_16x16x32_bf16 v[2:5], v[10:13], v[230:233], v[2:5]
	v_mfma_f32_16x16x32_bf16 v[30:33], v[14:17], v[94:97], v[26:29]
	v_mfma_f32_16x16x32_bf16 v[26:29], v[18:21], v[90:93], v[182:185]
	s_waitcnt lgkmcnt(0)
	v_mfma_f32_16x16x32_bf16 v[14:17], v[14:17], v[234:237], v[2:5]
	v_mfma_f32_16x16x32_bf16 v[2:5], v[18:21], v[230:233], v[6:9]
	v_mfma_f32_16x16x32_bf16 v[26:29], v[22:25], v[94:97], v[26:29]
	v_mfma_f32_16x16x32_bf16 v[10:13], v[22:25], v[234:237], v[2:5]
	s_setprio 0
	s_setprio 1
	v_mfma_f32_16x16x32_bf16 v[2:5], v[214:217], v[34:37], v[186:189]
	v_mfma_f32_16x16x32_bf16 v[54:57], v[218:221], v[38:41], v[2:5]
	v_mfma_f32_16x16x32_bf16 v[2:5], v[222:225], v[34:37], v[190:193]
	v_mfma_f32_16x16x32_bf16 v[50:53], v[226:229], v[38:41], v[2:5]
	v_mfma_f32_16x16x32_bf16 v[2:5], v[214:217], v[82:85], v[194:197]
	v_mfma_f32_16x16x32_bf16 v[38:41], v[218:221], v[86:89], v[2:5]
	v_mfma_f32_16x16x32_bf16 v[2:5], v[222:225], v[82:85], v[198:201]
	v_mfma_f32_16x16x32_bf16 v[34:37], v[226:229], v[86:89], v[2:5]
	v_mfma_f32_16x16x32_bf16 v[2:5], v[214:217], v[90:93], v[202:205]
	v_mfma_f32_16x16x32_bf16 v[22:25], v[218:221], v[94:97], v[2:5]
	v_mfma_f32_16x16x32_bf16 v[2:5], v[222:225], v[90:93], v[114:117]
	v_mfma_f32_16x16x32_bf16 v[18:21], v[226:229], v[94:97], v[2:5]
	v_mfma_f32_16x16x32_bf16 v[2:5], v[214:217], v[230:233], v[206:209]
	v_mfma_f32_16x16x32_bf16 v[6:9], v[218:221], v[234:237], v[2:5]
	v_mfma_f32_16x16x32_bf16 v[2:5], v[222:225], v[230:233], v[210:213]
	v_mfma_f32_16x16x32_bf16 v[2:5], v[226:229], v[234:237], v[2:5]
	s_setprio 0
	s_add_u32 s59, s28, 0x200
	s_addc_u32 s60, s29, 0
	s_mov_b32 s61, 0
.LBB0_1244:
	s_barrier
	ds_read_b128 v[82:85], v175
	ds_read_b128 v[86:89], v175 offset:1024
	ds_read_b128 v[90:93], v175 offset:2048
	ds_read_b128 v[94:97], v175 offset:3072
	ds_read_b128 v[114:117], v176
	ds_read_b128 v[134:137], v176 offset:1024
	ds_read_b128 v[154:157], v176 offset:2048
	ds_read_b128 v[158:161], v176 offset:3072
	s_add_u32 s28, s30, 0x100
	s_addc_u32 s29, s31, 0
	s_cmp_eq_u32 s61, 12
	s_cselect_b32 s38, s15, s28
	s_cselect_b32 s39, s13, s29
	s_cselect_b32 s36, s58, s59
	s_cselect_b32 s37, s57, s60
	s_add_u32 s34, s38, 0x80
	s_addc_u32 s35, s39, 0
	ds_read_b128 v[162:165], v177
	ds_read_b128 v[166:169], v177 offset:1024
	ds_read_b128 v[182:185], v177 offset:2048
	ds_read_b128 v[186:189], v177 offset:3072
	ds_read_b128 v[190:193], v177 offset:4096
	ds_read_b128 v[194:197], v177 offset:5120
	ds_read_b128 v[198:201], v177 offset:6144
	ds_read_b128 v[202:205], v177 offset:7168
	s_add_u32 s30, s30, 0x40080
	s_addc_u32 s31, s31, 0
	s_mov_b32 s62, m0
	s_mov_b32 m0, s55
	s_nop 0
	global_load_lds_dwordx4 v1, s[30:31]
	s_mov_b32 m0, s62
	s_nop 0
	s_mov_b32 s62, m0
	s_mov_b32 m0, s56
	s_nop 0
	global_load_lds_dwordx4 v171, s[30:31]
	s_mov_b32 m0, s62
	s_waitcnt vmcnt(8)
	s_waitcnt lgkmcnt(0)
	s_barrier
	s_setprio 1
	s_waitcnt lgkmcnt(7)
	v_mfma_f32_16x16x32_bf16 v[150:153], v[82:85], v[162:165], v[150:153]
	v_mfma_f32_16x16x32_bf16 v[146:149], v[90:93], v[162:165], v[146:149]
	s_waitcnt lgkmcnt(5)
	v_mfma_f32_16x16x32_bf16 v[130:133], v[82:85], v[182:185], v[130:133]
	v_mfma_f32_16x16x32_bf16 v[126:129], v[90:93], v[182:185], v[126:129]
	s_waitcnt lgkmcnt(3)
	v_mfma_f32_16x16x32_bf16 v[110:113], v[82:85], v[190:193], v[110:113]
	v_mfma_f32_16x16x32_bf16 v[106:109], v[90:93], v[190:193], v[106:109]
	s_waitcnt lgkmcnt(1)
	v_mfma_f32_16x16x32_bf16 v[78:81], v[82:85], v[198:201], v[78:81]
	v_mfma_f32_16x16x32_bf16 v[74:77], v[90:93], v[198:201], v[74:77]
	v_mfma_f32_16x16x32_bf16 v[150:153], v[86:89], v[166:169], v[150:153]
	v_mfma_f32_16x16x32_bf16 v[146:149], v[94:97], v[166:169], v[146:149]
	v_mfma_f32_16x16x32_bf16 v[130:133], v[86:89], v[186:189], v[130:133]
	v_mfma_f32_16x16x32_bf16 v[126:129], v[94:97], v[186:189], v[126:129]
	v_mfma_f32_16x16x32_bf16 v[110:113], v[86:89], v[194:197], v[110:113]
	v_mfma_f32_16x16x32_bf16 v[106:109], v[94:97], v[194:197], v[106:109]
	s_waitcnt lgkmcnt(0)
	v_mfma_f32_16x16x32_bf16 v[78:81], v[86:89], v[202:205], v[78:81]
	v_mfma_f32_16x16x32_bf16 v[74:77], v[94:97], v[202:205], v[74:77]
	s_setprio 0
	s_setprio 1
	v_mfma_f32_16x16x32_bf16 v[142:145], v[114:117], v[162:165], v[142:145]
	v_mfma_f32_16x16x32_bf16 v[138:141], v[154:157], v[162:165], v[138:141]
	v_mfma_f32_16x16x32_bf16 v[122:125], v[114:117], v[182:185], v[122:125]
	v_mfma_f32_16x16x32_bf16 v[118:121], v[154:157], v[182:185], v[118:121]
	v_mfma_f32_16x16x32_bf16 v[102:105], v[114:117], v[190:193], v[102:105]
	v_mfma_f32_16x16x32_bf16 v[98:101], v[154:157], v[190:193], v[98:101]
	v_mfma_f32_16x16x32_bf16 v[70:73], v[114:117], v[198:201], v[70:73]
	v_mfma_f32_16x16x32_bf16 v[66:69], v[154:157], v[198:201], v[66:69]
	v_mfma_f32_16x16x32_bf16 v[142:145], v[134:137], v[166:169], v[142:145]
	v_mfma_f32_16x16x32_bf16 v[138:141], v[158:161], v[166:169], v[138:141]
	v_mfma_f32_16x16x32_bf16 v[122:125], v[134:137], v[186:189], v[122:125]
	v_mfma_f32_16x16x32_bf16 v[118:121], v[158:161], v[186:189], v[118:121]
	v_mfma_f32_16x16x32_bf16 v[102:105], v[134:137], v[194:197], v[102:105]
	v_mfma_f32_16x16x32_bf16 v[98:101], v[158:161], v[194:197], v[98:101]
	v_mfma_f32_16x16x32_bf16 v[70:73], v[134:137], v[202:205], v[70:73]
	v_mfma_f32_16x16x32_bf16 v[66:69], v[158:161], v[202:205], v[66:69]
	s_setprio 0
	s_barrier
	ds_read_b128 v[162:165], v177 offset:16384
	ds_read_b128 v[166:169], v177 offset:17408
	ds_read_b128 v[182:185], v177 offset:18432
	ds_read_b128 v[186:189], v177 offset:19456
	ds_read_b128 v[190:193], v177 offset:20480
	ds_read_b128 v[194:197], v177 offset:21504
	ds_read_b128 v[198:201], v177 offset:22528
	ds_read_b128 v[202:205], v177 offset:23552
	s_mov_b32 s30, m0
	s_mov_b32 m0, s40
	s_nop 0
	global_load_lds_dwordx4 v170, s[36:37]
	s_mov_b32 m0, s30
	s_nop 0
	s_mov_b32 s30, m0
	s_mov_b32 m0, s41
	s_nop 0
	global_load_lds_dwordx4 v172, s[36:37]
	s_mov_b32 m0, s30
	s_add_u32 s30, s36, 0x40000
	s_addc_u32 s31, s37, 0
	s_mov_b32 s62, m0
	s_mov_b32 m0, s42
	s_nop 0
	global_load_lds_dwordx4 v170, s[30:31]
	s_mov_b32 m0, s62
	s_nop 0
	s_mov_b32 s62, m0
	s_mov_b32 m0, s43
	s_nop 0
	global_load_lds_dwordx4 v172, s[30:31]
	s_mov_b32 m0, s62
	s_mov_b32 s30, m0
	s_mov_b32 m0, s33
	s_nop 0
	global_load_lds_dwordx4 v1, s[38:39]
	s_mov_b32 m0, s30
	s_nop 0
	s_mov_b32 s30, m0
	s_mov_b32 m0, s44
	s_nop 0
	global_load_lds_dwordx4 v171, s[38:39]
	s_mov_b32 m0, s30
	s_waitcnt vmcnt(8)
	s_waitcnt lgkmcnt(0)
	s_barrier
	s_setprio 1
	s_waitcnt lgkmcnt(7)
	v_mfma_f32_16x16x32_bf16 v[62:65], v[82:85], v[162:165], v[62:65]
	v_mfma_f32_16x16x32_bf16 v[58:61], v[90:93], v[162:165], v[58:61]
	s_waitcnt lgkmcnt(5)
	v_mfma_f32_16x16x32_bf16 v[46:49], v[82:85], v[182:185], v[46:49]
	v_mfma_f32_16x16x32_bf16 v[42:45], v[90:93], v[182:185], v[42:45]
	s_waitcnt lgkmcnt(3)
	v_mfma_f32_16x16x32_bf16 v[30:33], v[82:85], v[190:193], v[30:33]
	v_mfma_f32_16x16x32_bf16 v[26:29], v[90:93], v[190:193], v[26:29]
	s_waitcnt lgkmcnt(1)
	v_mfma_f32_16x16x32_bf16 v[14:17], v[82:85], v[198:201], v[14:17]
	v_mfma_f32_16x16x32_bf16 v[10:13], v[90:93], v[198:201], v[10:13]
	v_mfma_f32_16x16x32_bf16 v[62:65], v[86:89], v[166:169], v[62:65]
	v_mfma_f32_16x16x32_bf16 v[58:61], v[94:97], v[166:169], v[58:61]
	v_mfma_f32_16x16x32_bf16 v[46:49], v[86:89], v[186:189], v[46:49]
	v_mfma_f32_16x16x32_bf16 v[42:45], v[94:97], v[186:189], v[42:45]
	v_mfma_f32_16x16x32_bf16 v[30:33], v[86:89], v[194:197], v[30:33]
	v_mfma_f32_16x16x32_bf16 v[26:29], v[94:97], v[194:197], v[26:29]
	s_waitcnt lgkmcnt(0)
	v_mfma_f32_16x16x32_bf16 v[14:17], v[86:89], v[202:205], v[14:17]
	v_mfma_f32_16x16x32_bf16 v[10:13], v[94:97], v[202:205], v[10:13]
	s_setprio 0
	s_setprio 1
	v_mfma_f32_16x16x32_bf16 v[54:57], v[114:117], v[162:165], v[54:57]
	v_mfma_f32_16x16x32_bf16 v[50:53], v[154:157], v[162:165], v[50:53]
	v_mfma_f32_16x16x32_bf16 v[38:41], v[114:117], v[182:185], v[38:41]
	v_mfma_f32_16x16x32_bf16 v[34:37], v[154:157], v[182:185], v[34:37]
	v_mfma_f32_16x16x32_bf16 v[22:25], v[114:117], v[190:193], v[22:25]
	v_mfma_f32_16x16x32_bf16 v[18:21], v[154:157], v[190:193], v[18:21]
	v_mfma_f32_16x16x32_bf16 v[6:9], v[114:117], v[198:201], v[6:9]
	v_mfma_f32_16x16x32_bf16 v[2:5], v[154:157], v[198:201], v[2:5]
	v_mfma_f32_16x16x32_bf16 v[54:57], v[134:137], v[166:169], v[54:57]
	v_mfma_f32_16x16x32_bf16 v[50:53], v[158:161], v[166:169], v[50:53]
	v_mfma_f32_16x16x32_bf16 v[38:41], v[134:137], v[186:189], v[38:41]
	v_mfma_f32_16x16x32_bf16 v[34:37], v[158:161], v[186:189], v[34:37]
	v_mfma_f32_16x16x32_bf16 v[22:25], v[134:137], v[194:197], v[22:25]
	v_mfma_f32_16x16x32_bf16 v[18:21], v[158:161], v[194:197], v[18:21]
	v_mfma_f32_16x16x32_bf16 v[6:9], v[134:137], v[202:205], v[6:9]
	v_mfma_f32_16x16x32_bf16 v[2:5], v[158:161], v[202:205], v[2:5]
	s_setprio 0
	s_barrier
	ds_read_b128 v[82:85], v178
	ds_read_b128 v[86:89], v178 offset:1024
	ds_read_b128 v[90:93], v178 offset:2048
	ds_read_b128 v[94:97], v178 offset:3072
	ds_read_b128 v[114:117], v179
	ds_read_b128 v[134:137], v179 offset:1024
	ds_read_b128 v[154:157], v179 offset:2048
	ds_read_b128 v[158:161], v179 offset:3072
	ds_read_b128 v[162:165], v177 offset:32768
	ds_read_b128 v[166:169], v177 offset:33792
	ds_read_b128 v[182:185], v177 offset:34816
	ds_read_b128 v[186:189], v177 offset:35840
	ds_read_b128 v[190:193], v177 offset:36864
	ds_read_b128 v[194:197], v177 offset:37888
	ds_read_b128 v[198:201], v177 offset:38912
	ds_read_b128 v[202:205], v177 offset:39936
	s_add_u32 s30, s38, 0x40000
	s_addc_u32 s31, s39, 0
	s_mov_b32 s38, m0
	s_mov_b32 m0, s45
	s_nop 0
	global_load_lds_dwordx4 v1, s[30:31]
	s_mov_b32 m0, s38
	s_nop 0
	s_mov_b32 s38, m0
	s_mov_b32 m0, s46
	s_nop 0
	global_load_lds_dwordx4 v171, s[30:31]
	s_mov_b32 m0, s38
	s_waitcnt vmcnt(8)
	s_waitcnt lgkmcnt(0)
	s_barrier
	s_setprio 1
	s_waitcnt lgkmcnt(7)
	v_mfma_f32_16x16x32_bf16 v[150:153], v[82:85], v[162:165], v[150:153]
	v_mfma_f32_16x16x32_bf16 v[146:149], v[90:93], v[162:165], v[146:149]
	s_waitcnt lgkmcnt(5)
	v_mfma_f32_16x16x32_bf16 v[130:133], v[82:85], v[182:185], v[130:133]
	v_mfma_f32_16x16x32_bf16 v[126:129], v[90:93], v[182:185], v[126:129]
	s_waitcnt lgkmcnt(3)
	v_mfma_f32_16x16x32_bf16 v[110:113], v[82:85], v[190:193], v[110:113]
	v_mfma_f32_16x16x32_bf16 v[106:109], v[90:93], v[190:193], v[106:109]
	s_waitcnt lgkmcnt(1)
	v_mfma_f32_16x16x32_bf16 v[78:81], v[82:85], v[198:201], v[78:81]
	v_mfma_f32_16x16x32_bf16 v[74:77], v[90:93], v[198:201], v[74:77]
	v_mfma_f32_16x16x32_bf16 v[150:153], v[86:89], v[166:169], v[150:153]
	v_mfma_f32_16x16x32_bf16 v[146:149], v[94:97], v[166:169], v[146:149]
	v_mfma_f32_16x16x32_bf16 v[130:133], v[86:89], v[186:189], v[130:133]
	v_mfma_f32_16x16x32_bf16 v[126:129], v[94:97], v[186:189], v[126:129]
	v_mfma_f32_16x16x32_bf16 v[110:113], v[86:89], v[194:197], v[110:113]
	v_mfma_f32_16x16x32_bf16 v[106:109], v[94:97], v[194:197], v[106:109]
	s_waitcnt lgkmcnt(0)
	v_mfma_f32_16x16x32_bf16 v[78:81], v[86:89], v[202:205], v[78:81]
	v_mfma_f32_16x16x32_bf16 v[74:77], v[94:97], v[202:205], v[74:77]
	s_setprio 0
	s_setprio 1
	v_mfma_f32_16x16x32_bf16 v[142:145], v[114:117], v[162:165], v[142:145]
	v_mfma_f32_16x16x32_bf16 v[138:141], v[154:157], v[162:165], v[138:141]
	v_mfma_f32_16x16x32_bf16 v[122:125], v[114:117], v[182:185], v[122:125]
	v_mfma_f32_16x16x32_bf16 v[118:121], v[154:157], v[182:185], v[118:121]
	v_mfma_f32_16x16x32_bf16 v[102:105], v[114:117], v[190:193], v[102:105]
	v_mfma_f32_16x16x32_bf16 v[98:101], v[154:157], v[190:193], v[98:101]
	v_mfma_f32_16x16x32_bf16 v[70:73], v[114:117], v[198:201], v[70:73]
	v_mfma_f32_16x16x32_bf16 v[66:69], v[154:157], v[198:201], v[66:69]
	v_mfma_f32_16x16x32_bf16 v[142:145], v[134:137], v[166:169], v[142:145]
	v_mfma_f32_16x16x32_bf16 v[138:141], v[158:161], v[166:169], v[138:141]
	v_mfma_f32_16x16x32_bf16 v[122:125], v[134:137], v[186:189], v[122:125]
	v_mfma_f32_16x16x32_bf16 v[118:121], v[158:161], v[186:189], v[118:121]
	v_mfma_f32_16x16x32_bf16 v[102:105], v[134:137], v[194:197], v[102:105]
	v_mfma_f32_16x16x32_bf16 v[98:101], v[158:161], v[194:197], v[98:101]
	v_mfma_f32_16x16x32_bf16 v[70:73], v[134:137], v[202:205], v[70:73]
	v_mfma_f32_16x16x32_bf16 v[66:69], v[158:161], v[202:205], v[66:69]
	s_setprio 0
	s_barrier
	ds_read_b128 v[162:165], v177 offset:49152
	ds_read_b128 v[166:169], v177 offset:50176
	ds_read_b128 v[182:185], v177 offset:51200
	ds_read_b128 v[186:189], v177 offset:52224
	ds_read_b128 v[190:193], v177 offset:53248
	ds_read_b128 v[194:197], v177 offset:54272
	ds_read_b128 v[198:201], v177 offset:55296
	ds_read_b128 v[202:205], v177 offset:56320
	s_add_u32 s30, s36, 0x80
	s_addc_u32 s31, s37, 0
	s_mov_b32 s38, m0
	s_mov_b32 m0, s49
	s_nop 0
	global_load_lds_dwordx4 v170, s[30:31]
	s_mov_b32 m0, s38
	s_nop 0
	s_mov_b32 s38, m0
	s_mov_b32 m0, s50
	s_nop 0
	global_load_lds_dwordx4 v172, s[30:31]
	s_mov_b32 m0, s38
	s_add_u32 s30, s36, 0x40080
	s_addc_u32 s31, s37, 0
	s_mov_b32 s36, m0
	s_mov_b32 m0, s53
	s_nop 0
	global_load_lds_dwordx4 v170, s[30:31]
	s_mov_b32 m0, s36
	s_nop 0
	s_mov_b32 s36, m0
	s_mov_b32 m0, s54
	s_nop 0
	global_load_lds_dwordx4 v172, s[30:31]
	s_mov_b32 m0, s36
	s_mov_b32 s30, m0
	s_mov_b32 m0, s51
	s_nop 0
	global_load_lds_dwordx4 v1, s[34:35]
	s_mov_b32 m0, s30
	s_nop 0
	s_mov_b32 s30, m0
	s_mov_b32 m0, s52
	s_nop 0
	global_load_lds_dwordx4 v171, s[34:35]
	s_mov_b32 m0, s30
	s_waitcnt vmcnt(8)
	s_waitcnt lgkmcnt(0)
	s_barrier
	s_setprio 1
	s_waitcnt lgkmcnt(7)
	v_mfma_f32_16x16x32_bf16 v[62:65], v[82:85], v[162:165], v[62:65]
	v_mfma_f32_16x16x32_bf16 v[58:61], v[90:93], v[162:165], v[58:61]
	s_waitcnt lgkmcnt(5)
	v_mfma_f32_16x16x32_bf16 v[46:49], v[82:85], v[182:185], v[46:49]
	v_mfma_f32_16x16x32_bf16 v[42:45], v[90:93], v[182:185], v[42:45]
	s_waitcnt lgkmcnt(3)
	v_mfma_f32_16x16x32_bf16 v[30:33], v[82:85], v[190:193], v[30:33]
	v_mfma_f32_16x16x32_bf16 v[26:29], v[90:93], v[190:193], v[26:29]
	s_waitcnt lgkmcnt(1)
	v_mfma_f32_16x16x32_bf16 v[14:17], v[82:85], v[198:201], v[14:17]
	v_mfma_f32_16x16x32_bf16 v[10:13], v[90:93], v[198:201], v[10:13]
	v_mfma_f32_16x16x32_bf16 v[62:65], v[86:89], v[166:169], v[62:65]
	v_mfma_f32_16x16x32_bf16 v[58:61], v[94:97], v[166:169], v[58:61]
	v_mfma_f32_16x16x32_bf16 v[46:49], v[86:89], v[186:189], v[46:49]
	v_mfma_f32_16x16x32_bf16 v[42:45], v[94:97], v[186:189], v[42:45]
	v_mfma_f32_16x16x32_bf16 v[30:33], v[86:89], v[194:197], v[30:33]
	v_mfma_f32_16x16x32_bf16 v[26:29], v[94:97], v[194:197], v[26:29]
	s_waitcnt lgkmcnt(0)
	v_mfma_f32_16x16x32_bf16 v[14:17], v[86:89], v[202:205], v[14:17]
	v_mfma_f32_16x16x32_bf16 v[10:13], v[94:97], v[202:205], v[10:13]
	s_setprio 0
	s_setprio 1
	v_mfma_f32_16x16x32_bf16 v[54:57], v[114:117], v[162:165], v[54:57]
	v_mfma_f32_16x16x32_bf16 v[50:53], v[154:157], v[162:165], v[50:53]
	v_mfma_f32_16x16x32_bf16 v[38:41], v[114:117], v[182:185], v[38:41]
	v_mfma_f32_16x16x32_bf16 v[34:37], v[154:157], v[182:185], v[34:37]
	v_mfma_f32_16x16x32_bf16 v[22:25], v[114:117], v[190:193], v[22:25]
	v_mfma_f32_16x16x32_bf16 v[18:21], v[154:157], v[190:193], v[18:21]
	v_mfma_f32_16x16x32_bf16 v[6:9], v[114:117], v[198:201], v[6:9]
	v_mfma_f32_16x16x32_bf16 v[2:5], v[154:157], v[198:201], v[2:5]
	v_mfma_f32_16x16x32_bf16 v[54:57], v[134:137], v[166:169], v[54:57]
	v_mfma_f32_16x16x32_bf16 v[50:53], v[158:161], v[166:169], v[50:53]
	v_mfma_f32_16x16x32_bf16 v[38:41], v[134:137], v[186:189], v[38:41]
	v_mfma_f32_16x16x32_bf16 v[34:37], v[158:161], v[186:189], v[34:37]
	v_mfma_f32_16x16x32_bf16 v[22:25], v[134:137], v[194:197], v[22:25]
	v_mfma_f32_16x16x32_bf16 v[18:21], v[158:161], v[194:197], v[18:21]
	v_mfma_f32_16x16x32_bf16 v[6:9], v[134:137], v[202:205], v[6:9]
	v_mfma_f32_16x16x32_bf16 v[2:5], v[158:161], v[202:205], v[2:5]
	s_setprio 0
	s_add_i32 s61, s61, 2
	s_add_u32 s59, s59, 0x100
	s_addc_u32 s60, s60, 0
	s_cmp_lt_u32 s61, 14
	s_mov_b64 s[30:31], s[28:29]
	s_cbranch_scc1 .LBB0_1244
	s_barrier
	s_andn2_b64 vcc, exec, s[8:9]
	s_cbranch_vccnz .LBB0_1247
	s_barrier

.LBB0_1322:
	s_ashr_i32 s9, s8, 31
	s_lshl_b64 s[12:13], s[8:9], 21
	s_add_u32 s12, s24, s12
	s_addc_u32 s13, s25, s13
	s_ashr_i32 s11, s10, 31
	s_lshl_b64 s[16:17], s[10:11], 21
	s_add_u32 s16, s64, s16
	s_addc_u32 s17, s65, s17
	s_add_u32 s34, s20, 0x100
	s_addc_u32 s35, s21, 0
	s_add_u32 s30, s20, 0x180
	ds_read_b128 v[0:3], v198
	ds_read_b128 v[4:7], v198 offset:1024
	s_waitcnt vmcnt(0)
	ds_read_b128 v[8:11], v198 offset:2048
	ds_read_b128 v[12:15], v198 offset:3072
	ds_read_b128 v[16:19], v199
	ds_read_b128 v[20:23], v199 offset:1024
	ds_read_b128 v[24:27], v199 offset:2048
	ds_read_b128 v[28:31], v199 offset:3072
	s_addc_u32 s31, s21, 0
	s_and_b64 s[56:57], s[14:15], exec
	s_cselect_b32 s9, s13, s21
	s_cselect_b32 s11, s12, s20
	s_add_u32 s58, s22, 0x100
	s_addc_u32 s59, s23, 0
	s_and_b64 s[56:57], s[14:15], exec
	s_cselect_b32 s55, s17, s23
	s_cselect_b32 s56, s16, s22
	ds_read_b128 v[32:35], v200
	ds_read_b128 v[36:39], v200 offset:1024
	ds_read_b128 v[40:43], v200 offset:2048
	ds_read_b128 v[44:47], v200 offset:3072
	ds_read_b128 v[48:51], v200 offset:4096
	ds_read_b128 v[52:55], v200 offset:5120
	ds_read_b128 v[56:59], v200 offset:6144
	ds_read_b128 v[60:63], v200 offset:7168
	s_add_u32 s60, s20, 0x10080
	s_addc_u32 s61, s21, 0
	s_mov_b32 s57, m0
	s_mov_b32 m0, s49
	s_nop 0
	global_load_lds_dwordx4 v192, s[60:61]
	s_mov_b32 m0, s57
	s_nop 0
	s_mov_b32 s57, m0
	s_mov_b32 m0, s50
	s_nop 0
	global_load_lds_dwordx4 v194, s[60:61]
	s_mov_b32 m0, s57
	s_waitcnt vmcnt(8)
	s_waitcnt lgkmcnt(0)
	s_barrier
	s_setprio 1
	s_waitcnt lgkmcnt(7)
	v_mfma_f32_16x16x32_bf16 v[64:67], v[0:3], v[32:35], 0
	v_mfma_f32_16x16x32_bf16 v[68:71], v[8:11], v[32:35], 0
	s_waitcnt lgkmcnt(5)
	v_mfma_f32_16x16x32_bf16 v[72:75], v[0:3], v[40:43], 0
	v_mfma_f32_16x16x32_bf16 v[76:79], v[8:11], v[40:43], 0
	s_waitcnt lgkmcnt(3)
	v_mfma_f32_16x16x32_bf16 v[80:83], v[0:3], v[48:51], 0
	v_mfma_f32_16x16x32_bf16 v[84:87], v[8:11], v[48:51], 0
	s_waitcnt lgkmcnt(1)
	v_mfma_f32_16x16x32_bf16 v[88:91], v[0:3], v[56:59], 0
	v_mfma_f32_16x16x32_bf16 v[64:67], v[4:7], v[36:39], v[64:67]
	v_mfma_f32_16x16x32_bf16 v[68:71], v[12:15], v[36:39], v[68:71]
	v_mfma_f32_16x16x32_bf16 v[72:75], v[4:7], v[44:47], v[72:75]
	v_mfma_f32_16x16x32_bf16 v[76:79], v[12:15], v[44:47], v[76:79]
	v_mfma_f32_16x16x32_bf16 v[80:83], v[4:7], v[52:55], v[80:83]
	v_mfma_f32_16x16x32_bf16 v[84:87], v[12:15], v[52:55], v[84:87]
	s_waitcnt lgkmcnt(0)
	v_mfma_f32_16x16x32_bf16 v[96:99], v[4:7], v[60:63], v[88:91]
	v_mfma_f32_16x16x32_bf16 v[88:91], v[8:11], v[56:59], 0
	v_mfma_f32_16x16x32_bf16 v[100:103], v[12:15], v[60:63], v[88:91]
	s_setprio 0
	s_setprio 1
	v_mfma_f32_16x16x32_bf16 v[88:91], v[16:19], v[32:35], 0
	v_mfma_f32_16x16x32_bf16 v[32:35], v[24:27], v[32:35], 0
	v_mfma_f32_16x16x32_bf16 v[104:107], v[20:23], v[36:39], v[88:91]
	v_mfma_f32_16x16x32_bf16 v[32:35], v[28:31], v[36:39], v[32:35]
	v_mfma_f32_16x16x32_bf16 v[36:39], v[16:19], v[40:43], 0
	v_mfma_f32_16x16x32_bf16 v[40:43], v[24:27], v[40:43], 0
	v_mfma_f32_16x16x32_bf16 v[36:39], v[20:23], v[44:47], v[36:39]
	v_mfma_f32_16x16x32_bf16 v[40:43], v[28:31], v[44:47], v[40:43]
	v_mfma_f32_16x16x32_bf16 v[44:47], v[16:19], v[48:51], 0
	v_mfma_f32_16x16x32_bf16 v[48:51], v[24:27], v[48:51], 0
	v_mfma_f32_16x16x32_bf16 v[44:47], v[20:23], v[52:55], v[44:47]
	v_mfma_f32_16x16x32_bf16 v[48:51], v[28:31], v[52:55], v[48:51]
	v_mfma_f32_16x16x32_bf16 v[52:55], v[16:19], v[56:59], 0
	v_mfma_f32_16x16x32_bf16 v[56:59], v[24:27], v[56:59], 0
	v_mfma_f32_16x16x32_bf16 v[52:55], v[20:23], v[60:63], v[52:55]
	v_mfma_f32_16x16x32_bf16 v[56:59], v[28:31], v[60:63], v[56:59]
	s_setprio 0
	s_barrier
	ds_read_b128 v[60:63], v200 offset:16384
	ds_read_b128 v[88:91], v200 offset:17408
	ds_read_b128 v[92:95], v200 offset:18432
	ds_read_b128 v[108:111], v200 offset:19456
	ds_read_b128 v[112:115], v200 offset:20480
	ds_read_b128 v[116:119], v200 offset:21504
	ds_read_b128 v[120:123], v200 offset:22528
	ds_read_b128 v[124:127], v200 offset:23552
	s_mov_b32 s57, m0
	s_mov_b32 m0, s19
	s_nop 0
	global_load_lds_dwordx4 v193, s[58:59]
	s_mov_b32 m0, s57
	s_nop 0
	s_mov_b32 s57, m0
	s_mov_b32 m0, s33
	s_nop 0
	global_load_lds_dwordx4 v195, s[58:59]
	s_mov_b32 m0, s57
	s_add_u32 s58, s22, 0x100100
	s_addc_u32 s59, s23, 0
	s_mov_b32 s57, m0
	s_mov_b32 m0, s36
	s_nop 0
	global_load_lds_dwordx4 v193, s[58:59]
	s_mov_b32 m0, s57
	s_nop 0
	s_mov_b32 s57, m0
	s_mov_b32 m0, s37
	s_nop 0
	global_load_lds_dwordx4 v195, s[58:59]
	s_mov_b32 m0, s57
	s_nop 0
	s_mov_b32 s57, m0
	s_mov_b32 m0, s3
	s_nop 0
	global_load_lds_dwordx4 v192, s[34:35]
	s_mov_b32 m0, s57
	s_nop 0
	s_mov_b32 s57, m0
	s_mov_b32 m0, s38
	s_nop 0
	global_load_lds_dwordx4 v194, s[34:35]
	s_mov_b32 m0, s57
	s_waitcnt vmcnt(8)
	s_waitcnt lgkmcnt(0)
	s_barrier
	s_setprio 1
	s_waitcnt lgkmcnt(7)
	v_mfma_f32_16x16x32_bf16 v[128:131], v[0:3], v[60:63], 0
	s_waitcnt lgkmcnt(6)
	v_mfma_f32_16x16x32_bf16 v[144:147], v[4:7], v[88:91], v[128:131]
	v_mfma_f32_16x16x32_bf16 v[128:131], v[8:11], v[60:63], 0
	v_mfma_f32_16x16x32_bf16 v[148:151], v[12:15], v[88:91], v[128:131]
	s_waitcnt lgkmcnt(5)
	v_mfma_f32_16x16x32_bf16 v[128:131], v[0:3], v[92:95], 0
	s_waitcnt lgkmcnt(4)
	v_mfma_f32_16x16x32_bf16 v[152:155], v[4:7], v[108:111], v[128:131]
	v_mfma_f32_16x16x32_bf16 v[128:131], v[8:11], v[92:95], 0
	v_mfma_f32_16x16x32_bf16 v[156:159], v[12:15], v[108:111], v[128:131]
	s_waitcnt lgkmcnt(3)
	v_mfma_f32_16x16x32_bf16 v[128:131], v[0:3], v[112:115], 0
	s_waitcnt lgkmcnt(1)
	v_mfma_f32_16x16x32_bf16 v[0:3], v[0:3], v[120:123], 0
	v_mfma_f32_16x16x32_bf16 v[160:163], v[4:7], v[116:119], v[128:131]
	s_waitcnt lgkmcnt(0)
	v_mfma_f32_16x16x32_bf16 v[0:3], v[4:7], v[124:127], v[0:3]
	v_mfma_f32_16x16x32_bf16 v[4:7], v[8:11], v[120:123], 0
	v_mfma_f32_16x16x32_bf16 v[128:131], v[8:11], v[112:115], 0
	v_mfma_f32_16x16x32_bf16 v[4:7], v[12:15], v[124:127], v[4:7]
	v_mfma_f32_16x16x32_bf16 v[164:167], v[12:15], v[116:119], v[128:131]
	s_setprio 0
	s_setprio 1
	v_mfma_f32_16x16x32_bf16 v[8:11], v[16:19], v[60:63], 0
	v_mfma_f32_16x16x32_bf16 v[168:171], v[20:23], v[88:91], v[8:11]
	v_mfma_f32_16x16x32_bf16 v[8:11], v[24:27], v[60:63], 0
	v_mfma_f32_16x16x32_bf16 v[172:175], v[28:31], v[88:91], v[8:11]
	v_mfma_f32_16x16x32_bf16 v[8:11], v[16:19], v[92:95], 0
	v_mfma_f32_16x16x32_bf16 v[176:179], v[20:23], v[108:111], v[8:11]
	v_mfma_f32_16x16x32_bf16 v[8:11], v[24:27], v[92:95], 0
	v_mfma_f32_16x16x32_bf16 v[180:183], v[28:31], v[108:111], v[8:11]
	v_mfma_f32_16x16x32_bf16 v[8:11], v[16:19], v[112:115], 0
	v_mfma_f32_16x16x32_bf16 v[184:187], v[20:23], v[116:119], v[8:11]
	v_mfma_f32_16x16x32_bf16 v[8:11], v[24:27], v[112:115], 0
	v_mfma_f32_16x16x32_bf16 v[112:115], v[28:31], v[116:119], v[8:11]
	v_mfma_f32_16x16x32_bf16 v[8:11], v[16:19], v[120:123], 0
	v_mfma_f32_16x16x32_bf16 v[188:191], v[20:23], v[124:127], v[8:11]
	v_mfma_f32_16x16x32_bf16 v[8:11], v[24:27], v[120:123], 0
	v_mfma_f32_16x16x32_bf16 v[120:123], v[28:31], v[124:127], v[8:11]
	s_setprio 0
	s_barrier
	s_nop 4
	ds_read_b128 v[8:11], v201
	ds_read_b128 v[12:15], v201 offset:1024
	ds_read_b128 v[16:19], v201 offset:2048
	ds_read_b128 v[20:23], v201 offset:3072
	ds_read_b128 v[124:127], v202
	ds_read_b128 v[204:207], v202 offset:1024
	ds_read_b128 v[208:211], v202 offset:2048
	ds_read_b128 v[212:215], v202 offset:3072
	ds_read_b128 v[24:27], v200 offset:32768
	ds_read_b128 v[28:31], v200 offset:33792
	ds_read_b128 v[60:63], v200 offset:34816
	ds_read_b128 v[216:219], v200 offset:35840
	ds_read_b128 v[220:223], v200 offset:36864
	ds_read_b128 v[224:227], v200 offset:37888
	ds_read_b128 v[228:231], v200 offset:38912
	ds_read_b128 v[232:235], v200 offset:39936
	s_add_u32 s34, s20, 0x10100
	s_addc_u32 s35, s21, 0
	s_mov_b32 s57, m0
	s_mov_b32 m0, s39
	s_nop 0
	global_load_lds_dwordx4 v192, s[34:35]
	s_mov_b32 m0, s57
	s_nop 0
	s_mov_b32 s57, m0
	s_mov_b32 m0, s40
	s_nop 0
	global_load_lds_dwordx4 v194, s[34:35]
	s_mov_b32 m0, s57
	s_waitcnt vmcnt(8)
	s_waitcnt lgkmcnt(0)
	s_barrier
	s_setprio 1
	s_waitcnt lgkmcnt(7)
	v_mfma_f32_16x16x32_bf16 v[64:67], v[8:11], v[24:27], v[64:67]
	s_waitcnt lgkmcnt(6)
	v_mfma_f32_16x16x32_bf16 v[140:143], v[12:15], v[28:31], v[64:67]
	v_mfma_f32_16x16x32_bf16 v[64:67], v[16:19], v[24:27], v[68:71]
	v_mfma_f32_16x16x32_bf16 v[136:139], v[20:23], v[28:31], v[64:67]
	s_waitcnt lgkmcnt(5)
	v_mfma_f32_16x16x32_bf16 v[64:67], v[8:11], v[60:63], v[72:75]
	s_waitcnt lgkmcnt(4)
	v_mfma_f32_16x16x32_bf16 v[116:119], v[12:15], v[216:219], v[64:67]
	v_mfma_f32_16x16x32_bf16 v[64:67], v[16:19], v[60:63], v[76:79]
	v_mfma_f32_16x16x32_bf16 v[108:111], v[20:23], v[216:219], v[64:67]
	s_waitcnt lgkmcnt(3)
	v_mfma_f32_16x16x32_bf16 v[64:67], v[8:11], v[220:223], v[80:83]
	s_waitcnt lgkmcnt(2)
	v_mfma_f32_16x16x32_bf16 v[92:95], v[12:15], v[224:227], v[64:67]
	v_mfma_f32_16x16x32_bf16 v[64:67], v[16:19], v[220:223], v[84:87]
	v_mfma_f32_16x16x32_bf16 v[88:91], v[20:23], v[224:227], v[64:67]
	s_waitcnt lgkmcnt(1)
	v_mfma_f32_16x16x32_bf16 v[64:67], v[8:11], v[228:231], v[96:99]
	s_waitcnt lgkmcnt(0)
	v_mfma_f32_16x16x32_bf16 v[76:79], v[12:15], v[232:235], v[64:67]
	v_mfma_f32_16x16x32_bf16 v[64:67], v[16:19], v[228:231], v[100:103]
	v_mfma_f32_16x16x32_bf16 v[68:71], v[20:23], v[232:235], v[64:67]
	s_setprio 0
	s_setprio 1
	v_mfma_f32_16x16x32_bf16 v[64:67], v[124:127], v[24:27], v[104:107]
	v_mfma_f32_16x16x32_bf16 v[24:27], v[208:211], v[24:27], v[32:35]
	v_mfma_f32_16x16x32_bf16 v[128:131], v[212:215], v[28:31], v[24:27]
	v_mfma_f32_16x16x32_bf16 v[24:27], v[124:127], v[60:63], v[36:39]
	v_mfma_f32_16x16x32_bf16 v[104:107], v[204:207], v[216:219], v[24:27]
	v_mfma_f32_16x16x32_bf16 v[24:27], v[208:211], v[60:63], v[40:43]
	v_mfma_f32_16x16x32_bf16 v[96:99], v[212:215], v[216:219], v[24:27]
	v_mfma_f32_16x16x32_bf16 v[24:27], v[124:127], v[220:223], v[44:47]
	v_mfma_f32_16x16x32_bf16 v[84:87], v[204:207], v[224:227], v[24:27]
	v_mfma_f32_16x16x32_bf16 v[24:27], v[208:211], v[220:223], v[48:51]
	v_mfma_f32_16x16x32_bf16 v[80:83], v[212:215], v[224:227], v[24:27]
	v_mfma_f32_16x16x32_bf16 v[24:27], v[124:127], v[228:231], v[52:55]
	v_mfma_f32_16x16x32_bf16 v[132:135], v[204:207], v[28:31], v[64:67]
	v_mfma_f32_16x16x32_bf16 v[64:67], v[204:207], v[232:235], v[24:27]
	v_mfma_f32_16x16x32_bf16 v[24:27], v[208:211], v[228:231], v[56:59]
	v_mfma_f32_16x16x32_bf16 v[52:55], v[212:215], v[232:235], v[24:27]
	s_setprio 0
	s_barrier
	ds_read_b128 v[32:35], v200 offset:49152
	ds_read_b128 v[36:39], v200 offset:50176
	ds_read_b128 v[100:103], v200 offset:51200
	ds_read_b128 v[216:219], v200 offset:52224
	ds_read_b128 v[220:223], v200 offset:53248
	ds_read_b128 v[224:227], v200 offset:54272
	ds_read_b128 v[228:231], v200 offset:55296
	ds_read_b128 v[232:235], v200 offset:56320
	s_add_u32 s34, s22, 0x180
	s_addc_u32 s35, s23, 0
	s_mov_b32 s57, m0
	s_mov_b32 m0, s43
	s_nop 0
	global_load_lds_dwordx4 v193, s[34:35]
	s_mov_b32 m0, s57
	s_nop 0
	s_mov_b32 s57, m0
	s_mov_b32 m0, s44
	s_nop 0
	global_load_lds_dwordx4 v195, s[34:35]
	s_mov_b32 m0, s57
	s_add_u32 s34, s22, 0x100180
	s_addc_u32 s35, s23, 0
	s_mov_b32 s57, m0
	s_mov_b32 m0, s47
	s_nop 0
	global_load_lds_dwordx4 v193, s[34:35]
	s_mov_b32 m0, s57
	s_nop 0
	s_mov_b32 s57, m0
	s_mov_b32 m0, s48
	s_nop 0
	global_load_lds_dwordx4 v195, s[34:35]
	s_mov_b32 m0, s57
	s_mov_b32 s34, m0
	s_mov_b32 m0, s45
	s_nop 0
	global_load_lds_dwordx4 v192, s[30:31]
	s_mov_b32 m0, s34
	s_nop 0
	s_mov_b32 s34, m0
	s_mov_b32 m0, s46
	s_nop 0
	global_load_lds_dwordx4 v194, s[30:31]
	s_mov_b32 m0, s34
	s_waitcnt vmcnt(8)
	s_waitcnt lgkmcnt(0)
	s_barrier
	s_setprio 1
	s_waitcnt lgkmcnt(7)
	v_mfma_f32_16x16x32_bf16 v[24:27], v[8:11], v[32:35], v[144:147]
	s_waitcnt lgkmcnt(6)
	v_mfma_f32_16x16x32_bf16 v[72:75], v[12:15], v[36:39], v[24:27]
	v_mfma_f32_16x16x32_bf16 v[24:27], v[16:19], v[32:35], v[148:151]
	v_mfma_f32_16x16x32_bf16 v[60:63], v[20:23], v[36:39], v[24:27]
	s_waitcnt lgkmcnt(5)
	v_mfma_f32_16x16x32_bf16 v[24:27], v[8:11], v[100:103], v[152:155]
	s_waitcnt lgkmcnt(4)
	v_mfma_f32_16x16x32_bf16 v[44:47], v[12:15], v[216:219], v[24:27]
	v_mfma_f32_16x16x32_bf16 v[24:27], v[16:19], v[100:103], v[156:159]
	v_mfma_f32_16x16x32_bf16 v[40:43], v[20:23], v[216:219], v[24:27]
	s_waitcnt lgkmcnt(3)
	v_mfma_f32_16x16x32_bf16 v[24:27], v[8:11], v[220:223], v[160:163]
	s_waitcnt lgkmcnt(1)
	v_mfma_f32_16x16x32_bf16 v[0:3], v[8:11], v[228:231], v[0:3]
	v_mfma_f32_16x16x32_bf16 v[28:31], v[12:15], v[224:227], v[24:27]
	v_mfma_f32_16x16x32_bf16 v[24:27], v[16:19], v[220:223], v[164:167]
	s_waitcnt lgkmcnt(0)
	v_mfma_f32_16x16x32_bf16 v[12:15], v[12:15], v[232:235], v[0:3]
	v_mfma_f32_16x16x32_bf16 v[0:3], v[16:19], v[228:231], v[4:7]
	v_mfma_f32_16x16x32_bf16 v[24:27], v[20:23], v[224:227], v[24:27]
	v_mfma_f32_16x16x32_bf16 v[8:11], v[20:23], v[232:235], v[0:3]
	s_setprio 0
	s_setprio 1
	v_mfma_f32_16x16x32_bf16 v[0:3], v[124:127], v[32:35], v[168:171]
	v_mfma_f32_16x16x32_bf16 v[56:59], v[204:207], v[36:39], v[0:3]
	v_mfma_f32_16x16x32_bf16 v[0:3], v[208:211], v[32:35], v[172:175]
	v_mfma_f32_16x16x32_bf16 v[48:51], v[212:215], v[36:39], v[0:3]
	v_mfma_f32_16x16x32_bf16 v[0:3], v[124:127], v[100:103], v[176:179]
	v_mfma_f32_16x16x32_bf16 v[36:39], v[204:207], v[216:219], v[0:3]
	v_mfma_f32_16x16x32_bf16 v[0:3], v[208:211], v[100:103], v[180:183]
	v_mfma_f32_16x16x32_bf16 v[32:35], v[212:215], v[216:219], v[0:3]
	v_mfma_f32_16x16x32_bf16 v[0:3], v[124:127], v[220:223], v[184:187]
	v_mfma_f32_16x16x32_bf16 v[20:23], v[204:207], v[224:227], v[0:3]
	v_mfma_f32_16x16x32_bf16 v[0:3], v[208:211], v[220:223], v[112:115]
	v_mfma_f32_16x16x32_bf16 v[16:19], v[212:215], v[224:227], v[0:3]
	v_mfma_f32_16x16x32_bf16 v[0:3], v[124:127], v[228:231], v[188:191]
	v_mfma_f32_16x16x32_bf16 v[4:7], v[204:207], v[232:235], v[0:3]
	v_mfma_f32_16x16x32_bf16 v[0:3], v[208:211], v[228:231], v[120:123]
	v_mfma_f32_16x16x32_bf16 v[0:3], v[212:215], v[232:235], v[0:3]
	s_setprio 0
	s_add_u32 s57, s22, 0x200
	s_addc_u32 s58, s23, 0
	s_mov_b32 s59, 0
	s_mov_b32 s60, 0x20000
.LBB0_1323:
	s_barrier
	s_add_i32 s22, s60, 0xffff0000
	s_and_b32 s30, s22, 0x1e0000
	s_add_u32 s22, s28, 0x100
	s_addc_u32 s23, s29, 0
	s_and_b32 s31, s22, 0x100
	s_or_b32 s61, s31, s30
	s_add_i32 s31, s28, 0x200
	s_and_b32 s30, s60, 0x3e0000
	s_and_b32 s31, s31, 0x100
	s_or_b32 s30, s30, s31
	s_add_u32 s30, s20, s30
	s_addc_u32 s31, s21, 0
	s_add_u32 s28, s57, s28
	ds_read_b128 v[100:103], v198
	ds_read_b128 v[112:115], v198 offset:1024
	ds_read_b128 v[120:123], v198 offset:2048
	ds_read_b128 v[124:127], v198 offset:3072
	ds_read_b128 v[144:147], v199
	ds_read_b128 v[148:151], v199 offset:1024
	ds_read_b128 v[152:155], v199 offset:2048
	ds_read_b128 v[156:159], v199 offset:3072
	s_addc_u32 s29, s58, s29
	s_cmp_eq_u32 s59, 60
	s_cselect_b32 s34, s11, s30
	s_cselect_b32 s35, s9, s31
	s_cselect_b32 s30, s56, s28
	s_cselect_b32 s31, s55, s29
	s_add_u32 s28, s34, 0x80
	s_addc_u32 s29, s35, 0
	s_add_u32 s61, s20, s61
	s_addc_u32 s63, s21, 0
	ds_read_b128 v[160:163], v200
	ds_read_b128 v[164:167], v200 offset:1024
	ds_read_b128 v[168:171], v200 offset:2048
	ds_read_b128 v[172:175], v200 offset:3072
	ds_read_b128 v[176:179], v200 offset:4096
	ds_read_b128 v[180:183], v200 offset:5120
	ds_read_b128 v[184:187], v200 offset:6144
	ds_read_b128 v[188:191], v200 offset:7168
	s_add_u32 s62, s61, 0x10080
	s_addc_u32 s63, s63, 0
	s_mov_b32 s61, m0
	s_mov_b32 m0, s49
	s_nop 0
	global_load_lds_dwordx4 v192, s[62:63]
	s_mov_b32 m0, s61
	s_nop 0
	s_mov_b32 s61, m0
	s_mov_b32 m0, s50
	s_nop 0
	global_load_lds_dwordx4 v194, s[62:63]
	s_mov_b32 m0, s61
	s_waitcnt vmcnt(8)
	s_waitcnt lgkmcnt(0)
	s_barrier
	s_setprio 1
	s_waitcnt lgkmcnt(7)
	v_mfma_f32_16x16x32_bf16 v[140:143], v[100:103], v[160:163], v[140:143]
	v_mfma_f32_16x16x32_bf16 v[136:139], v[120:123], v[160:163], v[136:139]
	s_waitcnt lgkmcnt(5)
	v_mfma_f32_16x16x32_bf16 v[116:119], v[100:103], v[168:171], v[116:119]
	v_mfma_f32_16x16x32_bf16 v[108:111], v[120:123], v[168:171], v[108:111]
	s_waitcnt lgkmcnt(3)
	v_mfma_f32_16x16x32_bf16 v[92:95], v[100:103], v[176:179], v[92:95]
	v_mfma_f32_16x16x32_bf16 v[88:91], v[120:123], v[176:179], v[88:91]
	s_waitcnt lgkmcnt(1)
	v_mfma_f32_16x16x32_bf16 v[76:79], v[100:103], v[184:187], v[76:79]
	v_mfma_f32_16x16x32_bf16 v[68:71], v[120:123], v[184:187], v[68:71]
	v_mfma_f32_16x16x32_bf16 v[140:143], v[112:115], v[164:167], v[140:143]
	v_mfma_f32_16x16x32_bf16 v[136:139], v[124:127], v[164:167], v[136:139]
	v_mfma_f32_16x16x32_bf16 v[116:119], v[112:115], v[172:175], v[116:119]
	v_mfma_f32_16x16x32_bf16 v[108:111], v[124:127], v[172:175], v[108:111]
	v_mfma_f32_16x16x32_bf16 v[92:95], v[112:115], v[180:183], v[92:95]
	v_mfma_f32_16x16x32_bf16 v[88:91], v[124:127], v[180:183], v[88:91]
	s_waitcnt lgkmcnt(0)
	v_mfma_f32_16x16x32_bf16 v[76:79], v[112:115], v[188:191], v[76:79]
	v_mfma_f32_16x16x32_bf16 v[68:71], v[124:127], v[188:191], v[68:71]
	s_setprio 0
	s_setprio 1
	v_mfma_f32_16x16x32_bf16 v[132:135], v[144:147], v[160:163], v[132:135]
	v_mfma_f32_16x16x32_bf16 v[128:131], v[152:155], v[160:163], v[128:131]
	v_mfma_f32_16x16x32_bf16 v[104:107], v[144:147], v[168:171], v[104:107]
	v_mfma_f32_16x16x32_bf16 v[96:99], v[152:155], v[168:171], v[96:99]
	v_mfma_f32_16x16x32_bf16 v[84:87], v[144:147], v[176:179], v[84:87]
	v_mfma_f32_16x16x32_bf16 v[80:83], v[152:155], v[176:179], v[80:83]
	v_mfma_f32_16x16x32_bf16 v[64:67], v[144:147], v[184:187], v[64:67]
	v_mfma_f32_16x16x32_bf16 v[52:55], v[152:155], v[184:187], v[52:55]
	v_mfma_f32_16x16x32_bf16 v[132:135], v[148:151], v[164:167], v[132:135]
	v_mfma_f32_16x16x32_bf16 v[128:131], v[156:159], v[164:167], v[128:131]
	v_mfma_f32_16x16x32_bf16 v[104:107], v[148:151], v[172:175], v[104:107]
	v_mfma_f32_16x16x32_bf16 v[96:99], v[156:159], v[172:175], v[96:99]
	v_mfma_f32_16x16x32_bf16 v[84:87], v[148:151], v[180:183], v[84:87]
	v_mfma_f32_16x16x32_bf16 v[80:83], v[156:159], v[180:183], v[80:83]
	v_mfma_f32_16x16x32_bf16 v[64:67], v[148:151], v[188:191], v[64:67]
	v_mfma_f32_16x16x32_bf16 v[52:55], v[156:159], v[188:191], v[52:55]
	s_setprio 0
	s_barrier
	ds_read_b128 v[160:163], v200 offset:16384
	ds_read_b128 v[164:167], v200 offset:17408
	ds_read_b128 v[168:171], v200 offset:18432
	ds_read_b128 v[172:175], v200 offset:19456
	ds_read_b128 v[176:179], v200 offset:20480
	ds_read_b128 v[180:183], v200 offset:21504
	ds_read_b128 v[184:187], v200 offset:22528
	ds_read_b128 v[188:191], v200 offset:23552
	s_mov_b32 s61, m0
	s_mov_b32 m0, s19
	s_nop 0
	global_load_lds_dwordx4 v193, s[30:31]
	s_mov_b32 m0, s61
	s_add_u32 s62, s30, 0x100000
	s_mov_b32 s61, m0
	s_mov_b32 m0, s33
	s_nop 0
	global_load_lds_dwordx4 v195, s[30:31]
	s_mov_b32 m0, s61
	s_addc_u32 s63, s31, 0
	s_mov_b32 s61, m0
	s_mov_b32 m0, s36
	s_nop 0
	global_load_lds_dwordx4 v193, s[62:63]
	s_mov_b32 m0, s61
	s_nop 0
	s_mov_b32 s61, m0
	s_mov_b32 m0, s37
	s_nop 0
	global_load_lds_dwordx4 v195, s[62:63]
	s_mov_b32 m0, s61
	s_nop 0
	s_mov_b32 s61, m0
	s_mov_b32 m0, s3
	s_nop 0
	global_load_lds_dwordx4 v192, s[34:35]
	s_mov_b32 m0, s61
	s_nop 0
	s_mov_b32 s61, m0
	s_mov_b32 m0, s38
	s_nop 0
	global_load_lds_dwordx4 v194, s[34:35]
	s_mov_b32 m0, s61
	s_waitcnt vmcnt(8)
	s_waitcnt lgkmcnt(0)
	s_barrier
	s_setprio 1
	s_waitcnt lgkmcnt(7)
	v_mfma_f32_16x16x32_bf16 v[72:75], v[100:103], v[160:163], v[72:75]
	v_mfma_f32_16x16x32_bf16 v[60:63], v[120:123], v[160:163], v[60:63]
	s_waitcnt lgkmcnt(5)
	v_mfma_f32_16x16x32_bf16 v[44:47], v[100:103], v[168:171], v[44:47]
	v_mfma_f32_16x16x32_bf16 v[40:43], v[120:123], v[168:171], v[40:43]
	s_waitcnt lgkmcnt(3)
	v_mfma_f32_16x16x32_bf16 v[28:31], v[100:103], v[176:179], v[28:31]
	v_mfma_f32_16x16x32_bf16 v[24:27], v[120:123], v[176:179], v[24:27]
	s_waitcnt lgkmcnt(1)
	v_mfma_f32_16x16x32_bf16 v[12:15], v[100:103], v[184:187], v[12:15]
	v_mfma_f32_16x16x32_bf16 v[8:11], v[120:123], v[184:187], v[8:11]
	v_mfma_f32_16x16x32_bf16 v[72:75], v[112:115], v[164:167], v[72:75]
	v_mfma_f32_16x16x32_bf16 v[60:63], v[124:127], v[164:167], v[60:63]
	v_mfma_f32_16x16x32_bf16 v[44:47], v[112:115], v[172:175], v[44:47]
	v_mfma_f32_16x16x32_bf16 v[40:43], v[124:127], v[172:175], v[40:43]
	v_mfma_f32_16x16x32_bf16 v[28:31], v[112:115], v[180:183], v[28:31]
	v_mfma_f32_16x16x32_bf16 v[24:27], v[124:127], v[180:183], v[24:27]
	s_waitcnt lgkmcnt(0)
	v_mfma_f32_16x16x32_bf16 v[12:15], v[112:115], v[188:191], v[12:15]
	v_mfma_f32_16x16x32_bf16 v[8:11], v[124:127], v[188:191], v[8:11]
	s_setprio 0
	s_setprio 1
	v_mfma_f32_16x16x32_bf16 v[56:59], v[144:147], v[160:163], v[56:59]
	v_mfma_f32_16x16x32_bf16 v[48:51], v[152:155], v[160:163], v[48:51]
	v_mfma_f32_16x16x32_bf16 v[36:39], v[144:147], v[168:171], v[36:39]
	v_mfma_f32_16x16x32_bf16 v[32:35], v[152:155], v[168:171], v[32:35]
	v_mfma_f32_16x16x32_bf16 v[20:23], v[144:147], v[176:179], v[20:23]
	v_mfma_f32_16x16x32_bf16 v[16:19], v[152:155], v[176:179], v[16:19]
	v_mfma_f32_16x16x32_bf16 v[4:7], v[144:147], v[184:187], v[4:7]
	v_mfma_f32_16x16x32_bf16 v[0:3], v[152:155], v[184:187], v[0:3]
	v_mfma_f32_16x16x32_bf16 v[56:59], v[148:151], v[164:167], v[56:59]
	v_mfma_f32_16x16x32_bf16 v[48:51], v[156:159], v[164:167], v[48:51]
	v_mfma_f32_16x16x32_bf16 v[36:39], v[148:151], v[172:175], v[36:39]
	v_mfma_f32_16x16x32_bf16 v[32:35], v[156:159], v[172:175], v[32:35]
	v_mfma_f32_16x16x32_bf16 v[20:23], v[148:151], v[180:183], v[20:23]
	v_mfma_f32_16x16x32_bf16 v[16:19], v[156:159], v[180:183], v[16:19]
	v_mfma_f32_16x16x32_bf16 v[4:7], v[148:151], v[188:191], v[4:7]
	v_mfma_f32_16x16x32_bf16 v[0:3], v[156:159], v[188:191], v[0:3]
	s_setprio 0
	s_barrier
	ds_read_b128 v[100:103], v201
	ds_read_b128 v[112:115], v201 offset:1024
	ds_read_b128 v[120:123], v201 offset:2048
	ds_read_b128 v[124:127], v201 offset:3072
	ds_read_b128 v[144:147], v202
	ds_read_b128 v[148:151], v202 offset:1024
	ds_read_b128 v[152:155], v202 offset:2048
	ds_read_b128 v[156:159], v202 offset:3072
	ds_read_b128 v[160:163], v200 offset:32768
	ds_read_b128 v[164:167], v200 offset:33792
	ds_read_b128 v[168:171], v200 offset:34816
	ds_read_b128 v[172:175], v200 offset:35840
	ds_read_b128 v[176:179], v200 offset:36864
	ds_read_b128 v[180:183], v200 offset:37888
	ds_read_b128 v[184:187], v200 offset:38912
	ds_read_b128 v[188:191], v200 offset:39936
	s_add_u32 s34, s34, 0x10000
	s_addc_u32 s35, s35, 0
	s_mov_b32 s61, m0
	s_mov_b32 m0, s39
	s_nop 0
	global_load_lds_dwordx4 v192, s[34:35]
	s_mov_b32 m0, s61
	s_nop 0
	s_mov_b32 s61, m0
	s_mov_b32 m0, s40
	s_nop 0
	global_load_lds_dwordx4 v194, s[34:35]
	s_mov_b32 m0, s61
	s_waitcnt vmcnt(8)
	s_waitcnt lgkmcnt(0)
	s_barrier
	s_setprio 1
	s_waitcnt lgkmcnt(7)
	v_mfma_f32_16x16x32_bf16 v[140:143], v[100:103], v[160:163], v[140:143]
	v_mfma_f32_16x16x32_bf16 v[136:139], v[120:123], v[160:163], v[136:139]
	s_waitcnt lgkmcnt(5)
	v_mfma_f32_16x16x32_bf16 v[116:119], v[100:103], v[168:171], v[116:119]
	v_mfma_f32_16x16x32_bf16 v[108:111], v[120:123], v[168:171], v[108:111]
	s_waitcnt lgkmcnt(3)
	v_mfma_f32_16x16x32_bf16 v[92:95], v[100:103], v[176:179], v[92:95]
	v_mfma_f32_16x16x32_bf16 v[88:91], v[120:123], v[176:179], v[88:91]
	s_waitcnt lgkmcnt(1)
	v_mfma_f32_16x16x32_bf16 v[76:79], v[100:103], v[184:187], v[76:79]
	v_mfma_f32_16x16x32_bf16 v[68:71], v[120:123], v[184:187], v[68:71]
	v_mfma_f32_16x16x32_bf16 v[140:143], v[112:115], v[164:167], v[140:143]
	v_mfma_f32_16x16x32_bf16 v[136:139], v[124:127], v[164:167], v[136:139]
	v_mfma_f32_16x16x32_bf16 v[116:119], v[112:115], v[172:175], v[116:119]
	v_mfma_f32_16x16x32_bf16 v[108:111], v[124:127], v[172:175], v[108:111]
	v_mfma_f32_16x16x32_bf16 v[92:95], v[112:115], v[180:183], v[92:95]
	v_mfma_f32_16x16x32_bf16 v[88:91], v[124:127], v[180:183], v[88:91]
	s_waitcnt lgkmcnt(0)
	v_mfma_f32_16x16x32_bf16 v[76:79], v[112:115], v[188:191], v[76:79]
	v_mfma_f32_16x16x32_bf16 v[68:71], v[124:127], v[188:191], v[68:71]
	s_setprio 0
	s_setprio 1
	v_mfma_f32_16x16x32_bf16 v[132:135], v[144:147], v[160:163], v[132:135]
	v_mfma_f32_16x16x32_bf16 v[128:131], v[152:155], v[160:163], v[128:131]
	v_mfma_f32_16x16x32_bf16 v[104:107], v[144:147], v[168:171], v[104:107]
	v_mfma_f32_16x16x32_bf16 v[96:99], v[152:155], v[168:171], v[96:99]
	v_mfma_f32_16x16x32_bf16 v[84:87], v[144:147], v[176:179], v[84:87]
	v_mfma_f32_16x16x32_bf16 v[80:83], v[152:155], v[176:179], v[80:83]
	v_mfma_f32_16x16x32_bf16 v[64:67], v[144:147], v[184:187], v[64:67]
	v_mfma_f32_16x16x32_bf16 v[52:55], v[152:155], v[184:187], v[52:55]
	v_mfma_f32_16x16x32_bf16 v[132:135], v[148:151], v[164:167], v[132:135]
	v_mfma_f32_16x16x32_bf16 v[128:131], v[156:159], v[164:167], v[128:131]
	v_mfma_f32_16x16x32_bf16 v[104:107], v[148:151], v[172:175], v[104:107]
	v_mfma_f32_16x16x32_bf16 v[96:99], v[156:159], v[172:175], v[96:99]
	v_mfma_f32_16x16x32_bf16 v[84:87], v[148:151], v[180:183], v[84:87]
	v_mfma_f32_16x16x32_bf16 v[80:83], v[156:159], v[180:183], v[80:83]
	v_mfma_f32_16x16x32_bf16 v[64:67], v[148:151], v[188:191], v[64:67]
	v_mfma_f32_16x16x32_bf16 v[52:55], v[156:159], v[188:191], v[52:55]
	s_setprio 0
	s_barrier
	ds_read_b128 v[160:163], v200 offset:49152
	ds_read_b128 v[164:167], v200 offset:50176
	ds_read_b128 v[168:171], v200 offset:51200
	ds_read_b128 v[172:175], v200 offset:52224
	ds_read_b128 v[176:179], v200 offset:53248
	ds_read_b128 v[180:183], v200 offset:54272
	ds_read_b128 v[184:187], v200 offset:55296
	ds_read_b128 v[188:191], v200 offset:56320
	s_add_u32 s34, s30, 0x80
	s_addc_u32 s35, s31, 0
	s_mov_b32 s61, m0
	s_mov_b32 m0, s43
	s_nop 0
	global_load_lds_dwordx4 v193, s[34:35]
	s_mov_b32 m0, s61
	s_add_u32 s30, s30, 0x100080
	s_mov_b32 s61, m0
	s_mov_b32 m0, s44
	s_nop 0
	global_load_lds_dwordx4 v195, s[34:35]
	s_mov_b32 m0, s61
	s_addc_u32 s31, s31, 0
	s_mov_b32 s34, m0
	s_mov_b32 m0, s47
	s_nop 0
	global_load_lds_dwordx4 v193, s[30:31]
	s_mov_b32 m0, s34
	s_nop 0
	s_mov_b32 s34, m0
	s_mov_b32 m0, s48
	s_nop 0
	global_load_lds_dwordx4 v195, s[30:31]
	s_mov_b32 m0, s34
	s_mov_b32 s30, m0
	s_mov_b32 m0, s45
	s_nop 0
	global_load_lds_dwordx4 v192, s[28:29]
	s_mov_b32 m0, s30
	s_nop 0
	s_mov_b32 s30, m0
	s_mov_b32 m0, s46
	s_nop 0
	global_load_lds_dwordx4 v194, s[28:29]
	s_mov_b32 m0, s30
	s_waitcnt vmcnt(8)
	s_waitcnt lgkmcnt(0)
	s_barrier
	s_setprio 1
	s_waitcnt lgkmcnt(7)
	v_mfma_f32_16x16x32_bf16 v[72:75], v[100:103], v[160:163], v[72:75]
	v_mfma_f32_16x16x32_bf16 v[60:63], v[120:123], v[160:163], v[60:63]
	s_waitcnt lgkmcnt(5)
	v_mfma_f32_16x16x32_bf16 v[44:47], v[100:103], v[168:171], v[44:47]
	v_mfma_f32_16x16x32_bf16 v[40:43], v[120:123], v[168:171], v[40:43]
	s_waitcnt lgkmcnt(3)
	v_mfma_f32_16x16x32_bf16 v[28:31], v[100:103], v[176:179], v[28:31]
	v_mfma_f32_16x16x32_bf16 v[24:27], v[120:123], v[176:179], v[24:27]
	s_waitcnt lgkmcnt(1)
	v_mfma_f32_16x16x32_bf16 v[12:15], v[100:103], v[184:187], v[12:15]
	v_mfma_f32_16x16x32_bf16 v[8:11], v[120:123], v[184:187], v[8:11]
	v_mfma_f32_16x16x32_bf16 v[72:75], v[112:115], v[164:167], v[72:75]
	v_mfma_f32_16x16x32_bf16 v[60:63], v[124:127], v[164:167], v[60:63]
	v_mfma_f32_16x16x32_bf16 v[44:47], v[112:115], v[172:175], v[44:47]
	v_mfma_f32_16x16x32_bf16 v[40:43], v[124:127], v[172:175], v[40:43]
	v_mfma_f32_16x16x32_bf16 v[28:31], v[112:115], v[180:183], v[28:31]
	v_mfma_f32_16x16x32_bf16 v[24:27], v[124:127], v[180:183], v[24:27]
	s_waitcnt lgkmcnt(0)
	v_mfma_f32_16x16x32_bf16 v[12:15], v[112:115], v[188:191], v[12:15]
	v_mfma_f32_16x16x32_bf16 v[8:11], v[124:127], v[188:191], v[8:11]
	s_setprio 0
	s_setprio 1
	v_mfma_f32_16x16x32_bf16 v[56:59], v[144:147], v[160:163], v[56:59]
	v_mfma_f32_16x16x32_bf16 v[48:51], v[152:155], v[160:163], v[48:51]
	v_mfma_f32_16x16x32_bf16 v[36:39], v[144:147], v[168:171], v[36:39]
	v_mfma_f32_16x16x32_bf16 v[32:35], v[152:155], v[168:171], v[32:35]
	v_mfma_f32_16x16x32_bf16 v[20:23], v[144:147], v[176:179], v[20:23]
	v_mfma_f32_16x16x32_bf16 v[16:19], v[152:155], v[176:179], v[16:19]
	v_mfma_f32_16x16x32_bf16 v[4:7], v[144:147], v[184:187], v[4:7]
	v_mfma_f32_16x16x32_bf16 v[0:3], v[152:155], v[184:187], v[0:3]
	v_mfma_f32_16x16x32_bf16 v[56:59], v[148:151], v[164:167], v[56:59]
	v_mfma_f32_16x16x32_bf16 v[48:51], v[156:159], v[164:167], v[48:51]
	v_mfma_f32_16x16x32_bf16 v[36:39], v[148:151], v[172:175], v[36:39]
	v_mfma_f32_16x16x32_bf16 v[32:35], v[156:159], v[172:175], v[32:35]
	v_mfma_f32_16x16x32_bf16 v[20:23], v[148:151], v[180:183], v[20:23]
	v_mfma_f32_16x16x32_bf16 v[16:19], v[156:159], v[180:183], v[16:19]
	v_mfma_f32_16x16x32_bf16 v[4:7], v[148:151], v[188:191], v[4:7]
	v_mfma_f32_16x16x32_bf16 v[0:3], v[156:159], v[188:191], v[0:3]
	s_setprio 0
	s_add_i32 s59, s59, 2
	s_add_i32 s60, s60, 0x10000
	s_cmp_lt_u32 s59, 62
	s_mov_b64 s[28:29], s[22:23]
	s_cbranch_scc1 .LBB0_1323
	s_barrier
	s_andn2_b64 vcc, exec, s[4:5]
	s_cbranch_vccnz .LBB0_1326
	s_barrier
